# v20 with the per-segment s_setprio toggles removed from the 8 GEMM loops (timing-only)
# speedup vs baseline: 1.0080x; 1.0080x over previous
.LBB0_288:
	v_or_b32_e32 v160, 0x10000, v156
	v_or_b32_e32 v162, 0x10000, v158
	v_or_b32_e32 v161, 0x10000, v157
	ds_read_b128 v[170:173], v160
	ds_read_b128 v[174:177], v161
	v_or_b32_e32 v163, 0x10000, v159
	ds_read_b128 v[178:181], v162
	ds_read_b128 v[182:185], v163
	s_add_u32 s34, s19, s16
	s_addc_u32 s35, s30, s17
	s_add_u32 s34, s34, 0x80
	v_add_u32_e32 v164, 0xc000, v137
	s_addc_u32 s35, s35, 0
	v_readfirstlane_b32 s36, v164
	ds_read_b128 v[186:189], v139
	ds_read_b128 v[190:193], v139 offset:1024
	ds_read_b128 v[194:197], v142
	ds_read_b128 v[198:201], v142 offset:1024
	ds_read_b128 v[202:205], v141
	ds_read_b128 v[206:209], v141 offset:1024
	ds_read_b128 v[224:227], v140
	ds_read_b128 v[228:231], v140 offset:1024
	s_mov_b32 m0, s36
	v_lshl_add_u64 v[166:167], s[34:35], 0, v[132:133]
	v_add_u32_e32 v165, 0xe000, v137
	global_load_lds_dwordx4 v[166:167], off
	v_lshl_add_u64 v[166:167], s[34:35], 0, v[130:131]
	v_readfirstlane_b32 s34, v165
	s_mov_b32 m0, s34
	s_nop 0
	global_load_lds_dwordx4 v[166:167], off
	s_waitcnt lgkmcnt(8)
	s_barrier
	s_waitcnt lgkmcnt(0)
	s_waitcnt lgkmcnt(0)
	v_mfma_f32_16x16x32_bf16 v[126:129], v[186:189], v[170:173], v[126:129]
	v_mfma_f32_16x16x32_bf16 v[122:125], v[186:189], v[178:181], v[122:125]
	v_mfma_f32_16x16x32_bf16 v[118:121], v[194:197], v[170:173], v[118:121]
	v_mfma_f32_16x16x32_bf16 v[114:117], v[194:197], v[178:181], v[114:117]
	v_mfma_f32_16x16x32_bf16 v[110:113], v[202:205], v[170:173], v[110:113]
	v_mfma_f32_16x16x32_bf16 v[106:109], v[202:205], v[178:181], v[106:109]
	v_mfma_f32_16x16x32_bf16 v[102:105], v[224:227], v[170:173], v[102:105]
	v_mfma_f32_16x16x32_bf16 v[98:101], v[224:227], v[178:181], v[98:101]
	v_mfma_f32_16x16x32_bf16 v[126:129], v[190:193], v[174:177], v[126:129]
	v_mfma_f32_16x16x32_bf16 v[122:125], v[190:193], v[182:185], v[122:125]
	v_mfma_f32_16x16x32_bf16 v[118:121], v[198:201], v[174:177], v[118:121]
	v_mfma_f32_16x16x32_bf16 v[114:117], v[198:201], v[182:185], v[114:117]
	v_mfma_f32_16x16x32_bf16 v[110:113], v[206:209], v[174:177], v[110:113]
	v_mfma_f32_16x16x32_bf16 v[106:109], v[206:209], v[182:185], v[106:109]
	v_mfma_f32_16x16x32_bf16 v[102:105], v[228:231], v[174:177], v[102:105]
	v_mfma_f32_16x16x32_bf16 v[98:101], v[228:231], v[182:185], v[98:101]
	s_barrier
	s_add_u32 s36, s0, s16
	s_addc_u32 s37, s1, s17
	s_add_u32 s34, s36, 0x100
	v_or_b32_e32 v166, 0x14000, v156
	v_or_b32_e32 v168, 0x14000, v158
	s_addc_u32 s35, s37, 0
	v_readfirstlane_b32 s38, v143
	v_or_b32_e32 v167, 0x14000, v157
	ds_read_b128 v[232:235], v166
	ds_read_b128 v[236:239], v167
	v_or_b32_e32 v169, 0x14000, v159
	ds_read_b128 v[240:243], v168
	ds_read_b128 v[244:247], v169
	s_mov_b32 m0, s38
	v_lshl_add_u64 v[212:213], s[34:35], 0, v[132:133]
	global_load_lds_dwordx4 v[212:213], off
	v_lshl_add_u64 v[212:213], s[34:35], 0, v[130:131]
	v_readfirstlane_b32 s34, v144
	s_mov_b32 m0, s34
	s_nop 0
	global_load_lds_dwordx4 v[212:213], off
	s_barrier
	s_waitcnt lgkmcnt(0)
	s_waitcnt lgkmcnt(0)
	v_mfma_f32_16x16x32_bf16 v[94:97], v[186:189], v[232:235], v[94:97]
	v_mfma_f32_16x16x32_bf16 v[90:93], v[186:189], v[240:243], v[90:93]
	v_mfma_f32_16x16x32_bf16 v[86:89], v[194:197], v[232:235], v[86:89]
	v_mfma_f32_16x16x32_bf16 v[82:85], v[194:197], v[240:243], v[82:85]
	v_mfma_f32_16x16x32_bf16 v[78:81], v[202:205], v[232:235], v[78:81]
	v_mfma_f32_16x16x32_bf16 v[74:77], v[202:205], v[240:243], v[74:77]
	v_mfma_f32_16x16x32_bf16 v[70:73], v[224:227], v[232:235], v[70:73]
	v_mfma_f32_16x16x32_bf16 v[66:69], v[224:227], v[240:243], v[66:69]
	v_mfma_f32_16x16x32_bf16 v[94:97], v[190:193], v[236:239], v[94:97]
	v_mfma_f32_16x16x32_bf16 v[90:93], v[190:193], v[244:247], v[90:93]
	v_mfma_f32_16x16x32_bf16 v[86:89], v[198:201], v[236:239], v[86:89]
	v_mfma_f32_16x16x32_bf16 v[82:85], v[198:201], v[244:247], v[82:85]
	v_mfma_f32_16x16x32_bf16 v[78:81], v[206:209], v[236:239], v[78:81]
	v_mfma_f32_16x16x32_bf16 v[74:77], v[206:209], v[244:247], v[74:77]
	v_mfma_f32_16x16x32_bf16 v[70:73], v[228:231], v[236:239], v[70:73]
	v_mfma_f32_16x16x32_bf16 v[66:69], v[228:231], v[244:247], v[66:69]
	s_add_u32 s38, s10, s16
	s_addc_u32 s39, s11, s17
	s_add_u32 s34, s38, 0x100
	s_addc_u32 s35, s39, 0
	v_readfirstlane_b32 s40, v137
	s_barrier
	ds_read_b128 v[186:189], v139 offset:16384
	ds_read_b128 v[190:193], v139 offset:17408
	ds_read_b128 v[194:197], v142 offset:16384
	ds_read_b128 v[198:201], v142 offset:17408
	ds_read_b128 v[202:205], v141 offset:16384
	ds_read_b128 v[206:209], v141 offset:17408
	ds_read_b128 v[224:227], v140 offset:16384
	ds_read_b128 v[228:231], v140 offset:17408
	s_mov_b32 m0, s40
	v_lshl_add_u64 v[212:213], s[34:35], 0, v[132:133]
	global_load_lds_dwordx4 v[212:213], off
	v_lshl_add_u64 v[212:213], s[34:35], 0, v[130:131]
	v_readfirstlane_b32 s34, v138
	s_mov_b32 m0, s34
	s_nop 0
	global_load_lds_dwordx4 v[212:213], off
	s_barrier
	s_waitcnt lgkmcnt(0)
	s_waitcnt lgkmcnt(0)
	v_mfma_f32_16x16x32_bf16 v[62:65], v[186:189], v[170:173], v[62:65]
	v_mfma_f32_16x16x32_bf16 v[58:61], v[186:189], v[178:181], v[58:61]
	v_mfma_f32_16x16x32_bf16 v[54:57], v[194:197], v[170:173], v[54:57]
	v_mfma_f32_16x16x32_bf16 v[50:53], v[194:197], v[178:181], v[50:53]
	v_mfma_f32_16x16x32_bf16 v[46:49], v[202:205], v[170:173], v[46:49]
	v_mfma_f32_16x16x32_bf16 v[42:45], v[202:205], v[178:181], v[42:45]
	v_mfma_f32_16x16x32_bf16 v[38:41], v[224:227], v[170:173], v[38:41]
	v_mfma_f32_16x16x32_bf16 v[34:37], v[224:227], v[178:181], v[34:37]
	v_mfma_f32_16x16x32_bf16 v[62:65], v[190:193], v[174:177], v[62:65]
	v_mfma_f32_16x16x32_bf16 v[58:61], v[190:193], v[182:185], v[58:61]
	v_mfma_f32_16x16x32_bf16 v[54:57], v[198:201], v[174:177], v[54:57]
	v_mfma_f32_16x16x32_bf16 v[50:53], v[198:201], v[182:185], v[50:53]
	v_mfma_f32_16x16x32_bf16 v[46:49], v[206:209], v[174:177], v[46:49]
	v_mfma_f32_16x16x32_bf16 v[42:45], v[206:209], v[182:185], v[42:45]
	v_mfma_f32_16x16x32_bf16 v[38:41], v[228:231], v[174:177], v[38:41]
	v_mfma_f32_16x16x32_bf16 v[34:37], v[228:231], v[182:185], v[34:37]
	s_barrier
	s_add_u32 s40, s12, s16
	s_addc_u32 s41, s13, s17
	s_add_u32 s34, s40, 0x100
	s_addc_u32 s35, s41, 0
	v_readfirstlane_b32 s42, v146
	s_mov_b32 m0, s42
	v_lshl_add_u64 v[170:171], s[34:35], 0, v[132:133]
	global_load_lds_dwordx4 v[170:171], off
	v_lshl_add_u64 v[170:171], s[34:35], 0, v[130:131]
	v_readfirstlane_b32 s34, v147
	s_mov_b32 m0, s34
	s_nop 0
	global_load_lds_dwordx4 v[170:171], off
	s_waitcnt vmcnt(6)
	s_barrier
	v_mfma_f32_16x16x32_bf16 v[30:33], v[186:189], v[232:235], v[30:33]
	v_mfma_f32_16x16x32_bf16 v[26:29], v[186:189], v[240:243], v[26:29]
	v_mfma_f32_16x16x32_bf16 v[22:25], v[194:197], v[232:235], v[22:25]
	v_mfma_f32_16x16x32_bf16 v[18:21], v[194:197], v[240:243], v[18:21]
	v_mfma_f32_16x16x32_bf16 v[14:17], v[202:205], v[232:235], v[14:17]
	v_mfma_f32_16x16x32_bf16 v[10:13], v[202:205], v[240:243], v[10:13]
	v_mfma_f32_16x16x32_bf16 v[6:9], v[224:227], v[232:235], v[6:9]
	v_mfma_f32_16x16x32_bf16 v[2:5], v[224:227], v[240:243], v[2:5]
	v_mfma_f32_16x16x32_bf16 v[30:33], v[190:193], v[236:239], v[30:33]
	v_mfma_f32_16x16x32_bf16 v[26:29], v[190:193], v[244:247], v[26:29]
	v_mfma_f32_16x16x32_bf16 v[22:25], v[198:201], v[236:239], v[22:25]
	v_mfma_f32_16x16x32_bf16 v[18:21], v[198:201], v[244:247], v[18:21]
	v_mfma_f32_16x16x32_bf16 v[14:17], v[206:209], v[236:239], v[14:17]
	v_mfma_f32_16x16x32_bf16 v[10:13], v[206:209], v[244:247], v[10:13]
	v_mfma_f32_16x16x32_bf16 v[6:9], v[228:231], v[236:239], v[6:9]
	v_mfma_f32_16x16x32_bf16 v[2:5], v[228:231], v[244:247], v[2:5]
	v_or_b32_e32 v170, 0x18000, v156
	v_or_b32_e32 v172, 0x18000, v158
	s_barrier
	v_or_b32_e32 v171, 0x18000, v157
	ds_read_b128 v[178:181], v170
	ds_read_b128 v[182:185], v171
	v_or_b32_e32 v173, 0x18000, v159
	ds_read_b128 v[186:189], v172
	ds_read_b128 v[190:193], v173
	s_add_u32 s34, s7, s16
	s_addc_u32 s35, s18, s17
	v_readfirstlane_b32 s42, v148
	ds_read_b128 v[194:197], v139 offset:32768
	ds_read_b128 v[198:201], v139 offset:33792
	ds_read_b128 v[202:205], v142 offset:32768
	ds_read_b128 v[206:209], v142 offset:33792
	ds_read_b128 v[224:227], v141 offset:32768
	ds_read_b128 v[228:231], v141 offset:33792
	ds_read_b128 v[232:235], v140 offset:32768
	ds_read_b128 v[236:239], v140 offset:33792
	s_mov_b32 m0, s42
	v_lshl_add_u64 v[174:175], s[34:35], 0, v[132:133]
	global_load_lds_dwordx4 v[174:175], off
	v_lshl_add_u64 v[174:175], s[34:35], 0, v[130:131]
	v_readfirstlane_b32 s34, v149
	s_mov_b32 m0, s34
	s_nop 0
	global_load_lds_dwordx4 v[174:175], off
	s_waitcnt lgkmcnt(8)
	s_barrier
	s_waitcnt lgkmcnt(0)
	s_waitcnt lgkmcnt(0)
	v_mfma_f32_16x16x32_bf16 v[126:129], v[194:197], v[178:181], v[126:129]
	v_mfma_f32_16x16x32_bf16 v[122:125], v[194:197], v[186:189], v[122:125]
	v_mfma_f32_16x16x32_bf16 v[118:121], v[202:205], v[178:181], v[118:121]
	v_mfma_f32_16x16x32_bf16 v[114:117], v[202:205], v[186:189], v[114:117]
	v_mfma_f32_16x16x32_bf16 v[110:113], v[224:227], v[178:181], v[110:113]
	v_mfma_f32_16x16x32_bf16 v[106:109], v[224:227], v[186:189], v[106:109]
	v_mfma_f32_16x16x32_bf16 v[102:105], v[232:235], v[178:181], v[102:105]
	v_mfma_f32_16x16x32_bf16 v[98:101], v[232:235], v[186:189], v[98:101]
	v_mfma_f32_16x16x32_bf16 v[126:129], v[198:201], v[182:185], v[126:129]
	v_mfma_f32_16x16x32_bf16 v[122:125], v[198:201], v[190:193], v[122:125]
	v_mfma_f32_16x16x32_bf16 v[118:121], v[206:209], v[182:185], v[118:121]
	v_mfma_f32_16x16x32_bf16 v[114:117], v[206:209], v[190:193], v[114:117]
	v_mfma_f32_16x16x32_bf16 v[110:113], v[228:231], v[182:185], v[110:113]
	v_mfma_f32_16x16x32_bf16 v[106:109], v[228:231], v[190:193], v[106:109]
	v_mfma_f32_16x16x32_bf16 v[102:105], v[236:239], v[182:185], v[102:105]
	v_mfma_f32_16x16x32_bf16 v[98:101], v[236:239], v[190:193], v[98:101]
	s_barrier
	s_add_u32 s34, s36, 0x180
	v_or_b32_e32 v174, 0x1c000, v156
	v_or_b32_e32 v176, 0x1c000, v158
	s_addc_u32 s35, s37, 0
	v_readfirstlane_b32 s36, v150
	v_or_b32_e32 v175, 0x1c000, v157
	ds_read_b128 v[240:243], v174
	ds_read_b128 v[244:247], v175
	v_or_b32_e32 v177, 0x1c000, v159
	ds_read_b128 v[248:251], v176
	ds_read_b128 v[212:215], v177
	s_mov_b32 m0, s36
	v_lshl_add_u64 v[216:217], s[34:35], 0, v[132:133]
	global_load_lds_dwordx4 v[216:217], off
	v_lshl_add_u64 v[216:217], s[34:35], 0, v[130:131]
	v_readfirstlane_b32 s34, v151
	s_mov_b32 m0, s34
	s_nop 0
	global_load_lds_dwordx4 v[216:217], off
	s_barrier
	s_waitcnt lgkmcnt(0)
	s_waitcnt lgkmcnt(0)
	v_mfma_f32_16x16x32_bf16 v[94:97], v[194:197], v[240:243], v[94:97]
	v_mfma_f32_16x16x32_bf16 v[90:93], v[194:197], v[248:251], v[90:93]
	v_mfma_f32_16x16x32_bf16 v[86:89], v[202:205], v[240:243], v[86:89]
	v_mfma_f32_16x16x32_bf16 v[82:85], v[202:205], v[248:251], v[82:85]
	v_mfma_f32_16x16x32_bf16 v[78:81], v[224:227], v[240:243], v[78:81]
	v_mfma_f32_16x16x32_bf16 v[74:77], v[224:227], v[248:251], v[74:77]
	v_mfma_f32_16x16x32_bf16 v[70:73], v[232:235], v[240:243], v[70:73]
	v_mfma_f32_16x16x32_bf16 v[66:69], v[232:235], v[248:251], v[66:69]
	v_mfma_f32_16x16x32_bf16 v[94:97], v[198:201], v[244:247], v[94:97]
	v_mfma_f32_16x16x32_bf16 v[90:93], v[198:201], v[212:215], v[90:93]
	v_mfma_f32_16x16x32_bf16 v[86:89], v[206:209], v[244:247], v[86:89]
	v_mfma_f32_16x16x32_bf16 v[82:85], v[206:209], v[212:215], v[82:85]
	v_mfma_f32_16x16x32_bf16 v[78:81], v[228:231], v[244:247], v[78:81]
	v_mfma_f32_16x16x32_bf16 v[74:77], v[228:231], v[212:215], v[74:77]
	v_mfma_f32_16x16x32_bf16 v[70:73], v[236:239], v[244:247], v[70:73]
	v_mfma_f32_16x16x32_bf16 v[66:69], v[236:239], v[212:215], v[66:69]
	s_add_u32 s34, s38, 0x180
	s_addc_u32 s35, s39, 0
	v_readfirstlane_b32 s36, v152
	s_barrier
	ds_read_b128 v[194:197], v139 offset:49152
	ds_read_b128 v[198:201], v139 offset:50176
	ds_read_b128 v[202:205], v142 offset:49152
	ds_read_b128 v[206:209], v142 offset:50176
	ds_read_b128 v[224:227], v141 offset:49152
	ds_read_b128 v[228:231], v141 offset:50176
	ds_read_b128 v[232:235], v140 offset:49152
	ds_read_b128 v[236:239], v140 offset:50176
	s_mov_b32 m0, s36
	v_lshl_add_u64 v[216:217], s[34:35], 0, v[132:133]
	global_load_lds_dwordx4 v[216:217], off
	v_lshl_add_u64 v[216:217], s[34:35], 0, v[130:131]
	v_readfirstlane_b32 s34, v153
	s_mov_b32 m0, s34
	s_nop 0
	global_load_lds_dwordx4 v[216:217], off
	s_barrier
	s_waitcnt lgkmcnt(0)
	s_waitcnt lgkmcnt(0)
	v_mfma_f32_16x16x32_bf16 v[62:65], v[194:197], v[178:181], v[62:65]
	v_mfma_f32_16x16x32_bf16 v[58:61], v[194:197], v[186:189], v[58:61]
	v_mfma_f32_16x16x32_bf16 v[54:57], v[202:205], v[178:181], v[54:57]
	v_mfma_f32_16x16x32_bf16 v[50:53], v[202:205], v[186:189], v[50:53]
	v_mfma_f32_16x16x32_bf16 v[46:49], v[224:227], v[178:181], v[46:49]
	v_mfma_f32_16x16x32_bf16 v[42:45], v[224:227], v[186:189], v[42:45]
	v_mfma_f32_16x16x32_bf16 v[38:41], v[232:235], v[178:181], v[38:41]
	v_mfma_f32_16x16x32_bf16 v[34:37], v[232:235], v[186:189], v[34:37]
	v_mfma_f32_16x16x32_bf16 v[62:65], v[198:201], v[182:185], v[62:65]
	v_mfma_f32_16x16x32_bf16 v[58:61], v[198:201], v[190:193], v[58:61]
	v_mfma_f32_16x16x32_bf16 v[54:57], v[206:209], v[182:185], v[54:57]
	v_mfma_f32_16x16x32_bf16 v[50:53], v[206:209], v[190:193], v[50:53]
	v_mfma_f32_16x16x32_bf16 v[46:49], v[228:231], v[182:185], v[46:49]
	v_mfma_f32_16x16x32_bf16 v[42:45], v[228:231], v[190:193], v[42:45]
	v_mfma_f32_16x16x32_bf16 v[38:41], v[236:239], v[182:185], v[38:41]
	v_mfma_f32_16x16x32_bf16 v[34:37], v[236:239], v[190:193], v[34:37]
	s_barrier
	s_add_u32 s34, s40, 0x180
	s_addc_u32 s35, s41, 0
	v_readfirstlane_b32 s36, v154
	s_mov_b32 m0, s36
	v_lshl_add_u64 v[178:179], s[34:35], 0, v[132:133]
	global_load_lds_dwordx4 v[178:179], off
	v_lshl_add_u64 v[178:179], s[34:35], 0, v[130:131]
	v_readfirstlane_b32 s34, v155
	s_mov_b32 m0, s34
	s_nop 0
	global_load_lds_dwordx4 v[178:179], off
	s_waitcnt vmcnt(6)
	s_barrier
	v_mfma_f32_16x16x32_bf16 v[30:33], v[194:197], v[240:243], v[30:33]
	v_mfma_f32_16x16x32_bf16 v[26:29], v[194:197], v[248:251], v[26:29]
	v_mfma_f32_16x16x32_bf16 v[22:25], v[202:205], v[240:243], v[22:25]
	v_mfma_f32_16x16x32_bf16 v[18:21], v[202:205], v[248:251], v[18:21]
	v_mfma_f32_16x16x32_bf16 v[14:17], v[224:227], v[240:243], v[14:17]
	v_mfma_f32_16x16x32_bf16 v[10:13], v[224:227], v[248:251], v[10:13]
	v_mfma_f32_16x16x32_bf16 v[6:9], v[232:235], v[240:243], v[6:9]
	v_mfma_f32_16x16x32_bf16 v[2:5], v[232:235], v[248:251], v[2:5]
	v_mfma_f32_16x16x32_bf16 v[30:33], v[198:201], v[244:247], v[30:33]
	v_mfma_f32_16x16x32_bf16 v[26:29], v[198:201], v[212:215], v[26:29]
	v_mfma_f32_16x16x32_bf16 v[22:25], v[206:209], v[244:247], v[22:25]
	v_mfma_f32_16x16x32_bf16 v[18:21], v[206:209], v[212:215], v[18:21]
	v_mfma_f32_16x16x32_bf16 v[14:17], v[228:231], v[244:247], v[14:17]
	v_mfma_f32_16x16x32_bf16 v[10:13], v[228:231], v[212:215], v[10:13]
	v_mfma_f32_16x16x32_bf16 v[6:9], v[236:239], v[244:247], v[6:9]
	v_mfma_f32_16x16x32_bf16 v[2:5], v[236:239], v[212:215], v[2:5]
	s_add_i32 s31, s31, 2
	s_add_u32 s16, s16, 0x100
	s_addc_u32 s17, s17, 0
	s_cmp_lt_u32 s31, 12
	s_barrier
	s_cbranch_scc1 .LBB0_288
	s_add_u32 s0, s14, 0x780
	s_addc_u32 s1, s15, 0
	ds_read_b128 v[146:149], v160
	ds_read_b128 v[150:153], v161
	ds_read_b128 v[154:157], v162
	ds_read_b128 v[158:161], v163
	ds_read_b128 v[178:181], v139
	ds_read_b128 v[182:185], v139 offset:1024
	ds_read_b128 v[186:189], v142
	ds_read_b128 v[190:193], v142 offset:1024
	ds_read_b128 v[194:197], v141
	ds_read_b128 v[198:201], v141 offset:1024
	ds_read_b128 v[202:205], v140
	ds_read_b128 v[206:209], v140 offset:1024
	v_readfirstlane_b32 s7, v164
	v_lshl_add_u64 v[132:133], s[0:1], 0, v[132:133]
	s_mov_b32 m0, s7
	v_lshl_add_u64 v[130:131], s[0:1], 0, v[130:131]
	v_readfirstlane_b32 s0, v165
	global_load_lds_dwordx4 v[132:133], off
	s_mov_b32 m0, s0
	s_nop 0
	global_load_lds_dwordx4 v[130:131], off
	s_barrier
	s_waitcnt lgkmcnt(0)
	s_waitcnt lgkmcnt(0)
	v_mfma_f32_16x16x32_bf16 v[126:129], v[178:181], v[146:149], v[126:129]
	v_mfma_f32_16x16x32_bf16 v[122:125], v[178:181], v[154:157], v[122:125]
	v_mfma_f32_16x16x32_bf16 v[110:113], v[194:197], v[146:149], v[110:113]
	v_mfma_f32_16x16x32_bf16 v[106:109], v[194:197], v[154:157], v[106:109]
	v_mfma_f32_16x16x32_bf16 v[126:129], v[182:185], v[150:153], v[126:129]
	v_mfma_f32_16x16x32_bf16 v[122:125], v[182:185], v[158:161], v[122:125]
	v_mfma_f32_16x16x32_bf16 v[118:121], v[186:189], v[146:149], v[118:121]
	v_mfma_f32_16x16x32_bf16 v[114:117], v[186:189], v[154:157], v[114:117]
	v_mfma_f32_16x16x32_bf16 v[110:113], v[198:201], v[150:153], v[110:113]
	v_mfma_f32_16x16x32_bf16 v[106:109], v[198:201], v[158:161], v[106:109]
	v_mfma_f32_16x16x32_bf16 v[102:105], v[202:205], v[146:149], v[102:105]
	v_mfma_f32_16x16x32_bf16 v[98:101], v[202:205], v[154:157], v[98:101]
	v_mfma_f32_16x16x32_bf16 v[130:133], v[190:193], v[150:153], v[118:121]
	v_mfma_f32_16x16x32_bf16 v[162:165], v[190:193], v[158:161], v[114:117]
	v_mfma_f32_16x16x32_bf16 v[212:215], v[206:209], v[150:153], v[102:105]
	v_mfma_f32_16x16x32_bf16 v[224:227], v[206:209], v[158:161], v[98:101]
	s_barrier
	s_nop 0
	ds_read_b128 v[98:101], v166
	ds_read_b128 v[102:105], v167
	ds_read_b128 v[114:117], v168
	ds_read_b128 v[118:121], v169
	s_barrier
	s_waitcnt lgkmcnt(0)
	s_waitcnt lgkmcnt(3)
	v_mfma_f32_16x16x32_bf16 v[94:97], v[178:181], v[98:101], v[94:97]
	s_waitcnt lgkmcnt(1)
	v_mfma_f32_16x16x32_bf16 v[90:93], v[178:181], v[114:117], v[90:93]
	v_mfma_f32_16x16x32_bf16 v[78:81], v[194:197], v[98:101], v[78:81]
	v_mfma_f32_16x16x32_bf16 v[74:77], v[194:197], v[114:117], v[74:77]
	v_mfma_f32_16x16x32_bf16 v[94:97], v[182:185], v[102:105], v[94:97]
	s_waitcnt lgkmcnt(0)
	v_mfma_f32_16x16x32_bf16 v[90:93], v[182:185], v[118:121], v[90:93]
	v_mfma_f32_16x16x32_bf16 v[86:89], v[186:189], v[98:101], v[86:89]
	v_mfma_f32_16x16x32_bf16 v[82:85], v[186:189], v[114:117], v[82:85]
	v_mfma_f32_16x16x32_bf16 v[78:81], v[198:201], v[102:105], v[78:81]
	v_mfma_f32_16x16x32_bf16 v[74:77], v[198:201], v[118:121], v[74:77]
	v_mfma_f32_16x16x32_bf16 v[70:73], v[202:205], v[98:101], v[70:73]
	v_mfma_f32_16x16x32_bf16 v[66:69], v[202:205], v[114:117], v[66:69]
	v_mfma_f32_16x16x32_bf16 v[166:169], v[190:193], v[102:105], v[86:89]
	v_mfma_f32_16x16x32_bf16 v[178:181], v[190:193], v[118:121], v[82:85]
	v_mfma_f32_16x16x32_bf16 v[182:185], v[206:209], v[102:105], v[70:73]
	v_mfma_f32_16x16x32_bf16 v[186:189], v[206:209], v[118:121], v[66:69]
	s_barrier
	s_nop 1
	ds_read_b128 v[66:69], v139 offset:16384
	ds_read_b128 v[70:73], v139 offset:17408
	ds_read_b128 v[82:85], v142 offset:16384
	ds_read_b128 v[86:89], v142 offset:17408
	ds_read_b128 v[190:193], v141 offset:16384
	ds_read_b128 v[194:197], v141 offset:17408
	ds_read_b128 v[198:201], v140 offset:16384
	ds_read_b128 v[202:205], v140 offset:17408
	s_waitcnt vmcnt(4)
	s_barrier
	s_waitcnt lgkmcnt(0)
	s_waitcnt lgkmcnt(7)
	v_mfma_f32_16x16x32_bf16 v[62:65], v[66:69], v[146:149], v[62:65]
	v_mfma_f32_16x16x32_bf16 v[58:61], v[66:69], v[154:157], v[58:61]
	s_waitcnt lgkmcnt(3)
	v_mfma_f32_16x16x32_bf16 v[46:49], v[190:193], v[146:149], v[46:49]
	v_mfma_f32_16x16x32_bf16 v[42:45], v[190:193], v[154:157], v[42:45]
	v_mfma_f32_16x16x32_bf16 v[62:65], v[70:73], v[150:153], v[62:65]
	v_mfma_f32_16x16x32_bf16 v[58:61], v[70:73], v[158:161], v[58:61]
	v_mfma_f32_16x16x32_bf16 v[54:57], v[82:85], v[146:149], v[54:57]
	v_mfma_f32_16x16x32_bf16 v[50:53], v[82:85], v[154:157], v[50:53]
	s_waitcnt lgkmcnt(2)
	v_mfma_f32_16x16x32_bf16 v[46:49], v[194:197], v[150:153], v[46:49]
	v_mfma_f32_16x16x32_bf16 v[42:45], v[194:197], v[158:161], v[42:45]
	s_waitcnt lgkmcnt(1)
	v_mfma_f32_16x16x32_bf16 v[38:41], v[198:201], v[146:149], v[38:41]
	v_mfma_f32_16x16x32_bf16 v[34:37], v[198:201], v[154:157], v[34:37]
	v_mfma_f32_16x16x32_bf16 v[206:209], v[86:89], v[150:153], v[54:57]
	v_mfma_f32_16x16x32_bf16 v[228:231], v[86:89], v[158:161], v[50:53]
	s_waitcnt lgkmcnt(0)
	v_mfma_f32_16x16x32_bf16 v[146:149], v[202:205], v[150:153], v[38:41]
	v_mfma_f32_16x16x32_bf16 v[150:153], v[202:205], v[158:161], v[34:37]
	v_mfma_f32_16x16x32_bf16 v[30:33], v[66:69], v[98:101], v[30:33]
	v_mfma_f32_16x16x32_bf16 v[26:29], v[66:69], v[114:117], v[26:29]
	v_mfma_f32_16x16x32_bf16 v[14:17], v[190:193], v[98:101], v[14:17]
	v_mfma_f32_16x16x32_bf16 v[10:13], v[190:193], v[114:117], v[10:13]
	v_mfma_f32_16x16x32_bf16 v[30:33], v[70:73], v[102:105], v[30:33]
	v_mfma_f32_16x16x32_bf16 v[26:29], v[70:73], v[118:121], v[26:29]
	v_mfma_f32_16x16x32_bf16 v[22:25], v[82:85], v[98:101], v[22:25]
	v_mfma_f32_16x16x32_bf16 v[18:21], v[82:85], v[114:117], v[18:21]
	v_mfma_f32_16x16x32_bf16 v[14:17], v[194:197], v[102:105], v[14:17]
	v_mfma_f32_16x16x32_bf16 v[10:13], v[194:197], v[118:121], v[10:13]
	v_mfma_f32_16x16x32_bf16 v[6:9], v[198:201], v[98:101], v[6:9]
	v_mfma_f32_16x16x32_bf16 v[2:5], v[198:201], v[114:117], v[2:5]
	v_mfma_f32_16x16x32_bf16 v[154:157], v[86:89], v[102:105], v[22:25]
	v_mfma_f32_16x16x32_bf16 v[158:161], v[86:89], v[118:121], v[18:21]
	v_mfma_f32_16x16x32_bf16 v[190:193], v[202:205], v[102:105], v[6:9]
	v_mfma_f32_16x16x32_bf16 v[194:197], v[202:205], v[118:121], v[2:5]
	s_barrier
	s_nop 1
	ds_read_b128 v[2:5], v170
	ds_read_b128 v[6:9], v171
	ds_read_b128 v[198:201], v172
	ds_read_b128 v[170:173], v173
	ds_read_b128 v[18:21], v139 offset:32768
	ds_read_b128 v[22:25], v139 offset:33792
	ds_read_b128 v[34:37], v142 offset:32768
	ds_read_b128 v[38:41], v142 offset:33792
	ds_read_b128 v[50:53], v141 offset:32768
	ds_read_b128 v[54:57], v141 offset:33792
	ds_read_b128 v[202:205], v140 offset:32768
	ds_read_b128 v[232:235], v140 offset:33792
	s_waitcnt vmcnt(2)
	s_barrier
	s_waitcnt lgkmcnt(0)
	s_waitcnt lgkmcnt(7)
	v_mfma_f32_16x16x32_bf16 v[66:69], v[18:21], v[2:5], v[126:129]
	s_waitcnt lgkmcnt(6)
	v_mfma_f32_16x16x32_bf16 v[114:117], v[22:25], v[6:9], v[66:69]
	v_mfma_f32_16x16x32_bf16 v[66:69], v[18:21], v[198:201], v[122:125]
	v_mfma_f32_16x16x32_bf16 v[118:121], v[22:25], v[170:173], v[66:69]
	s_waitcnt lgkmcnt(5)
	v_mfma_f32_16x16x32_bf16 v[66:69], v[34:37], v[2:5], v[130:133]
	s_waitcnt lgkmcnt(4)
	v_mfma_f32_16x16x32_bf16 v[98:101], v[38:41], v[6:9], v[66:69]
	v_mfma_f32_16x16x32_bf16 v[66:69], v[34:37], v[198:201], v[162:165]
	v_mfma_f32_16x16x32_bf16 v[102:105], v[38:41], v[170:173], v[66:69]
	s_waitcnt lgkmcnt(3)
	v_mfma_f32_16x16x32_bf16 v[66:69], v[50:53], v[2:5], v[110:113]
	s_waitcnt lgkmcnt(2)
	v_mfma_f32_16x16x32_bf16 v[82:85], v[54:57], v[6:9], v[66:69]
	v_mfma_f32_16x16x32_bf16 v[66:69], v[50:53], v[198:201], v[106:109]
	v_mfma_f32_16x16x32_bf16 v[86:89], v[54:57], v[170:173], v[66:69]
	s_waitcnt lgkmcnt(1)
	v_mfma_f32_16x16x32_bf16 v[66:69], v[202:205], v[2:5], v[212:215]
	v_mfma_f32_16x16x32_bf16 v[70:73], v[202:205], v[198:201], v[224:227]
	s_waitcnt lgkmcnt(0)
	v_mfma_f32_16x16x32_bf16 v[66:69], v[232:235], v[6:9], v[66:69]
	v_mfma_f32_16x16x32_bf16 v[70:73], v[232:235], v[170:173], v[70:73]
	s_barrier
	ds_read_b128 v[130:133], v174
	ds_read_b128 v[162:165], v175
	ds_read_b128 v[212:215], v176
	ds_read_b128 v[174:177], v177
	s_waitcnt vmcnt(0)
	s_barrier
	s_waitcnt lgkmcnt(0)
	s_waitcnt lgkmcnt(3)
	v_mfma_f32_16x16x32_bf16 v[94:97], v[18:21], v[130:133], v[94:97]
	s_waitcnt lgkmcnt(1)
	v_mfma_f32_16x16x32_bf16 v[18:21], v[18:21], v[212:215], v[90:93]
	s_waitcnt lgkmcnt(0)
	v_mfma_f32_16x16x32_bf16 v[122:125], v[22:25], v[174:177], v[18:21]
	v_mfma_f32_16x16x32_bf16 v[18:21], v[34:37], v[130:133], v[166:169]
	v_mfma_f32_16x16x32_bf16 v[110:113], v[38:41], v[162:165], v[18:21]
	v_mfma_f32_16x16x32_bf16 v[18:21], v[34:37], v[212:215], v[178:181]
	v_mfma_f32_16x16x32_bf16 v[106:109], v[38:41], v[174:177], v[18:21]
	v_mfma_f32_16x16x32_bf16 v[18:21], v[50:53], v[130:133], v[78:81]
	v_mfma_f32_16x16x32_bf16 v[126:129], v[22:25], v[162:165], v[94:97]
	v_mfma_f32_16x16x32_bf16 v[94:97], v[54:57], v[162:165], v[18:21]
	v_mfma_f32_16x16x32_bf16 v[18:21], v[50:53], v[212:215], v[74:77]
	v_mfma_f32_16x16x32_bf16 v[90:93], v[54:57], v[174:177], v[18:21]
	v_mfma_f32_16x16x32_bf16 v[18:21], v[202:205], v[130:133], v[182:185]
	v_mfma_f32_16x16x32_bf16 v[78:81], v[232:235], v[162:165], v[18:21]
	v_mfma_f32_16x16x32_bf16 v[18:21], v[202:205], v[212:215], v[186:189]
	v_mfma_f32_16x16x32_bf16 v[74:77], v[232:235], v[174:177], v[18:21]
	s_barrier
	ds_read_b128 v[166:169], v139 offset:49152
	ds_read_b128 v[178:181], v139 offset:50176
	ds_read_b128 v[182:185], v142 offset:49152
	ds_read_b128 v[186:189], v142 offset:50176
	ds_read_b128 v[202:205], v141 offset:49152
	ds_read_b128 v[224:227], v141 offset:50176
	ds_read_b128 v[232:235], v140 offset:49152
	ds_read_b128 v[138:141], v140 offset:50176
	s_barrier
	s_waitcnt lgkmcnt(0)
	s_waitcnt lgkmcnt(7)
	v_mfma_f32_16x16x32_bf16 v[18:21], v[166:169], v[2:5], v[62:65]
	s_waitcnt lgkmcnt(6)
	v_mfma_f32_16x16x32_bf16 v[50:53], v[178:181], v[6:9], v[18:21]
	v_mfma_f32_16x16x32_bf16 v[18:21], v[166:169], v[198:201], v[58:61]
	v_mfma_f32_16x16x32_bf16 v[54:57], v[178:181], v[170:173], v[18:21]
	s_waitcnt lgkmcnt(5)
	v_mfma_f32_16x16x32_bf16 v[18:21], v[182:185], v[2:5], v[206:209]
	s_waitcnt lgkmcnt(4)
	v_mfma_f32_16x16x32_bf16 v[34:37], v[186:189], v[6:9], v[18:21]
	v_mfma_f32_16x16x32_bf16 v[18:21], v[182:185], v[198:201], v[228:231]
	v_mfma_f32_16x16x32_bf16 v[38:41], v[186:189], v[170:173], v[18:21]
	s_waitcnt lgkmcnt(3)
	v_mfma_f32_16x16x32_bf16 v[18:21], v[202:205], v[2:5], v[46:49]
	s_waitcnt lgkmcnt(1)
	v_mfma_f32_16x16x32_bf16 v[2:5], v[232:235], v[2:5], v[146:149]
	v_mfma_f32_16x16x32_bf16 v[18:21], v[224:227], v[6:9], v[18:21]
	v_mfma_f32_16x16x32_bf16 v[22:25], v[202:205], v[198:201], v[42:45]
	s_waitcnt lgkmcnt(0)
	v_mfma_f32_16x16x32_bf16 v[2:5], v[138:141], v[6:9], v[2:5]
	v_mfma_f32_16x16x32_bf16 v[6:9], v[232:235], v[198:201], v[150:153]
	v_mfma_f32_16x16x32_bf16 v[22:25], v[224:227], v[170:173], v[22:25]
	v_mfma_f32_16x16x32_bf16 v[6:9], v[138:141], v[170:173], v[6:9]
	v_mfma_f32_16x16x32_bf16 v[26:29], v[166:169], v[212:215], v[26:29]
	v_mfma_f32_16x16x32_bf16 v[58:61], v[178:181], v[174:177], v[26:29]
	v_mfma_f32_16x16x32_bf16 v[26:29], v[182:185], v[130:133], v[154:157]
	v_mfma_f32_16x16x32_bf16 v[46:49], v[186:189], v[162:165], v[26:29]
	v_mfma_f32_16x16x32_bf16 v[26:29], v[182:185], v[212:215], v[158:161]
	v_mfma_f32_16x16x32_bf16 v[10:13], v[202:205], v[212:215], v[10:13]
	v_mfma_f32_16x16x32_bf16 v[30:33], v[166:169], v[130:133], v[30:33]
	v_mfma_f32_16x16x32_bf16 v[42:45], v[186:189], v[174:177], v[26:29]
	v_mfma_f32_16x16x32_bf16 v[14:17], v[202:205], v[130:133], v[14:17]
	v_mfma_f32_16x16x32_bf16 v[26:29], v[224:227], v[174:177], v[10:13]
	v_mfma_f32_16x16x32_bf16 v[10:13], v[232:235], v[130:133], v[190:193]
	v_mfma_f32_16x16x32_bf16 v[62:65], v[178:181], v[162:165], v[30:33]
	v_mfma_f32_16x16x32_bf16 v[30:33], v[224:227], v[162:165], v[14:17]
	v_mfma_f32_16x16x32_bf16 v[14:17], v[138:141], v[162:165], v[10:13]
	v_mfma_f32_16x16x32_bf16 v[10:13], v[232:235], v[212:215], v[194:197]
	v_mfma_f32_16x16x32_bf16 v[10:13], v[138:141], v[174:177], v[10:13]
	s_movk_i32 s0, 0x100
	v_cmp_gt_u32_e32 vcc, s0, v134
	s_barrier
	s_and_saveexec_b64 s[0:1], vcc
	s_cbranch_execz .LBB0_291
	s_barrier

.LBB0_709:
	v_or_b32_e32 v160, 0x10000, v156
	v_or_b32_e32 v162, 0x10000, v158
	v_or_b32_e32 v161, 0x10000, v157
	ds_read_b128 v[170:173], v160
	ds_read_b128 v[174:177], v161
	v_or_b32_e32 v163, 0x10000, v159
	ds_read_b128 v[178:181], v162
	ds_read_b128 v[182:185], v163
	s_add_u32 s25, s17, s14
	s_addc_u32 s27, s23, s15
	s_add_u32 s26, s25, 0x80
	v_add_u32_e32 v164, 0xc000, v138
	s_addc_u32 s27, s27, 0
	v_readfirstlane_b32 s25, v164
	v_add_u32_e32 v165, 0xe000, v138
	ds_read_b128 v[186:189], v140
	ds_read_b128 v[190:193], v140 offset:1024
	ds_read_b128 v[194:197], v143
	ds_read_b128 v[198:201], v143 offset:1024
	ds_read_b128 v[202:205], v142
	ds_read_b128 v[206:209], v142 offset:1024
	ds_read_b128 v[212:215], v141
	ds_read_b128 v[224:227], v141 offset:1024
	s_mov_b32 m0, s25
	v_lshl_add_u64 v[166:167], s[26:27], 0, v[132:133]
	v_readfirstlane_b32 s25, v165
	global_load_lds_dwordx4 v[166:167], off
	v_lshl_add_u64 v[166:167], s[26:27], 0, v[130:131]
	s_mov_b32 m0, s25
	s_nop 0
	global_load_lds_dwordx4 v[166:167], off
	s_waitcnt lgkmcnt(8)
	s_barrier
	s_waitcnt lgkmcnt(0)
	s_waitcnt lgkmcnt(0)
	v_mfma_f32_16x16x32_bf16 v[126:129], v[186:189], v[170:173], v[126:129]
	v_mfma_f32_16x16x32_bf16 v[122:125], v[186:189], v[178:181], v[122:125]
	v_mfma_f32_16x16x32_bf16 v[118:121], v[194:197], v[170:173], v[118:121]
	v_mfma_f32_16x16x32_bf16 v[114:117], v[194:197], v[178:181], v[114:117]
	v_mfma_f32_16x16x32_bf16 v[110:113], v[202:205], v[170:173], v[110:113]
	v_mfma_f32_16x16x32_bf16 v[106:109], v[202:205], v[178:181], v[106:109]
	v_mfma_f32_16x16x32_bf16 v[102:105], v[212:215], v[170:173], v[102:105]
	v_mfma_f32_16x16x32_bf16 v[98:101], v[212:215], v[178:181], v[98:101]
	v_mfma_f32_16x16x32_bf16 v[126:129], v[190:193], v[174:177], v[126:129]
	v_mfma_f32_16x16x32_bf16 v[122:125], v[190:193], v[182:185], v[122:125]
	v_mfma_f32_16x16x32_bf16 v[118:121], v[198:201], v[174:177], v[118:121]
	v_mfma_f32_16x16x32_bf16 v[114:117], v[198:201], v[182:185], v[114:117]
	v_mfma_f32_16x16x32_bf16 v[110:113], v[206:209], v[174:177], v[110:113]
	v_mfma_f32_16x16x32_bf16 v[106:109], v[206:209], v[182:185], v[106:109]
	v_mfma_f32_16x16x32_bf16 v[102:105], v[224:227], v[174:177], v[102:105]
	v_mfma_f32_16x16x32_bf16 v[98:101], v[224:227], v[182:185], v[98:101]
	s_barrier
	s_add_u32 s25, s6, s14
	s_addc_u32 s28, s7, s15
	s_add_u32 s26, s25, 0x100
	v_or_b32_e32 v166, 0x14000, v156
	v_or_b32_e32 v168, 0x14000, v158
	s_addc_u32 s27, s28, 0
	v_readfirstlane_b32 s29, v144
	v_or_b32_e32 v167, 0x14000, v157
	ds_read_b128 v[228:231], v166
	ds_read_b128 v[232:235], v167
	v_or_b32_e32 v169, 0x14000, v159
	ds_read_b128 v[236:239], v168
	ds_read_b128 v[240:243], v169
	s_mov_b32 m0, s29
	v_lshl_add_u64 v[216:217], s[26:27], 0, v[132:133]
	global_load_lds_dwordx4 v[216:217], off
	v_lshl_add_u64 v[216:217], s[26:27], 0, v[130:131]
	v_readfirstlane_b32 s26, v145
	s_mov_b32 m0, s26
	s_nop 0
	global_load_lds_dwordx4 v[216:217], off
	s_barrier
	s_waitcnt lgkmcnt(0)
	s_waitcnt lgkmcnt(0)
	v_mfma_f32_16x16x32_bf16 v[94:97], v[186:189], v[228:231], v[94:97]
	v_mfma_f32_16x16x32_bf16 v[90:93], v[186:189], v[236:239], v[90:93]
	v_mfma_f32_16x16x32_bf16 v[86:89], v[194:197], v[228:231], v[86:89]
	v_mfma_f32_16x16x32_bf16 v[82:85], v[194:197], v[236:239], v[82:85]
	v_mfma_f32_16x16x32_bf16 v[78:81], v[202:205], v[228:231], v[78:81]
	v_mfma_f32_16x16x32_bf16 v[74:77], v[202:205], v[236:239], v[74:77]
	v_mfma_f32_16x16x32_bf16 v[70:73], v[212:215], v[228:231], v[70:73]
	v_mfma_f32_16x16x32_bf16 v[66:69], v[212:215], v[236:239], v[66:69]
	v_mfma_f32_16x16x32_bf16 v[94:97], v[190:193], v[232:235], v[94:97]
	v_mfma_f32_16x16x32_bf16 v[90:93], v[190:193], v[240:243], v[90:93]
	v_mfma_f32_16x16x32_bf16 v[86:89], v[198:201], v[232:235], v[86:89]
	v_mfma_f32_16x16x32_bf16 v[82:85], v[198:201], v[240:243], v[82:85]
	v_mfma_f32_16x16x32_bf16 v[78:81], v[206:209], v[232:235], v[78:81]
	v_mfma_f32_16x16x32_bf16 v[74:77], v[206:209], v[240:243], v[74:77]
	v_mfma_f32_16x16x32_bf16 v[70:73], v[224:227], v[232:235], v[70:73]
	v_mfma_f32_16x16x32_bf16 v[66:69], v[224:227], v[240:243], v[66:69]
	s_add_u32 s29, s8, s14
	s_addc_u32 s30, s9, s15
	s_add_u32 s26, s29, 0x100
	s_addc_u32 s27, s30, 0
	v_readfirstlane_b32 s31, v138
	s_barrier
	ds_read_b128 v[186:189], v140 offset:16384
	ds_read_b128 v[190:193], v140 offset:17408
	ds_read_b128 v[194:197], v143 offset:16384
	ds_read_b128 v[198:201], v143 offset:17408
	ds_read_b128 v[202:205], v142 offset:16384
	ds_read_b128 v[206:209], v142 offset:17408
	ds_read_b128 v[212:215], v141 offset:16384
	ds_read_b128 v[224:227], v141 offset:17408
	s_mov_b32 m0, s31
	v_lshl_add_u64 v[216:217], s[26:27], 0, v[132:133]
	global_load_lds_dwordx4 v[216:217], off
	v_lshl_add_u64 v[216:217], s[26:27], 0, v[130:131]
	v_readfirstlane_b32 s26, v139
	s_mov_b32 m0, s26
	s_nop 0
	global_load_lds_dwordx4 v[216:217], off
	s_barrier
	s_waitcnt lgkmcnt(0)
	s_waitcnt lgkmcnt(0)
	v_mfma_f32_16x16x32_bf16 v[62:65], v[186:189], v[170:173], v[62:65]
	v_mfma_f32_16x16x32_bf16 v[58:61], v[186:189], v[178:181], v[58:61]
	v_mfma_f32_16x16x32_bf16 v[54:57], v[194:197], v[170:173], v[54:57]
	v_mfma_f32_16x16x32_bf16 v[50:53], v[194:197], v[178:181], v[50:53]
	v_mfma_f32_16x16x32_bf16 v[46:49], v[202:205], v[170:173], v[46:49]
	v_mfma_f32_16x16x32_bf16 v[42:45], v[202:205], v[178:181], v[42:45]
	v_mfma_f32_16x16x32_bf16 v[38:41], v[212:215], v[170:173], v[38:41]
	v_mfma_f32_16x16x32_bf16 v[34:37], v[212:215], v[178:181], v[34:37]
	v_mfma_f32_16x16x32_bf16 v[62:65], v[190:193], v[174:177], v[62:65]
	v_mfma_f32_16x16x32_bf16 v[58:61], v[190:193], v[182:185], v[58:61]
	v_mfma_f32_16x16x32_bf16 v[54:57], v[198:201], v[174:177], v[54:57]
	v_mfma_f32_16x16x32_bf16 v[50:53], v[198:201], v[182:185], v[50:53]
	v_mfma_f32_16x16x32_bf16 v[46:49], v[206:209], v[174:177], v[46:49]
	v_mfma_f32_16x16x32_bf16 v[42:45], v[206:209], v[182:185], v[42:45]
	v_mfma_f32_16x16x32_bf16 v[38:41], v[224:227], v[174:177], v[38:41]
	v_mfma_f32_16x16x32_bf16 v[34:37], v[224:227], v[182:185], v[34:37]
	s_barrier
	s_add_u32 s31, s10, s14
	s_addc_u32 s34, s11, s15
	s_add_u32 s26, s31, 0x100
	s_addc_u32 s27, s34, 0
	v_readfirstlane_b32 s35, v146
	s_mov_b32 m0, s35
	v_lshl_add_u64 v[170:171], s[26:27], 0, v[132:133]
	global_load_lds_dwordx4 v[170:171], off
	v_lshl_add_u64 v[170:171], s[26:27], 0, v[130:131]
	v_readfirstlane_b32 s26, v147
	s_mov_b32 m0, s26
	s_nop 0
	global_load_lds_dwordx4 v[170:171], off
	s_waitcnt vmcnt(6)
	s_barrier
	v_mfma_f32_16x16x32_bf16 v[30:33], v[186:189], v[228:231], v[30:33]
	v_mfma_f32_16x16x32_bf16 v[26:29], v[186:189], v[236:239], v[26:29]
	v_mfma_f32_16x16x32_bf16 v[22:25], v[194:197], v[228:231], v[22:25]
	v_mfma_f32_16x16x32_bf16 v[18:21], v[194:197], v[236:239], v[18:21]
	v_mfma_f32_16x16x32_bf16 v[14:17], v[202:205], v[228:231], v[14:17]
	v_mfma_f32_16x16x32_bf16 v[10:13], v[202:205], v[236:239], v[10:13]
	v_mfma_f32_16x16x32_bf16 v[6:9], v[212:215], v[228:231], v[6:9]
	v_mfma_f32_16x16x32_bf16 v[2:5], v[212:215], v[236:239], v[2:5]
	v_mfma_f32_16x16x32_bf16 v[30:33], v[190:193], v[232:235], v[30:33]
	v_mfma_f32_16x16x32_bf16 v[26:29], v[190:193], v[240:243], v[26:29]
	v_mfma_f32_16x16x32_bf16 v[22:25], v[198:201], v[232:235], v[22:25]
	v_mfma_f32_16x16x32_bf16 v[18:21], v[198:201], v[240:243], v[18:21]
	v_mfma_f32_16x16x32_bf16 v[14:17], v[206:209], v[232:235], v[14:17]
	v_mfma_f32_16x16x32_bf16 v[10:13], v[206:209], v[240:243], v[10:13]
	v_mfma_f32_16x16x32_bf16 v[6:9], v[224:227], v[232:235], v[6:9]
	v_mfma_f32_16x16x32_bf16 v[2:5], v[224:227], v[240:243], v[2:5]
	v_or_b32_e32 v170, 0x18000, v156
	v_or_b32_e32 v172, 0x18000, v158
	s_barrier
	v_or_b32_e32 v171, 0x18000, v157
	ds_read_b128 v[178:181], v170
	ds_read_b128 v[182:185], v171
	v_or_b32_e32 v173, 0x18000, v159
	ds_read_b128 v[186:189], v172
	ds_read_b128 v[190:193], v173
	s_add_u32 s26, s1, s14
	s_addc_u32 s27, s16, s15
	v_readfirstlane_b32 s35, v148
	ds_read_b128 v[194:197], v140 offset:32768
	ds_read_b128 v[198:201], v140 offset:33792
	ds_read_b128 v[202:205], v143 offset:32768
	ds_read_b128 v[206:209], v143 offset:33792
	ds_read_b128 v[212:215], v142 offset:32768
	ds_read_b128 v[224:227], v142 offset:33792
	ds_read_b128 v[228:231], v141 offset:32768
	ds_read_b128 v[232:235], v141 offset:33792
	s_mov_b32 m0, s35
	v_lshl_add_u64 v[174:175], s[26:27], 0, v[132:133]
	global_load_lds_dwordx4 v[174:175], off
	v_lshl_add_u64 v[174:175], s[26:27], 0, v[130:131]
	v_readfirstlane_b32 s26, v149
	s_mov_b32 m0, s26
	s_nop 0
	global_load_lds_dwordx4 v[174:175], off
	s_waitcnt lgkmcnt(8)
	s_barrier
	s_waitcnt lgkmcnt(0)
	s_waitcnt lgkmcnt(0)
	v_mfma_f32_16x16x32_bf16 v[126:129], v[194:197], v[178:181], v[126:129]
	v_mfma_f32_16x16x32_bf16 v[122:125], v[194:197], v[186:189], v[122:125]
	v_mfma_f32_16x16x32_bf16 v[118:121], v[202:205], v[178:181], v[118:121]
	v_mfma_f32_16x16x32_bf16 v[114:117], v[202:205], v[186:189], v[114:117]
	v_mfma_f32_16x16x32_bf16 v[110:113], v[212:215], v[178:181], v[110:113]
	v_mfma_f32_16x16x32_bf16 v[106:109], v[212:215], v[186:189], v[106:109]
	v_mfma_f32_16x16x32_bf16 v[102:105], v[228:231], v[178:181], v[102:105]
	v_mfma_f32_16x16x32_bf16 v[98:101], v[228:231], v[186:189], v[98:101]
	v_mfma_f32_16x16x32_bf16 v[126:129], v[198:201], v[182:185], v[126:129]
	v_mfma_f32_16x16x32_bf16 v[122:125], v[198:201], v[190:193], v[122:125]
	v_mfma_f32_16x16x32_bf16 v[118:121], v[206:209], v[182:185], v[118:121]
	v_mfma_f32_16x16x32_bf16 v[114:117], v[206:209], v[190:193], v[114:117]
	v_mfma_f32_16x16x32_bf16 v[110:113], v[224:227], v[182:185], v[110:113]
	v_mfma_f32_16x16x32_bf16 v[106:109], v[224:227], v[190:193], v[106:109]
	v_mfma_f32_16x16x32_bf16 v[102:105], v[232:235], v[182:185], v[102:105]
	v_mfma_f32_16x16x32_bf16 v[98:101], v[232:235], v[190:193], v[98:101]
	s_barrier
	s_add_u32 s26, s25, 0x180
	v_or_b32_e32 v174, 0x1c000, v156
	v_or_b32_e32 v176, 0x1c000, v158
	s_addc_u32 s27, s28, 0
	v_readfirstlane_b32 s25, v150
	v_or_b32_e32 v175, 0x1c000, v157
	ds_read_b128 v[236:239], v174
	ds_read_b128 v[240:243], v175
	v_or_b32_e32 v177, 0x1c000, v159
	ds_read_b128 v[244:247], v176
	ds_read_b128 v[248:251], v177
	s_mov_b32 m0, s25
	v_lshl_add_u64 v[216:217], s[26:27], 0, v[132:133]
	v_readfirstlane_b32 s25, v151
	global_load_lds_dwordx4 v[216:217], off
	v_lshl_add_u64 v[216:217], s[26:27], 0, v[130:131]
	s_mov_b32 m0, s25
	s_nop 0
	global_load_lds_dwordx4 v[216:217], off
	s_barrier
	s_waitcnt lgkmcnt(0)
	s_waitcnt lgkmcnt(0)
	v_mfma_f32_16x16x32_bf16 v[94:97], v[194:197], v[236:239], v[94:97]
	v_mfma_f32_16x16x32_bf16 v[90:93], v[194:197], v[244:247], v[90:93]
	v_mfma_f32_16x16x32_bf16 v[86:89], v[202:205], v[236:239], v[86:89]
	v_mfma_f32_16x16x32_bf16 v[82:85], v[202:205], v[244:247], v[82:85]
	v_mfma_f32_16x16x32_bf16 v[78:81], v[212:215], v[236:239], v[78:81]
	v_mfma_f32_16x16x32_bf16 v[74:77], v[212:215], v[244:247], v[74:77]
	v_mfma_f32_16x16x32_bf16 v[70:73], v[228:231], v[236:239], v[70:73]
	v_mfma_f32_16x16x32_bf16 v[66:69], v[228:231], v[244:247], v[66:69]
	v_mfma_f32_16x16x32_bf16 v[94:97], v[198:201], v[240:243], v[94:97]
	v_mfma_f32_16x16x32_bf16 v[90:93], v[198:201], v[248:251], v[90:93]
	v_mfma_f32_16x16x32_bf16 v[86:89], v[206:209], v[240:243], v[86:89]
	v_mfma_f32_16x16x32_bf16 v[82:85], v[206:209], v[248:251], v[82:85]
	v_mfma_f32_16x16x32_bf16 v[78:81], v[224:227], v[240:243], v[78:81]
	v_mfma_f32_16x16x32_bf16 v[74:77], v[224:227], v[248:251], v[74:77]
	v_mfma_f32_16x16x32_bf16 v[70:73], v[232:235], v[240:243], v[70:73]
	v_mfma_f32_16x16x32_bf16 v[66:69], v[232:235], v[248:251], v[66:69]
	s_add_u32 s26, s29, 0x180
	s_addc_u32 s27, s30, 0
	v_readfirstlane_b32 s25, v152
	s_barrier
	ds_read_b128 v[194:197], v140 offset:49152
	ds_read_b128 v[198:201], v140 offset:50176
	ds_read_b128 v[202:205], v143 offset:49152
	ds_read_b128 v[206:209], v143 offset:50176
	ds_read_b128 v[212:215], v142 offset:49152
	ds_read_b128 v[224:227], v142 offset:50176
	ds_read_b128 v[228:231], v141 offset:49152
	ds_read_b128 v[232:235], v141 offset:50176
	s_mov_b32 m0, s25
	v_lshl_add_u64 v[216:217], s[26:27], 0, v[132:133]
	v_readfirstlane_b32 s25, v153
	global_load_lds_dwordx4 v[216:217], off
	v_lshl_add_u64 v[216:217], s[26:27], 0, v[130:131]
	s_mov_b32 m0, s25
	s_nop 0
	global_load_lds_dwordx4 v[216:217], off
	s_barrier
	s_waitcnt lgkmcnt(0)
	s_waitcnt lgkmcnt(0)
	v_mfma_f32_16x16x32_bf16 v[62:65], v[194:197], v[178:181], v[62:65]
	v_mfma_f32_16x16x32_bf16 v[58:61], v[194:197], v[186:189], v[58:61]
	v_mfma_f32_16x16x32_bf16 v[54:57], v[202:205], v[178:181], v[54:57]
	v_mfma_f32_16x16x32_bf16 v[50:53], v[202:205], v[186:189], v[50:53]
	v_mfma_f32_16x16x32_bf16 v[46:49], v[212:215], v[178:181], v[46:49]
	v_mfma_f32_16x16x32_bf16 v[42:45], v[212:215], v[186:189], v[42:45]
	v_mfma_f32_16x16x32_bf16 v[38:41], v[228:231], v[178:181], v[38:41]
	v_mfma_f32_16x16x32_bf16 v[34:37], v[228:231], v[186:189], v[34:37]
	v_mfma_f32_16x16x32_bf16 v[62:65], v[198:201], v[182:185], v[62:65]
	v_mfma_f32_16x16x32_bf16 v[58:61], v[198:201], v[190:193], v[58:61]
	v_mfma_f32_16x16x32_bf16 v[54:57], v[206:209], v[182:185], v[54:57]
	v_mfma_f32_16x16x32_bf16 v[50:53], v[206:209], v[190:193], v[50:53]
	v_mfma_f32_16x16x32_bf16 v[46:49], v[224:227], v[182:185], v[46:49]
	v_mfma_f32_16x16x32_bf16 v[42:45], v[224:227], v[190:193], v[42:45]
	v_mfma_f32_16x16x32_bf16 v[38:41], v[232:235], v[182:185], v[38:41]
	v_mfma_f32_16x16x32_bf16 v[34:37], v[232:235], v[190:193], v[34:37]
	s_barrier
	s_add_u32 s26, s31, 0x180
	s_addc_u32 s27, s34, 0
	v_readfirstlane_b32 s25, v154
	s_mov_b32 m0, s25
	v_lshl_add_u64 v[178:179], s[26:27], 0, v[132:133]
	v_readfirstlane_b32 s25, v155
	global_load_lds_dwordx4 v[178:179], off
	v_lshl_add_u64 v[178:179], s[26:27], 0, v[130:131]
	s_mov_b32 m0, s25
	s_nop 0
	global_load_lds_dwordx4 v[178:179], off
	s_waitcnt vmcnt(6)
	s_barrier
	v_mfma_f32_16x16x32_bf16 v[30:33], v[194:197], v[236:239], v[30:33]
	v_mfma_f32_16x16x32_bf16 v[26:29], v[194:197], v[244:247], v[26:29]
	v_mfma_f32_16x16x32_bf16 v[22:25], v[202:205], v[236:239], v[22:25]
	v_mfma_f32_16x16x32_bf16 v[18:21], v[202:205], v[244:247], v[18:21]
	v_mfma_f32_16x16x32_bf16 v[14:17], v[212:215], v[236:239], v[14:17]
	v_mfma_f32_16x16x32_bf16 v[10:13], v[212:215], v[244:247], v[10:13]
	v_mfma_f32_16x16x32_bf16 v[6:9], v[228:231], v[236:239], v[6:9]
	v_mfma_f32_16x16x32_bf16 v[2:5], v[228:231], v[244:247], v[2:5]
	v_mfma_f32_16x16x32_bf16 v[30:33], v[198:201], v[240:243], v[30:33]
	v_mfma_f32_16x16x32_bf16 v[26:29], v[198:201], v[248:251], v[26:29]
	v_mfma_f32_16x16x32_bf16 v[22:25], v[206:209], v[240:243], v[22:25]
	v_mfma_f32_16x16x32_bf16 v[18:21], v[206:209], v[248:251], v[18:21]
	v_mfma_f32_16x16x32_bf16 v[14:17], v[224:227], v[240:243], v[14:17]
	v_mfma_f32_16x16x32_bf16 v[10:13], v[224:227], v[248:251], v[10:13]
	v_mfma_f32_16x16x32_bf16 v[6:9], v[232:235], v[240:243], v[6:9]
	v_mfma_f32_16x16x32_bf16 v[2:5], v[232:235], v[248:251], v[2:5]
	s_add_i32 s24, s24, 2
	s_add_u32 s14, s14, 0x100
	s_addc_u32 s15, s15, 0
	s_cmp_lt_u32 s24, 28
	s_barrier
	s_cbranch_scc1 .LBB0_709
	s_add_u32 s6, s12, 0xf80
	s_addc_u32 s7, s13, 0
	v_readfirstlane_b32 s1, v164
	ds_read_b128 v[144:147], v160
	ds_read_b128 v[148:151], v161
	ds_read_b128 v[152:155], v162
	ds_read_b128 v[156:159], v163
	ds_read_b128 v[160:163], v140
	ds_read_b128 v[178:181], v140 offset:1024
	ds_read_b128 v[182:185], v143
	ds_read_b128 v[186:189], v143 offset:1024
	ds_read_b128 v[190:193], v142
	ds_read_b128 v[194:197], v142 offset:1024
	ds_read_b128 v[198:201], v141
	ds_read_b128 v[202:205], v141 offset:1024
	s_mov_b32 m0, s1
	v_lshl_add_u64 v[132:133], s[6:7], 0, v[132:133]
	v_readfirstlane_b32 s1, v165
	global_load_lds_dwordx4 v[132:133], off
	v_lshl_add_u64 v[130:131], s[6:7], 0, v[130:131]
	s_mov_b32 m0, s1
	s_nop 0
	global_load_lds_dwordx4 v[130:131], off
	s_barrier
	s_waitcnt lgkmcnt(0)
	s_waitcnt lgkmcnt(0)
	v_mfma_f32_16x16x32_bf16 v[126:129], v[160:163], v[144:147], v[126:129]
	v_mfma_f32_16x16x32_bf16 v[122:125], v[160:163], v[152:155], v[122:125]
	v_mfma_f32_16x16x32_bf16 v[118:121], v[182:185], v[144:147], v[118:121]
	v_mfma_f32_16x16x32_bf16 v[114:117], v[182:185], v[152:155], v[114:117]
	v_mfma_f32_16x16x32_bf16 v[110:113], v[190:193], v[144:147], v[110:113]
	v_mfma_f32_16x16x32_bf16 v[106:109], v[190:193], v[152:155], v[106:109]
	v_mfma_f32_16x16x32_bf16 v[98:101], v[198:201], v[152:155], v[98:101]
	v_mfma_f32_16x16x32_bf16 v[126:129], v[178:181], v[148:151], v[126:129]
	v_mfma_f32_16x16x32_bf16 v[122:125], v[178:181], v[156:159], v[122:125]
	v_mfma_f32_16x16x32_bf16 v[118:121], v[186:189], v[148:151], v[118:121]
	v_mfma_f32_16x16x32_bf16 v[114:117], v[186:189], v[156:159], v[114:117]
	v_mfma_f32_16x16x32_bf16 v[110:113], v[194:197], v[148:151], v[110:113]
	v_mfma_f32_16x16x32_bf16 v[106:109], v[194:197], v[156:159], v[106:109]
	v_mfma_f32_16x16x32_bf16 v[102:105], v[198:201], v[144:147], v[102:105]
	v_mfma_f32_16x16x32_bf16 v[98:101], v[202:205], v[156:159], v[98:101]
	v_mfma_f32_16x16x32_bf16 v[130:133], v[202:205], v[148:151], v[102:105]
	s_barrier
	s_nop 2
	ds_read_b128 v[102:105], v166
	ds_read_b128 v[164:167], v167
	ds_read_b128 v[206:209], v168
	ds_read_b128 v[212:215], v169
	s_barrier
	s_waitcnt lgkmcnt(0)
	s_waitcnt lgkmcnt(1)
	v_mfma_f32_16x16x32_bf16 v[90:93], v[160:163], v[206:209], v[90:93]
	v_mfma_f32_16x16x32_bf16 v[94:97], v[160:163], v[102:105], v[94:97]
	s_waitcnt lgkmcnt(0)
	v_mfma_f32_16x16x32_bf16 v[90:93], v[178:181], v[212:215], v[90:93]
	v_mfma_f32_16x16x32_bf16 v[86:89], v[182:185], v[102:105], v[86:89]
	v_mfma_f32_16x16x32_bf16 v[82:85], v[182:185], v[206:209], v[82:85]
	v_mfma_f32_16x16x32_bf16 v[78:81], v[190:193], v[102:105], v[78:81]
	v_mfma_f32_16x16x32_bf16 v[74:77], v[190:193], v[206:209], v[74:77]
	v_mfma_f32_16x16x32_bf16 v[70:73], v[198:201], v[102:105], v[70:73]
	v_mfma_f32_16x16x32_bf16 v[66:69], v[198:201], v[206:209], v[66:69]
	v_mfma_f32_16x16x32_bf16 v[224:227], v[178:181], v[164:167], v[94:97]
	v_mfma_f32_16x16x32_bf16 v[160:163], v[186:189], v[164:167], v[86:89]
	v_mfma_f32_16x16x32_bf16 v[178:181], v[186:189], v[212:215], v[82:85]
	v_mfma_f32_16x16x32_bf16 v[182:185], v[194:197], v[164:167], v[78:81]
	v_mfma_f32_16x16x32_bf16 v[186:189], v[194:197], v[212:215], v[74:77]
	v_mfma_f32_16x16x32_bf16 v[190:193], v[202:205], v[164:167], v[70:73]
	v_mfma_f32_16x16x32_bf16 v[194:197], v[202:205], v[212:215], v[66:69]
	s_barrier
	s_nop 0
	ds_read_b128 v[66:69], v140 offset:16384
	ds_read_b128 v[70:73], v140 offset:17408
	ds_read_b128 v[74:77], v143 offset:16384
	ds_read_b128 v[78:81], v143 offset:17408
	ds_read_b128 v[82:85], v142 offset:16384
	ds_read_b128 v[86:89], v142 offset:17408
	ds_read_b128 v[94:97], v141 offset:16384
	ds_read_b128 v[198:201], v141 offset:17408
	s_waitcnt vmcnt(4)
	s_barrier
	s_waitcnt lgkmcnt(0)
	s_waitcnt lgkmcnt(7)
	v_mfma_f32_16x16x32_bf16 v[62:65], v[66:69], v[144:147], v[62:65]
	v_mfma_f32_16x16x32_bf16 v[58:61], v[66:69], v[152:155], v[58:61]
	s_waitcnt lgkmcnt(5)
	v_mfma_f32_16x16x32_bf16 v[54:57], v[74:77], v[144:147], v[54:57]
	v_mfma_f32_16x16x32_bf16 v[50:53], v[74:77], v[152:155], v[50:53]
	s_waitcnt lgkmcnt(3)
	v_mfma_f32_16x16x32_bf16 v[46:49], v[82:85], v[144:147], v[46:49]
	v_mfma_f32_16x16x32_bf16 v[42:45], v[82:85], v[152:155], v[42:45]
	s_waitcnt lgkmcnt(1)
	v_mfma_f32_16x16x32_bf16 v[38:41], v[94:97], v[144:147], v[38:41]
	v_mfma_f32_16x16x32_bf16 v[34:37], v[94:97], v[152:155], v[34:37]
	v_mfma_f32_16x16x32_bf16 v[62:65], v[70:73], v[148:151], v[62:65]
	v_mfma_f32_16x16x32_bf16 v[58:61], v[70:73], v[156:159], v[58:61]
	v_mfma_f32_16x16x32_bf16 v[54:57], v[78:81], v[148:151], v[54:57]
	v_mfma_f32_16x16x32_bf16 v[50:53], v[78:81], v[156:159], v[50:53]
	v_mfma_f32_16x16x32_bf16 v[46:49], v[86:89], v[148:151], v[46:49]
	v_mfma_f32_16x16x32_bf16 v[42:45], v[86:89], v[156:159], v[42:45]
	s_waitcnt lgkmcnt(0)
	v_mfma_f32_16x16x32_bf16 v[38:41], v[198:201], v[148:151], v[38:41]
	v_mfma_f32_16x16x32_bf16 v[34:37], v[198:201], v[156:159], v[34:37]
	v_mfma_f32_16x16x32_bf16 v[30:33], v[66:69], v[102:105], v[30:33]
	v_mfma_f32_16x16x32_bf16 v[26:29], v[66:69], v[206:209], v[26:29]
	v_mfma_f32_16x16x32_bf16 v[22:25], v[74:77], v[102:105], v[22:25]
	v_mfma_f32_16x16x32_bf16 v[18:21], v[74:77], v[206:209], v[18:21]
	v_mfma_f32_16x16x32_bf16 v[14:17], v[82:85], v[102:105], v[14:17]
	v_mfma_f32_16x16x32_bf16 v[10:13], v[82:85], v[206:209], v[10:13]
	v_mfma_f32_16x16x32_bf16 v[6:9], v[94:97], v[102:105], v[6:9]
	v_mfma_f32_16x16x32_bf16 v[2:5], v[94:97], v[206:209], v[2:5]
	v_mfma_f32_16x16x32_bf16 v[144:147], v[70:73], v[164:167], v[30:33]
	v_mfma_f32_16x16x32_bf16 v[148:151], v[70:73], v[212:215], v[26:29]
	v_mfma_f32_16x16x32_bf16 v[152:155], v[78:81], v[164:167], v[22:25]
	v_mfma_f32_16x16x32_bf16 v[156:159], v[78:81], v[212:215], v[18:21]
	v_mfma_f32_16x16x32_bf16 v[202:205], v[86:89], v[164:167], v[14:17]
	v_mfma_f32_16x16x32_bf16 v[228:231], v[86:89], v[212:215], v[10:13]
	v_mfma_f32_16x16x32_bf16 v[164:167], v[198:201], v[164:167], v[6:9]
	v_mfma_f32_16x16x32_bf16 v[198:201], v[198:201], v[212:215], v[2:5]
	s_barrier
	s_nop 0
	ds_read_b128 v[2:5], v170
	ds_read_b128 v[6:9], v171
	ds_read_b128 v[168:171], v172
	ds_read_b128 v[206:209], v173
	ds_read_b128 v[10:13], v140 offset:32768
	ds_read_b128 v[14:17], v140 offset:33792
	ds_read_b128 v[18:21], v143 offset:32768
	ds_read_b128 v[22:25], v143 offset:33792
	ds_read_b128 v[26:29], v142 offset:32768
	ds_read_b128 v[30:33], v142 offset:33792
	ds_read_b128 v[212:215], v141 offset:32768
	ds_read_b128 v[232:235], v141 offset:33792
	s_waitcnt vmcnt(2)
	s_barrier
	s_waitcnt lgkmcnt(0)
	s_waitcnt lgkmcnt(7)
	v_mfma_f32_16x16x32_bf16 v[66:69], v[10:13], v[2:5], v[126:129]
	s_waitcnt lgkmcnt(6)
	v_mfma_f32_16x16x32_bf16 v[94:97], v[14:17], v[6:9], v[66:69]
	v_mfma_f32_16x16x32_bf16 v[66:69], v[10:13], v[168:171], v[122:125]
	v_mfma_f32_16x16x32_bf16 v[102:105], v[14:17], v[206:209], v[66:69]
	s_waitcnt lgkmcnt(5)
	v_mfma_f32_16x16x32_bf16 v[66:69], v[18:21], v[2:5], v[118:121]
	s_waitcnt lgkmcnt(4)
	v_mfma_f32_16x16x32_bf16 v[82:85], v[22:25], v[6:9], v[66:69]
	v_mfma_f32_16x16x32_bf16 v[66:69], v[18:21], v[168:171], v[114:117]
	v_mfma_f32_16x16x32_bf16 v[86:89], v[22:25], v[206:209], v[66:69]
	s_waitcnt lgkmcnt(3)
	v_mfma_f32_16x16x32_bf16 v[66:69], v[26:29], v[2:5], v[110:113]
	s_waitcnt lgkmcnt(2)
	v_mfma_f32_16x16x32_bf16 v[74:77], v[30:33], v[6:9], v[66:69]
	v_mfma_f32_16x16x32_bf16 v[66:69], v[26:29], v[168:171], v[106:109]
	v_mfma_f32_16x16x32_bf16 v[78:81], v[30:33], v[206:209], v[66:69]
	s_waitcnt lgkmcnt(1)
	v_mfma_f32_16x16x32_bf16 v[66:69], v[212:215], v[2:5], v[130:133]
	v_mfma_f32_16x16x32_bf16 v[70:73], v[212:215], v[168:171], v[98:101]
	s_waitcnt lgkmcnt(0)
	v_mfma_f32_16x16x32_bf16 v[66:69], v[232:235], v[6:9], v[66:69]
	v_mfma_f32_16x16x32_bf16 v[70:73], v[232:235], v[206:209], v[70:73]
	s_barrier
	ds_read_b128 v[130:133], v174
	ds_read_b128 v[172:175], v175
	ds_read_b128 v[236:239], v176
	ds_read_b128 v[240:243], v177
	s_waitcnt vmcnt(0)
	s_barrier
	s_waitcnt lgkmcnt(0)
	s_waitcnt lgkmcnt(3)
	v_mfma_f32_16x16x32_bf16 v[98:101], v[10:13], v[130:133], v[224:227]
	s_waitcnt lgkmcnt(1)
	v_mfma_f32_16x16x32_bf16 v[10:13], v[10:13], v[236:239], v[90:93]
	s_waitcnt lgkmcnt(0)
	v_mfma_f32_16x16x32_bf16 v[126:129], v[14:17], v[240:243], v[10:13]
	v_mfma_f32_16x16x32_bf16 v[10:13], v[18:21], v[130:133], v[160:163]
	v_mfma_f32_16x16x32_bf16 v[114:117], v[22:25], v[172:175], v[10:13]
	v_mfma_f32_16x16x32_bf16 v[10:13], v[18:21], v[236:239], v[178:181]
	v_mfma_f32_16x16x32_bf16 v[118:121], v[22:25], v[240:243], v[10:13]
	v_mfma_f32_16x16x32_bf16 v[10:13], v[26:29], v[130:133], v[182:185]
	v_mfma_f32_16x16x32_bf16 v[106:109], v[30:33], v[172:175], v[10:13]
	v_mfma_f32_16x16x32_bf16 v[10:13], v[26:29], v[236:239], v[186:189]
	v_mfma_f32_16x16x32_bf16 v[110:113], v[30:33], v[240:243], v[10:13]
	v_mfma_f32_16x16x32_bf16 v[10:13], v[212:215], v[130:133], v[190:193]
	v_mfma_f32_16x16x32_bf16 v[90:93], v[232:235], v[172:175], v[10:13]
	v_mfma_f32_16x16x32_bf16 v[10:13], v[212:215], v[236:239], v[194:197]
	v_mfma_f32_16x16x32_bf16 v[122:125], v[14:17], v[172:175], v[98:101]
	v_mfma_f32_16x16x32_bf16 v[98:101], v[232:235], v[240:243], v[10:13]
	s_barrier
	ds_read_b128 v[160:163], v140 offset:49152
	ds_read_b128 v[176:179], v140 offset:50176
	ds_read_b128 v[180:183], v143 offset:49152
	ds_read_b128 v[184:187], v143 offset:50176
	ds_read_b128 v[188:191], v142 offset:49152
	ds_read_b128 v[192:195], v142 offset:50176
	ds_read_b128 v[212:215], v141 offset:49152
	ds_read_b128 v[138:141], v141 offset:50176
	s_barrier
	s_waitcnt lgkmcnt(0)
	s_waitcnt lgkmcnt(7)
	v_mfma_f32_16x16x32_bf16 v[10:13], v[160:163], v[2:5], v[62:65]
	s_waitcnt lgkmcnt(6)
	v_mfma_f32_16x16x32_bf16 v[26:29], v[176:179], v[6:9], v[10:13]
	v_mfma_f32_16x16x32_bf16 v[10:13], v[160:163], v[168:171], v[58:61]
	v_mfma_f32_16x16x32_bf16 v[30:33], v[176:179], v[206:209], v[10:13]
	s_waitcnt lgkmcnt(5)
	v_mfma_f32_16x16x32_bf16 v[10:13], v[180:183], v[2:5], v[54:57]
	s_waitcnt lgkmcnt(4)
	v_mfma_f32_16x16x32_bf16 v[18:21], v[184:187], v[6:9], v[10:13]
	v_mfma_f32_16x16x32_bf16 v[10:13], v[180:183], v[168:171], v[50:53]
	v_mfma_f32_16x16x32_bf16 v[22:25], v[184:187], v[206:209], v[10:13]
	s_waitcnt lgkmcnt(3)
	v_mfma_f32_16x16x32_bf16 v[10:13], v[188:191], v[2:5], v[46:49]
	s_waitcnt lgkmcnt(1)
	v_mfma_f32_16x16x32_bf16 v[2:5], v[212:215], v[2:5], v[38:41]
	v_mfma_f32_16x16x32_bf16 v[10:13], v[192:195], v[6:9], v[10:13]
	v_mfma_f32_16x16x32_bf16 v[14:17], v[188:191], v[168:171], v[42:45]
	s_waitcnt lgkmcnt(0)
	v_mfma_f32_16x16x32_bf16 v[2:5], v[138:141], v[6:9], v[2:5]
	v_mfma_f32_16x16x32_bf16 v[6:9], v[212:215], v[168:171], v[34:37]
	v_mfma_f32_16x16x32_bf16 v[14:17], v[192:195], v[206:209], v[14:17]
	v_mfma_f32_16x16x32_bf16 v[6:9], v[138:141], v[206:209], v[6:9]
	v_mfma_f32_16x16x32_bf16 v[34:37], v[160:163], v[130:133], v[144:147]
	v_mfma_f32_16x16x32_bf16 v[58:61], v[176:179], v[172:175], v[34:37]
	v_mfma_f32_16x16x32_bf16 v[34:37], v[160:163], v[236:239], v[148:151]
	v_mfma_f32_16x16x32_bf16 v[62:65], v[176:179], v[240:243], v[34:37]
	v_mfma_f32_16x16x32_bf16 v[34:37], v[180:183], v[130:133], v[152:155]
	v_mfma_f32_16x16x32_bf16 v[50:53], v[184:187], v[172:175], v[34:37]
	v_mfma_f32_16x16x32_bf16 v[34:37], v[180:183], v[236:239], v[156:159]
	v_mfma_f32_16x16x32_bf16 v[54:57], v[184:187], v[240:243], v[34:37]
	v_mfma_f32_16x16x32_bf16 v[34:37], v[188:191], v[130:133], v[202:205]
	v_mfma_f32_16x16x32_bf16 v[42:45], v[192:195], v[172:175], v[34:37]
	v_mfma_f32_16x16x32_bf16 v[34:37], v[188:191], v[236:239], v[228:231]
	v_mfma_f32_16x16x32_bf16 v[46:49], v[192:195], v[240:243], v[34:37]
	v_mfma_f32_16x16x32_bf16 v[34:37], v[212:215], v[130:133], v[164:167]
	v_mfma_f32_16x16x32_bf16 v[38:41], v[212:215], v[236:239], v[198:201]
	v_mfma_f32_16x16x32_bf16 v[34:37], v[138:141], v[172:175], v[34:37]
	v_mfma_f32_16x16x32_bf16 v[38:41], v[138:141], v[240:243], v[38:41]
	s_movk_i32 s1, 0x100
	v_cmp_gt_u32_e32 vcc, s1, v1
	s_barrier
	s_and_saveexec_b64 s[6:7], vcc
	s_cbranch_execz .LBB0_712
	s_barrier

.LBB0_847:
	v_or_b32_e32 v160, 0x10000, v156
	v_or_b32_e32 v162, 0x10000, v158
	v_or_b32_e32 v161, 0x10000, v157
	ds_read_b128 v[170:173], v160
	ds_read_b128 v[174:177], v161
	v_or_b32_e32 v163, 0x10000, v159
	ds_read_b128 v[178:181], v162
	ds_read_b128 v[182:185], v163
	s_add_u32 s36, s19, s16
	s_addc_u32 s37, s34, s17
	s_add_u32 s36, s36, 0x80
	v_add_u32_e32 v164, 0xc000, v137
	s_addc_u32 s37, s37, 0
	v_readfirstlane_b32 s38, v164
	ds_read_b128 v[186:189], v140
	ds_read_b128 v[190:193], v140 offset:1024
	ds_read_b128 v[194:197], v143
	ds_read_b128 v[198:201], v143 offset:1024
	ds_read_b128 v[202:205], v142
	ds_read_b128 v[206:209], v142 offset:1024
	ds_read_b128 v[212:215], v141
	ds_read_b128 v[224:227], v141 offset:1024
	s_mov_b32 m0, s38
	v_lshl_add_u64 v[166:167], s[36:37], 0, v[132:133]
	v_add_u32_e32 v165, 0xe000, v137
	global_load_lds_dwordx4 v[166:167], off
	v_lshl_add_u64 v[166:167], s[36:37], 0, v[130:131]
	v_readfirstlane_b32 s36, v165
	s_mov_b32 m0, s36
	s_nop 0
	global_load_lds_dwordx4 v[166:167], off
	s_waitcnt lgkmcnt(8)
	s_barrier
	s_waitcnt lgkmcnt(0)
	s_waitcnt lgkmcnt(0)
	v_mfma_f32_16x16x32_bf16 v[126:129], v[186:189], v[170:173], v[126:129]
	v_mfma_f32_16x16x32_bf16 v[122:125], v[186:189], v[178:181], v[122:125]
	v_mfma_f32_16x16x32_bf16 v[118:121], v[194:197], v[170:173], v[118:121]
	v_mfma_f32_16x16x32_bf16 v[114:117], v[194:197], v[178:181], v[114:117]
	v_mfma_f32_16x16x32_bf16 v[110:113], v[202:205], v[170:173], v[110:113]
	v_mfma_f32_16x16x32_bf16 v[106:109], v[202:205], v[178:181], v[106:109]
	v_mfma_f32_16x16x32_bf16 v[102:105], v[212:215], v[170:173], v[102:105]
	v_mfma_f32_16x16x32_bf16 v[98:101], v[212:215], v[178:181], v[98:101]
	v_mfma_f32_16x16x32_bf16 v[126:129], v[190:193], v[174:177], v[126:129]
	v_mfma_f32_16x16x32_bf16 v[122:125], v[190:193], v[182:185], v[122:125]
	v_mfma_f32_16x16x32_bf16 v[118:121], v[198:201], v[174:177], v[118:121]
	v_mfma_f32_16x16x32_bf16 v[114:117], v[198:201], v[182:185], v[114:117]
	v_mfma_f32_16x16x32_bf16 v[110:113], v[206:209], v[174:177], v[110:113]
	v_mfma_f32_16x16x32_bf16 v[106:109], v[206:209], v[182:185], v[106:109]
	v_mfma_f32_16x16x32_bf16 v[102:105], v[224:227], v[174:177], v[102:105]
	v_mfma_f32_16x16x32_bf16 v[98:101], v[224:227], v[182:185], v[98:101]
	s_barrier
	s_add_u32 s38, s8, s16
	s_addc_u32 s39, s9, s17
	s_add_u32 s36, s38, 0x100
	v_or_b32_e32 v166, 0x14000, v156
	v_or_b32_e32 v168, 0x14000, v158
	s_addc_u32 s37, s39, 0
	v_readfirstlane_b32 s40, v144
	v_or_b32_e32 v167, 0x14000, v157
	ds_read_b128 v[228:231], v166
	ds_read_b128 v[232:235], v167
	v_or_b32_e32 v169, 0x14000, v159
	ds_read_b128 v[236:239], v168
	ds_read_b128 v[240:243], v169
	s_mov_b32 m0, s40
	v_lshl_add_u64 v[216:217], s[36:37], 0, v[132:133]
	global_load_lds_dwordx4 v[216:217], off
	v_lshl_add_u64 v[216:217], s[36:37], 0, v[130:131]
	v_readfirstlane_b32 s36, v145
	s_mov_b32 m0, s36
	s_nop 0
	global_load_lds_dwordx4 v[216:217], off
	s_barrier
	s_waitcnt lgkmcnt(0)
	s_waitcnt lgkmcnt(0)
	v_mfma_f32_16x16x32_bf16 v[94:97], v[186:189], v[228:231], v[94:97]
	v_mfma_f32_16x16x32_bf16 v[90:93], v[186:189], v[236:239], v[90:93]
	v_mfma_f32_16x16x32_bf16 v[86:89], v[194:197], v[228:231], v[86:89]
	v_mfma_f32_16x16x32_bf16 v[82:85], v[194:197], v[236:239], v[82:85]
	v_mfma_f32_16x16x32_bf16 v[78:81], v[202:205], v[228:231], v[78:81]
	v_mfma_f32_16x16x32_bf16 v[74:77], v[202:205], v[236:239], v[74:77]
	v_mfma_f32_16x16x32_bf16 v[70:73], v[212:215], v[228:231], v[70:73]
	v_mfma_f32_16x16x32_bf16 v[66:69], v[212:215], v[236:239], v[66:69]
	v_mfma_f32_16x16x32_bf16 v[94:97], v[190:193], v[232:235], v[94:97]
	v_mfma_f32_16x16x32_bf16 v[90:93], v[190:193], v[240:243], v[90:93]
	v_mfma_f32_16x16x32_bf16 v[86:89], v[198:201], v[232:235], v[86:89]
	v_mfma_f32_16x16x32_bf16 v[82:85], v[198:201], v[240:243], v[82:85]
	v_mfma_f32_16x16x32_bf16 v[78:81], v[206:209], v[232:235], v[78:81]
	v_mfma_f32_16x16x32_bf16 v[74:77], v[206:209], v[240:243], v[74:77]
	v_mfma_f32_16x16x32_bf16 v[70:73], v[224:227], v[232:235], v[70:73]
	v_mfma_f32_16x16x32_bf16 v[66:69], v[224:227], v[240:243], v[66:69]
	s_add_u32 s40, s10, s16
	s_addc_u32 s41, s11, s17
	s_add_u32 s36, s40, 0x100
	s_addc_u32 s37, s41, 0
	v_readfirstlane_b32 s42, v137
	s_barrier
	ds_read_b128 v[186:189], v140 offset:16384
	ds_read_b128 v[190:193], v140 offset:17408
	ds_read_b128 v[194:197], v143 offset:16384
	ds_read_b128 v[198:201], v143 offset:17408
	ds_read_b128 v[202:205], v142 offset:16384
	ds_read_b128 v[206:209], v142 offset:17408
	ds_read_b128 v[212:215], v141 offset:16384
	ds_read_b128 v[224:227], v141 offset:17408
	s_mov_b32 m0, s42
	v_lshl_add_u64 v[216:217], s[36:37], 0, v[132:133]
	global_load_lds_dwordx4 v[216:217], off
	v_lshl_add_u64 v[216:217], s[36:37], 0, v[130:131]
	v_readfirstlane_b32 s36, v138
	s_mov_b32 m0, s36
	s_nop 0
	global_load_lds_dwordx4 v[216:217], off
	s_barrier
	s_waitcnt lgkmcnt(0)
	s_waitcnt lgkmcnt(0)
	v_mfma_f32_16x16x32_bf16 v[62:65], v[186:189], v[170:173], v[62:65]
	v_mfma_f32_16x16x32_bf16 v[58:61], v[186:189], v[178:181], v[58:61]
	v_mfma_f32_16x16x32_bf16 v[54:57], v[194:197], v[170:173], v[54:57]
	v_mfma_f32_16x16x32_bf16 v[50:53], v[194:197], v[178:181], v[50:53]
	v_mfma_f32_16x16x32_bf16 v[46:49], v[202:205], v[170:173], v[46:49]
	v_mfma_f32_16x16x32_bf16 v[42:45], v[202:205], v[178:181], v[42:45]
	v_mfma_f32_16x16x32_bf16 v[38:41], v[212:215], v[170:173], v[38:41]
	v_mfma_f32_16x16x32_bf16 v[34:37], v[212:215], v[178:181], v[34:37]
	v_mfma_f32_16x16x32_bf16 v[62:65], v[190:193], v[174:177], v[62:65]
	v_mfma_f32_16x16x32_bf16 v[58:61], v[190:193], v[182:185], v[58:61]
	v_mfma_f32_16x16x32_bf16 v[54:57], v[198:201], v[174:177], v[54:57]
	v_mfma_f32_16x16x32_bf16 v[50:53], v[198:201], v[182:185], v[50:53]
	v_mfma_f32_16x16x32_bf16 v[46:49], v[206:209], v[174:177], v[46:49]
	v_mfma_f32_16x16x32_bf16 v[42:45], v[206:209], v[182:185], v[42:45]
	v_mfma_f32_16x16x32_bf16 v[38:41], v[224:227], v[174:177], v[38:41]
	v_mfma_f32_16x16x32_bf16 v[34:37], v[224:227], v[182:185], v[34:37]
	s_barrier
	s_add_u32 s42, s12, s16
	s_addc_u32 s43, s13, s17
	s_add_u32 s36, s42, 0x100
	s_addc_u32 s37, s43, 0
	v_readfirstlane_b32 s44, v146
	s_mov_b32 m0, s44
	v_lshl_add_u64 v[170:171], s[36:37], 0, v[132:133]
	global_load_lds_dwordx4 v[170:171], off
	v_lshl_add_u64 v[170:171], s[36:37], 0, v[130:131]
	v_readfirstlane_b32 s36, v147
	s_mov_b32 m0, s36
	s_nop 0
	global_load_lds_dwordx4 v[170:171], off
	s_waitcnt vmcnt(6)
	s_barrier
	v_mfma_f32_16x16x32_bf16 v[30:33], v[186:189], v[228:231], v[30:33]
	v_mfma_f32_16x16x32_bf16 v[26:29], v[186:189], v[236:239], v[26:29]
	v_mfma_f32_16x16x32_bf16 v[22:25], v[194:197], v[228:231], v[22:25]
	v_mfma_f32_16x16x32_bf16 v[18:21], v[194:197], v[236:239], v[18:21]
	v_mfma_f32_16x16x32_bf16 v[14:17], v[202:205], v[228:231], v[14:17]
	v_mfma_f32_16x16x32_bf16 v[10:13], v[202:205], v[236:239], v[10:13]
	v_mfma_f32_16x16x32_bf16 v[6:9], v[212:215], v[228:231], v[6:9]
	v_mfma_f32_16x16x32_bf16 v[2:5], v[212:215], v[236:239], v[2:5]
	v_mfma_f32_16x16x32_bf16 v[30:33], v[190:193], v[232:235], v[30:33]
	v_mfma_f32_16x16x32_bf16 v[26:29], v[190:193], v[240:243], v[26:29]
	v_mfma_f32_16x16x32_bf16 v[22:25], v[198:201], v[232:235], v[22:25]
	v_mfma_f32_16x16x32_bf16 v[18:21], v[198:201], v[240:243], v[18:21]
	v_mfma_f32_16x16x32_bf16 v[14:17], v[206:209], v[232:235], v[14:17]
	v_mfma_f32_16x16x32_bf16 v[10:13], v[206:209], v[240:243], v[10:13]
	v_mfma_f32_16x16x32_bf16 v[6:9], v[224:227], v[232:235], v[6:9]
	v_mfma_f32_16x16x32_bf16 v[2:5], v[224:227], v[240:243], v[2:5]
	v_or_b32_e32 v170, 0x18000, v156
	v_or_b32_e32 v172, 0x18000, v158
	s_barrier
	v_or_b32_e32 v171, 0x18000, v157
	ds_read_b128 v[178:181], v170
	ds_read_b128 v[182:185], v171
	v_or_b32_e32 v173, 0x18000, v159
	ds_read_b128 v[186:189], v172
	ds_read_b128 v[190:193], v173
	s_add_u32 s36, s5, s16
	s_addc_u32 s37, s18, s17
	v_readfirstlane_b32 s44, v148
	ds_read_b128 v[194:197], v140 offset:32768
	ds_read_b128 v[198:201], v140 offset:33792
	ds_read_b128 v[202:205], v143 offset:32768
	ds_read_b128 v[206:209], v143 offset:33792
	ds_read_b128 v[212:215], v142 offset:32768
	ds_read_b128 v[224:227], v142 offset:33792
	ds_read_b128 v[228:231], v141 offset:32768
	ds_read_b128 v[232:235], v141 offset:33792
	s_mov_b32 m0, s44
	v_lshl_add_u64 v[174:175], s[36:37], 0, v[132:133]
	global_load_lds_dwordx4 v[174:175], off
	v_lshl_add_u64 v[174:175], s[36:37], 0, v[130:131]
	v_readfirstlane_b32 s36, v149
	s_mov_b32 m0, s36
	s_nop 0
	global_load_lds_dwordx4 v[174:175], off
	s_waitcnt lgkmcnt(8)
	s_barrier
	s_waitcnt lgkmcnt(0)
	s_waitcnt lgkmcnt(0)
	v_mfma_f32_16x16x32_bf16 v[126:129], v[194:197], v[178:181], v[126:129]
	v_mfma_f32_16x16x32_bf16 v[122:125], v[194:197], v[186:189], v[122:125]
	v_mfma_f32_16x16x32_bf16 v[118:121], v[202:205], v[178:181], v[118:121]
	v_mfma_f32_16x16x32_bf16 v[114:117], v[202:205], v[186:189], v[114:117]
	v_mfma_f32_16x16x32_bf16 v[110:113], v[212:215], v[178:181], v[110:113]
	v_mfma_f32_16x16x32_bf16 v[106:109], v[212:215], v[186:189], v[106:109]
	v_mfma_f32_16x16x32_bf16 v[102:105], v[228:231], v[178:181], v[102:105]
	v_mfma_f32_16x16x32_bf16 v[98:101], v[228:231], v[186:189], v[98:101]
	v_mfma_f32_16x16x32_bf16 v[126:129], v[198:201], v[182:185], v[126:129]
	v_mfma_f32_16x16x32_bf16 v[122:125], v[198:201], v[190:193], v[122:125]
	v_mfma_f32_16x16x32_bf16 v[118:121], v[206:209], v[182:185], v[118:121]
	v_mfma_f32_16x16x32_bf16 v[114:117], v[206:209], v[190:193], v[114:117]
	v_mfma_f32_16x16x32_bf16 v[110:113], v[224:227], v[182:185], v[110:113]
	v_mfma_f32_16x16x32_bf16 v[106:109], v[224:227], v[190:193], v[106:109]
	v_mfma_f32_16x16x32_bf16 v[102:105], v[232:235], v[182:185], v[102:105]
	v_mfma_f32_16x16x32_bf16 v[98:101], v[232:235], v[190:193], v[98:101]
	s_barrier
	s_add_u32 s36, s38, 0x180
	v_or_b32_e32 v174, 0x1c000, v156
	v_or_b32_e32 v176, 0x1c000, v158
	s_addc_u32 s37, s39, 0
	v_readfirstlane_b32 s38, v150
	v_or_b32_e32 v175, 0x1c000, v157
	ds_read_b128 v[236:239], v174
	ds_read_b128 v[240:243], v175
	v_or_b32_e32 v177, 0x1c000, v159
	ds_read_b128 v[244:247], v176
	ds_read_b128 v[248:251], v177
	s_mov_b32 m0, s38
	v_lshl_add_u64 v[216:217], s[36:37], 0, v[132:133]
	global_load_lds_dwordx4 v[216:217], off
	v_lshl_add_u64 v[216:217], s[36:37], 0, v[130:131]
	v_readfirstlane_b32 s36, v151
	s_mov_b32 m0, s36
	s_nop 0
	global_load_lds_dwordx4 v[216:217], off
	s_barrier
	s_waitcnt lgkmcnt(0)
	s_waitcnt lgkmcnt(0)
	v_mfma_f32_16x16x32_bf16 v[94:97], v[194:197], v[236:239], v[94:97]
	v_mfma_f32_16x16x32_bf16 v[90:93], v[194:197], v[244:247], v[90:93]
	v_mfma_f32_16x16x32_bf16 v[86:89], v[202:205], v[236:239], v[86:89]
	v_mfma_f32_16x16x32_bf16 v[82:85], v[202:205], v[244:247], v[82:85]
	v_mfma_f32_16x16x32_bf16 v[78:81], v[212:215], v[236:239], v[78:81]
	v_mfma_f32_16x16x32_bf16 v[74:77], v[212:215], v[244:247], v[74:77]
	v_mfma_f32_16x16x32_bf16 v[70:73], v[228:231], v[236:239], v[70:73]
	v_mfma_f32_16x16x32_bf16 v[66:69], v[228:231], v[244:247], v[66:69]
	v_mfma_f32_16x16x32_bf16 v[94:97], v[198:201], v[240:243], v[94:97]
	v_mfma_f32_16x16x32_bf16 v[90:93], v[198:201], v[248:251], v[90:93]
	v_mfma_f32_16x16x32_bf16 v[86:89], v[206:209], v[240:243], v[86:89]
	v_mfma_f32_16x16x32_bf16 v[82:85], v[206:209], v[248:251], v[82:85]
	v_mfma_f32_16x16x32_bf16 v[78:81], v[224:227], v[240:243], v[78:81]
	v_mfma_f32_16x16x32_bf16 v[74:77], v[224:227], v[248:251], v[74:77]
	v_mfma_f32_16x16x32_bf16 v[70:73], v[232:235], v[240:243], v[70:73]
	v_mfma_f32_16x16x32_bf16 v[66:69], v[232:235], v[248:251], v[66:69]
	s_add_u32 s36, s40, 0x180
	s_addc_u32 s37, s41, 0
	v_readfirstlane_b32 s38, v152
	s_barrier
	ds_read_b128 v[194:197], v140 offset:49152
	ds_read_b128 v[198:201], v140 offset:50176
	ds_read_b128 v[202:205], v143 offset:49152
	ds_read_b128 v[206:209], v143 offset:50176
	ds_read_b128 v[212:215], v142 offset:49152
	ds_read_b128 v[224:227], v142 offset:50176
	ds_read_b128 v[228:231], v141 offset:49152
	ds_read_b128 v[232:235], v141 offset:50176
	s_mov_b32 m0, s38
	v_lshl_add_u64 v[216:217], s[36:37], 0, v[132:133]
	global_load_lds_dwordx4 v[216:217], off
	v_lshl_add_u64 v[216:217], s[36:37], 0, v[130:131]
	v_readfirstlane_b32 s36, v153
	s_mov_b32 m0, s36
	s_nop 0
	global_load_lds_dwordx4 v[216:217], off
	s_barrier
	s_waitcnt lgkmcnt(0)
	s_waitcnt lgkmcnt(0)
	v_mfma_f32_16x16x32_bf16 v[62:65], v[194:197], v[178:181], v[62:65]
	v_mfma_f32_16x16x32_bf16 v[58:61], v[194:197], v[186:189], v[58:61]
	v_mfma_f32_16x16x32_bf16 v[54:57], v[202:205], v[178:181], v[54:57]
	v_mfma_f32_16x16x32_bf16 v[50:53], v[202:205], v[186:189], v[50:53]
	v_mfma_f32_16x16x32_bf16 v[46:49], v[212:215], v[178:181], v[46:49]
	v_mfma_f32_16x16x32_bf16 v[42:45], v[212:215], v[186:189], v[42:45]
	v_mfma_f32_16x16x32_bf16 v[38:41], v[228:231], v[178:181], v[38:41]
	v_mfma_f32_16x16x32_bf16 v[34:37], v[228:231], v[186:189], v[34:37]
	v_mfma_f32_16x16x32_bf16 v[62:65], v[198:201], v[182:185], v[62:65]
	v_mfma_f32_16x16x32_bf16 v[58:61], v[198:201], v[190:193], v[58:61]
	v_mfma_f32_16x16x32_bf16 v[54:57], v[206:209], v[182:185], v[54:57]
	v_mfma_f32_16x16x32_bf16 v[50:53], v[206:209], v[190:193], v[50:53]
	v_mfma_f32_16x16x32_bf16 v[46:49], v[224:227], v[182:185], v[46:49]
	v_mfma_f32_16x16x32_bf16 v[42:45], v[224:227], v[190:193], v[42:45]
	v_mfma_f32_16x16x32_bf16 v[38:41], v[232:235], v[182:185], v[38:41]
	v_mfma_f32_16x16x32_bf16 v[34:37], v[232:235], v[190:193], v[34:37]
	s_barrier
	s_add_u32 s36, s42, 0x180
	s_addc_u32 s37, s43, 0
	v_readfirstlane_b32 s38, v154
	s_mov_b32 m0, s38
	v_lshl_add_u64 v[178:179], s[36:37], 0, v[132:133]
	global_load_lds_dwordx4 v[178:179], off
	v_lshl_add_u64 v[178:179], s[36:37], 0, v[130:131]
	v_readfirstlane_b32 s36, v155
	s_mov_b32 m0, s36
	s_nop 0
	global_load_lds_dwordx4 v[178:179], off
	s_waitcnt vmcnt(6)
	s_barrier
	v_mfma_f32_16x16x32_bf16 v[30:33], v[194:197], v[236:239], v[30:33]
	v_mfma_f32_16x16x32_bf16 v[26:29], v[194:197], v[244:247], v[26:29]
	v_mfma_f32_16x16x32_bf16 v[22:25], v[202:205], v[236:239], v[22:25]
	v_mfma_f32_16x16x32_bf16 v[18:21], v[202:205], v[244:247], v[18:21]
	v_mfma_f32_16x16x32_bf16 v[14:17], v[212:215], v[236:239], v[14:17]
	v_mfma_f32_16x16x32_bf16 v[10:13], v[212:215], v[244:247], v[10:13]
	v_mfma_f32_16x16x32_bf16 v[6:9], v[228:231], v[236:239], v[6:9]
	v_mfma_f32_16x16x32_bf16 v[2:5], v[228:231], v[244:247], v[2:5]
	v_mfma_f32_16x16x32_bf16 v[30:33], v[198:201], v[240:243], v[30:33]
	v_mfma_f32_16x16x32_bf16 v[26:29], v[198:201], v[248:251], v[26:29]
	v_mfma_f32_16x16x32_bf16 v[22:25], v[206:209], v[240:243], v[22:25]
	v_mfma_f32_16x16x32_bf16 v[18:21], v[206:209], v[248:251], v[18:21]
	v_mfma_f32_16x16x32_bf16 v[14:17], v[224:227], v[240:243], v[14:17]
	v_mfma_f32_16x16x32_bf16 v[10:13], v[224:227], v[248:251], v[10:13]
	v_mfma_f32_16x16x32_bf16 v[6:9], v[232:235], v[240:243], v[6:9]
	v_mfma_f32_16x16x32_bf16 v[2:5], v[232:235], v[248:251], v[2:5]
	s_add_i32 s35, s35, 2
	s_add_u32 s16, s16, 0x100
	s_addc_u32 s17, s17, 0
	s_cmp_lt_u32 s35, 12
	s_barrier
	s_cbranch_scc1 .LBB0_847
	s_add_u32 s8, s14, 0x780
	s_addc_u32 s9, s15, 0
	v_readfirstlane_b32 s5, v164
	ds_read_b128 v[144:147], v160
	ds_read_b128 v[148:151], v161
	ds_read_b128 v[152:155], v162
	ds_read_b128 v[156:159], v163
	ds_read_b128 v[160:163], v140
	ds_read_b128 v[178:181], v140 offset:1024
	ds_read_b128 v[182:185], v143
	ds_read_b128 v[186:189], v143 offset:1024
	ds_read_b128 v[190:193], v142
	ds_read_b128 v[194:197], v142 offset:1024
	ds_read_b128 v[198:201], v141
	ds_read_b128 v[202:205], v141 offset:1024
	s_mov_b32 m0, s5
	v_lshl_add_u64 v[132:133], s[8:9], 0, v[132:133]
	v_readfirstlane_b32 s5, v165
	global_load_lds_dwordx4 v[132:133], off
	v_lshl_add_u64 v[130:131], s[8:9], 0, v[130:131]
	s_mov_b32 m0, s5
	s_nop 0
	global_load_lds_dwordx4 v[130:131], off
	s_barrier
	s_waitcnt lgkmcnt(0)
	s_waitcnt lgkmcnt(0)
	v_mfma_f32_16x16x32_bf16 v[126:129], v[160:163], v[144:147], v[126:129]
	v_mfma_f32_16x16x32_bf16 v[122:125], v[160:163], v[152:155], v[122:125]
	v_mfma_f32_16x16x32_bf16 v[110:113], v[190:193], v[144:147], v[110:113]
	v_mfma_f32_16x16x32_bf16 v[106:109], v[190:193], v[152:155], v[106:109]
	v_mfma_f32_16x16x32_bf16 v[126:129], v[178:181], v[148:151], v[126:129]
	v_mfma_f32_16x16x32_bf16 v[122:125], v[178:181], v[156:159], v[122:125]
	v_mfma_f32_16x16x32_bf16 v[118:121], v[182:185], v[144:147], v[118:121]
	v_mfma_f32_16x16x32_bf16 v[114:117], v[182:185], v[152:155], v[114:117]
	v_mfma_f32_16x16x32_bf16 v[110:113], v[194:197], v[148:151], v[110:113]
	v_mfma_f32_16x16x32_bf16 v[106:109], v[194:197], v[156:159], v[106:109]
	v_mfma_f32_16x16x32_bf16 v[102:105], v[198:201], v[144:147], v[102:105]
	v_mfma_f32_16x16x32_bf16 v[98:101], v[198:201], v[152:155], v[98:101]
	v_mfma_f32_16x16x32_bf16 v[130:133], v[186:189], v[148:151], v[118:121]
	v_mfma_f32_16x16x32_bf16 v[206:209], v[186:189], v[156:159], v[114:117]
	v_mfma_f32_16x16x32_bf16 v[212:215], v[202:205], v[148:151], v[102:105]
	v_mfma_f32_16x16x32_bf16 v[224:227], v[202:205], v[156:159], v[98:101]
	s_barrier
	s_nop 0
	ds_read_b128 v[98:101], v166
	ds_read_b128 v[102:105], v167
	ds_read_b128 v[114:117], v168
	ds_read_b128 v[118:121], v169
	s_barrier
	s_waitcnt lgkmcnt(0)
	s_waitcnt lgkmcnt(3)
	v_mfma_f32_16x16x32_bf16 v[94:97], v[160:163], v[98:101], v[94:97]
	s_waitcnt lgkmcnt(1)
	v_mfma_f32_16x16x32_bf16 v[90:93], v[160:163], v[114:117], v[90:93]
	v_mfma_f32_16x16x32_bf16 v[78:81], v[190:193], v[98:101], v[78:81]
	v_mfma_f32_16x16x32_bf16 v[74:77], v[190:193], v[114:117], v[74:77]
	v_mfma_f32_16x16x32_bf16 v[94:97], v[178:181], v[102:105], v[94:97]
	s_waitcnt lgkmcnt(0)
	v_mfma_f32_16x16x32_bf16 v[90:93], v[178:181], v[118:121], v[90:93]
	v_mfma_f32_16x16x32_bf16 v[86:89], v[182:185], v[98:101], v[86:89]
	v_mfma_f32_16x16x32_bf16 v[82:85], v[182:185], v[114:117], v[82:85]
	v_mfma_f32_16x16x32_bf16 v[78:81], v[194:197], v[102:105], v[78:81]
	v_mfma_f32_16x16x32_bf16 v[74:77], v[194:197], v[118:121], v[74:77]
	v_mfma_f32_16x16x32_bf16 v[70:73], v[198:201], v[98:101], v[70:73]
	v_mfma_f32_16x16x32_bf16 v[66:69], v[198:201], v[114:117], v[66:69]
	v_mfma_f32_16x16x32_bf16 v[160:163], v[186:189], v[102:105], v[86:89]
	v_mfma_f32_16x16x32_bf16 v[164:167], v[186:189], v[118:121], v[82:85]
	v_mfma_f32_16x16x32_bf16 v[178:181], v[202:205], v[102:105], v[70:73]
	v_mfma_f32_16x16x32_bf16 v[182:185], v[202:205], v[118:121], v[66:69]
	s_barrier
	s_nop 1
	ds_read_b128 v[66:69], v140 offset:16384
	ds_read_b128 v[70:73], v140 offset:17408
	ds_read_b128 v[82:85], v143 offset:16384
	ds_read_b128 v[86:89], v143 offset:17408
	ds_read_b128 v[186:189], v142 offset:16384
	ds_read_b128 v[190:193], v142 offset:17408
	ds_read_b128 v[194:197], v141 offset:16384
	ds_read_b128 v[198:201], v141 offset:17408
	s_waitcnt vmcnt(4)
	s_barrier
	s_waitcnt lgkmcnt(0)
	s_waitcnt lgkmcnt(7)
	v_mfma_f32_16x16x32_bf16 v[62:65], v[66:69], v[144:147], v[62:65]
	v_mfma_f32_16x16x32_bf16 v[58:61], v[66:69], v[152:155], v[58:61]
	s_waitcnt lgkmcnt(3)
	v_mfma_f32_16x16x32_bf16 v[46:49], v[186:189], v[144:147], v[46:49]
	v_mfma_f32_16x16x32_bf16 v[42:45], v[186:189], v[152:155], v[42:45]
	v_mfma_f32_16x16x32_bf16 v[62:65], v[70:73], v[148:151], v[62:65]
	v_mfma_f32_16x16x32_bf16 v[58:61], v[70:73], v[156:159], v[58:61]
	v_mfma_f32_16x16x32_bf16 v[54:57], v[82:85], v[144:147], v[54:57]
	v_mfma_f32_16x16x32_bf16 v[50:53], v[82:85], v[152:155], v[50:53]
	s_waitcnt lgkmcnt(2)
	v_mfma_f32_16x16x32_bf16 v[46:49], v[190:193], v[148:151], v[46:49]
	v_mfma_f32_16x16x32_bf16 v[42:45], v[190:193], v[156:159], v[42:45]
	s_waitcnt lgkmcnt(1)
	v_mfma_f32_16x16x32_bf16 v[38:41], v[194:197], v[144:147], v[38:41]
	v_mfma_f32_16x16x32_bf16 v[34:37], v[194:197], v[152:155], v[34:37]
	v_mfma_f32_16x16x32_bf16 v[202:205], v[86:89], v[148:151], v[54:57]
	v_mfma_f32_16x16x32_bf16 v[228:231], v[86:89], v[156:159], v[50:53]
	s_waitcnt lgkmcnt(0)
	v_mfma_f32_16x16x32_bf16 v[144:147], v[198:201], v[148:151], v[38:41]
	v_mfma_f32_16x16x32_bf16 v[148:151], v[198:201], v[156:159], v[34:37]
	v_mfma_f32_16x16x32_bf16 v[30:33], v[66:69], v[98:101], v[30:33]
	v_mfma_f32_16x16x32_bf16 v[26:29], v[66:69], v[114:117], v[26:29]
	v_mfma_f32_16x16x32_bf16 v[14:17], v[186:189], v[98:101], v[14:17]
	v_mfma_f32_16x16x32_bf16 v[10:13], v[186:189], v[114:117], v[10:13]
	v_mfma_f32_16x16x32_bf16 v[30:33], v[70:73], v[102:105], v[30:33]
	v_mfma_f32_16x16x32_bf16 v[26:29], v[70:73], v[118:121], v[26:29]
	v_mfma_f32_16x16x32_bf16 v[22:25], v[82:85], v[98:101], v[22:25]
	v_mfma_f32_16x16x32_bf16 v[18:21], v[82:85], v[114:117], v[18:21]
	v_mfma_f32_16x16x32_bf16 v[14:17], v[190:193], v[102:105], v[14:17]
	v_mfma_f32_16x16x32_bf16 v[10:13], v[190:193], v[118:121], v[10:13]
	v_mfma_f32_16x16x32_bf16 v[6:9], v[194:197], v[98:101], v[6:9]
	v_mfma_f32_16x16x32_bf16 v[2:5], v[194:197], v[114:117], v[2:5]
	v_mfma_f32_16x16x32_bf16 v[152:155], v[86:89], v[102:105], v[22:25]
	v_mfma_f32_16x16x32_bf16 v[156:159], v[86:89], v[118:121], v[18:21]
	v_mfma_f32_16x16x32_bf16 v[186:189], v[198:201], v[102:105], v[6:9]
	v_mfma_f32_16x16x32_bf16 v[190:193], v[198:201], v[118:121], v[2:5]
	s_barrier
	s_nop 1
	ds_read_b128 v[2:5], v170
	ds_read_b128 v[6:9], v171
	ds_read_b128 v[168:171], v172
	ds_read_b128 v[194:197], v173
	ds_read_b128 v[18:21], v140 offset:32768
	ds_read_b128 v[22:25], v140 offset:33792
	ds_read_b128 v[34:37], v143 offset:32768
	ds_read_b128 v[38:41], v143 offset:33792
	ds_read_b128 v[50:53], v142 offset:32768
	ds_read_b128 v[54:57], v142 offset:33792
	ds_read_b128 v[198:201], v141 offset:32768
	ds_read_b128 v[232:235], v141 offset:33792
	s_waitcnt vmcnt(2)
	s_barrier
	s_waitcnt lgkmcnt(0)
	s_waitcnt lgkmcnt(7)
	v_mfma_f32_16x16x32_bf16 v[66:69], v[18:21], v[2:5], v[126:129]
	s_waitcnt lgkmcnt(6)
	v_mfma_f32_16x16x32_bf16 v[114:117], v[22:25], v[6:9], v[66:69]
	v_mfma_f32_16x16x32_bf16 v[66:69], v[18:21], v[168:171], v[122:125]
	v_mfma_f32_16x16x32_bf16 v[118:121], v[22:25], v[194:197], v[66:69]
	s_waitcnt lgkmcnt(5)
	v_mfma_f32_16x16x32_bf16 v[66:69], v[34:37], v[2:5], v[130:133]
	s_waitcnt lgkmcnt(4)
	v_mfma_f32_16x16x32_bf16 v[98:101], v[38:41], v[6:9], v[66:69]
	v_mfma_f32_16x16x32_bf16 v[66:69], v[34:37], v[168:171], v[206:209]
	v_mfma_f32_16x16x32_bf16 v[102:105], v[38:41], v[194:197], v[66:69]
	s_waitcnt lgkmcnt(3)
	v_mfma_f32_16x16x32_bf16 v[66:69], v[50:53], v[2:5], v[110:113]
	s_waitcnt lgkmcnt(2)
	v_mfma_f32_16x16x32_bf16 v[82:85], v[54:57], v[6:9], v[66:69]
	v_mfma_f32_16x16x32_bf16 v[66:69], v[50:53], v[168:171], v[106:109]
	v_mfma_f32_16x16x32_bf16 v[86:89], v[54:57], v[194:197], v[66:69]
	s_waitcnt lgkmcnt(1)
	v_mfma_f32_16x16x32_bf16 v[66:69], v[198:201], v[2:5], v[212:215]
	v_mfma_f32_16x16x32_bf16 v[70:73], v[198:201], v[168:171], v[224:227]
	s_waitcnt lgkmcnt(0)
	v_mfma_f32_16x16x32_bf16 v[66:69], v[232:235], v[6:9], v[66:69]
	v_mfma_f32_16x16x32_bf16 v[70:73], v[232:235], v[194:197], v[70:73]
	s_barrier
	ds_read_b128 v[130:133], v174
	ds_read_b128 v[172:175], v175
	ds_read_b128 v[206:209], v176
	ds_read_b128 v[212:215], v177
	s_waitcnt vmcnt(0)
	s_barrier
	s_waitcnt lgkmcnt(0)
	s_waitcnt lgkmcnt(3)
	v_mfma_f32_16x16x32_bf16 v[94:97], v[18:21], v[130:133], v[94:97]
	s_waitcnt lgkmcnt(1)
	v_mfma_f32_16x16x32_bf16 v[18:21], v[18:21], v[206:209], v[90:93]
	s_waitcnt lgkmcnt(0)
	v_mfma_f32_16x16x32_bf16 v[126:129], v[22:25], v[212:215], v[18:21]
	v_mfma_f32_16x16x32_bf16 v[18:21], v[34:37], v[130:133], v[160:163]
	v_mfma_f32_16x16x32_bf16 v[106:109], v[38:41], v[172:175], v[18:21]
	v_mfma_f32_16x16x32_bf16 v[18:21], v[34:37], v[206:209], v[164:167]
	v_mfma_f32_16x16x32_bf16 v[110:113], v[38:41], v[212:215], v[18:21]
	v_mfma_f32_16x16x32_bf16 v[18:21], v[50:53], v[130:133], v[78:81]
	v_mfma_f32_16x16x32_bf16 v[90:93], v[54:57], v[172:175], v[18:21]
	v_mfma_f32_16x16x32_bf16 v[18:21], v[50:53], v[206:209], v[74:77]
	v_mfma_f32_16x16x32_bf16 v[122:125], v[22:25], v[172:175], v[94:97]
	v_mfma_f32_16x16x32_bf16 v[94:97], v[54:57], v[212:215], v[18:21]
	v_mfma_f32_16x16x32_bf16 v[18:21], v[198:201], v[130:133], v[178:181]
	v_mfma_f32_16x16x32_bf16 v[74:77], v[232:235], v[172:175], v[18:21]
	v_mfma_f32_16x16x32_bf16 v[18:21], v[198:201], v[206:209], v[182:185]
	v_mfma_f32_16x16x32_bf16 v[78:81], v[232:235], v[212:215], v[18:21]
	s_barrier
	ds_read_b128 v[160:163], v140 offset:49152
	ds_read_b128 v[164:167], v140 offset:50176
	ds_read_b128 v[176:179], v143 offset:49152
	ds_read_b128 v[180:183], v143 offset:50176
	ds_read_b128 v[198:201], v142 offset:49152
	ds_read_b128 v[224:227], v142 offset:50176
	ds_read_b128 v[232:235], v141 offset:49152
	ds_read_b128 v[140:143], v141 offset:50176
	s_barrier
	s_waitcnt lgkmcnt(0)
	s_waitcnt lgkmcnt(7)
	v_mfma_f32_16x16x32_bf16 v[18:21], v[160:163], v[2:5], v[62:65]
	s_waitcnt lgkmcnt(6)
	v_mfma_f32_16x16x32_bf16 v[50:53], v[164:167], v[6:9], v[18:21]
	v_mfma_f32_16x16x32_bf16 v[18:21], v[160:163], v[168:171], v[58:61]
	v_mfma_f32_16x16x32_bf16 v[54:57], v[164:167], v[194:197], v[18:21]
	s_waitcnt lgkmcnt(5)
	v_mfma_f32_16x16x32_bf16 v[18:21], v[176:179], v[2:5], v[202:205]
	s_waitcnt lgkmcnt(4)
	v_mfma_f32_16x16x32_bf16 v[34:37], v[180:183], v[6:9], v[18:21]
	v_mfma_f32_16x16x32_bf16 v[18:21], v[176:179], v[168:171], v[228:231]
	v_mfma_f32_16x16x32_bf16 v[38:41], v[180:183], v[194:197], v[18:21]
	s_waitcnt lgkmcnt(3)
	v_mfma_f32_16x16x32_bf16 v[18:21], v[198:201], v[2:5], v[46:49]
	s_waitcnt lgkmcnt(1)
	v_mfma_f32_16x16x32_bf16 v[2:5], v[232:235], v[2:5], v[144:147]
	v_mfma_f32_16x16x32_bf16 v[18:21], v[224:227], v[6:9], v[18:21]
	v_mfma_f32_16x16x32_bf16 v[22:25], v[198:201], v[168:171], v[42:45]
	s_waitcnt lgkmcnt(0)
	v_mfma_f32_16x16x32_bf16 v[2:5], v[140:143], v[6:9], v[2:5]
	v_mfma_f32_16x16x32_bf16 v[6:9], v[232:235], v[168:171], v[148:151]
	v_mfma_f32_16x16x32_bf16 v[22:25], v[224:227], v[194:197], v[22:25]
	v_mfma_f32_16x16x32_bf16 v[6:9], v[140:143], v[194:197], v[6:9]
	v_mfma_f32_16x16x32_bf16 v[26:29], v[160:163], v[206:209], v[26:29]
	v_mfma_f32_16x16x32_bf16 v[62:65], v[164:167], v[212:215], v[26:29]
	v_mfma_f32_16x16x32_bf16 v[26:29], v[176:179], v[130:133], v[152:155]
	v_mfma_f32_16x16x32_bf16 v[30:33], v[160:163], v[130:133], v[30:33]
	v_mfma_f32_16x16x32_bf16 v[42:45], v[180:183], v[172:175], v[26:29]
	v_mfma_f32_16x16x32_bf16 v[26:29], v[176:179], v[206:209], v[156:159]
	v_mfma_f32_16x16x32_bf16 v[14:17], v[198:201], v[130:133], v[14:17]
	v_mfma_f32_16x16x32_bf16 v[10:13], v[198:201], v[206:209], v[10:13]
	v_mfma_f32_16x16x32_bf16 v[58:61], v[164:167], v[172:175], v[30:33]
	v_mfma_f32_16x16x32_bf16 v[46:49], v[180:183], v[212:215], v[26:29]
	v_mfma_f32_16x16x32_bf16 v[26:29], v[224:227], v[172:175], v[14:17]
	v_mfma_f32_16x16x32_bf16 v[30:33], v[224:227], v[212:215], v[10:13]
	v_mfma_f32_16x16x32_bf16 v[10:13], v[232:235], v[130:133], v[186:189]
	v_mfma_f32_16x16x32_bf16 v[14:17], v[232:235], v[206:209], v[190:193]
	v_mfma_f32_16x16x32_bf16 v[10:13], v[140:143], v[172:175], v[10:13]
	v_mfma_f32_16x16x32_bf16 v[14:17], v[140:143], v[212:215], v[14:17]
	s_movk_i32 s5, 0x100
	v_cmp_gt_u32_e32 vcc, s5, v134
	s_barrier
	s_and_saveexec_b64 s[8:9], vcc
	s_cbranch_execz .LBB0_850
	s_barrier

.LBB0_1353:
	v_or_b32_e32 v164, 0x10000, v160
	v_or_b32_e32 v166, 0x10000, v162
	v_or_b32_e32 v165, 0x10000, v161
	ds_read_b128 v[174:177], v164
	ds_read_b128 v[178:181], v165
	v_or_b32_e32 v167, 0x10000, v163
	ds_read_b128 v[182:185], v166
	ds_read_b128 v[186:189], v167
	s_add_u32 s25, s22, s12
	s_addc_u32 s27, s23, s13
	s_add_u32 s26, s25, 0x80
	v_add_u32_e32 v168, 0xc000, v142
	s_addc_u32 s27, s27, 0
	v_readfirstlane_b32 s25, v168
	v_add_u32_e32 v169, 0xe000, v142
	ds_read_b128 v[190:193], v144
	ds_read_b128 v[194:197], v144 offset:1024
	ds_read_b128 v[198:201], v147
	ds_read_b128 v[202:205], v147 offset:1024
	ds_read_b128 v[206:209], v146
	ds_read_b128 v[212:215], v146 offset:1024
	ds_read_b128 v[224:227], v145
	ds_read_b128 v[228:231], v145 offset:1024
	s_mov_b32 m0, s25
	v_lshl_add_u64 v[170:171], s[26:27], 0, v[132:133]
	v_readfirstlane_b32 s25, v169
	global_load_lds_dwordx4 v[170:171], off
	v_lshl_add_u64 v[170:171], s[26:27], 0, v[130:131]
	s_mov_b32 m0, s25
	s_nop 0
	global_load_lds_dwordx4 v[170:171], off
	s_waitcnt lgkmcnt(8)
	s_barrier
	s_waitcnt lgkmcnt(0)
	s_waitcnt lgkmcnt(0)
	v_mfma_f32_16x16x32_bf16 v[126:129], v[190:193], v[174:177], v[126:129]
	v_mfma_f32_16x16x32_bf16 v[122:125], v[190:193], v[182:185], v[122:125]
	v_mfma_f32_16x16x32_bf16 v[118:121], v[198:201], v[174:177], v[118:121]
	v_mfma_f32_16x16x32_bf16 v[114:117], v[198:201], v[182:185], v[114:117]
	v_mfma_f32_16x16x32_bf16 v[110:113], v[206:209], v[174:177], v[110:113]
	v_mfma_f32_16x16x32_bf16 v[106:109], v[206:209], v[182:185], v[106:109]
	v_mfma_f32_16x16x32_bf16 v[102:105], v[224:227], v[174:177], v[102:105]
	v_mfma_f32_16x16x32_bf16 v[98:101], v[224:227], v[182:185], v[98:101]
	v_mfma_f32_16x16x32_bf16 v[126:129], v[194:197], v[178:181], v[126:129]
	v_mfma_f32_16x16x32_bf16 v[122:125], v[194:197], v[186:189], v[122:125]
	v_mfma_f32_16x16x32_bf16 v[118:121], v[202:205], v[178:181], v[118:121]
	v_mfma_f32_16x16x32_bf16 v[114:117], v[202:205], v[186:189], v[114:117]
	v_mfma_f32_16x16x32_bf16 v[110:113], v[212:215], v[178:181], v[110:113]
	v_mfma_f32_16x16x32_bf16 v[106:109], v[212:215], v[186:189], v[106:109]
	v_mfma_f32_16x16x32_bf16 v[102:105], v[228:231], v[178:181], v[102:105]
	v_mfma_f32_16x16x32_bf16 v[98:101], v[228:231], v[186:189], v[98:101]
	s_barrier
	s_add_u32 s25, s4, s12
	s_addc_u32 s28, s5, s13
	s_add_u32 s26, s25, 0x100
	v_or_b32_e32 v170, 0x14000, v160
	v_or_b32_e32 v172, 0x14000, v162
	s_addc_u32 s27, s28, 0
	v_readfirstlane_b32 s29, v148
	v_or_b32_e32 v171, 0x14000, v161
	ds_read_b128 v[232:235], v170
	ds_read_b128 v[236:239], v171
	v_or_b32_e32 v173, 0x14000, v163
	ds_read_b128 v[240:243], v172
	ds_read_b128 v[244:247], v173
	s_mov_b32 m0, s29
	v_lshl_add_u64 v[216:217], s[26:27], 0, v[134:135]
	global_load_lds_dwordx4 v[216:217], off
	v_lshl_add_u64 v[216:217], s[26:27], 0, v[136:137]
	v_readfirstlane_b32 s26, v149
	s_mov_b32 m0, s26
	s_nop 0
	global_load_lds_dwordx4 v[216:217], off
	s_barrier
	s_waitcnt lgkmcnt(0)
	s_waitcnt lgkmcnt(0)
	v_mfma_f32_16x16x32_bf16 v[94:97], v[190:193], v[232:235], v[94:97]
	v_mfma_f32_16x16x32_bf16 v[90:93], v[190:193], v[240:243], v[90:93]
	v_mfma_f32_16x16x32_bf16 v[86:89], v[198:201], v[232:235], v[86:89]
	v_mfma_f32_16x16x32_bf16 v[82:85], v[198:201], v[240:243], v[82:85]
	v_mfma_f32_16x16x32_bf16 v[78:81], v[206:209], v[232:235], v[78:81]
	v_mfma_f32_16x16x32_bf16 v[74:77], v[206:209], v[240:243], v[74:77]
	v_mfma_f32_16x16x32_bf16 v[70:73], v[224:227], v[232:235], v[70:73]
	v_mfma_f32_16x16x32_bf16 v[66:69], v[224:227], v[240:243], v[66:69]
	v_mfma_f32_16x16x32_bf16 v[94:97], v[194:197], v[236:239], v[94:97]
	v_mfma_f32_16x16x32_bf16 v[90:93], v[194:197], v[244:247], v[90:93]
	v_mfma_f32_16x16x32_bf16 v[86:89], v[202:205], v[236:239], v[86:89]
	v_mfma_f32_16x16x32_bf16 v[82:85], v[202:205], v[244:247], v[82:85]
	v_mfma_f32_16x16x32_bf16 v[78:81], v[212:215], v[236:239], v[78:81]
	v_mfma_f32_16x16x32_bf16 v[74:77], v[212:215], v[244:247], v[74:77]
	v_mfma_f32_16x16x32_bf16 v[70:73], v[228:231], v[236:239], v[70:73]
	v_mfma_f32_16x16x32_bf16 v[66:69], v[228:231], v[244:247], v[66:69]
	s_add_u32 s29, s6, s12
	s_addc_u32 s30, s7, s13
	s_add_u32 s26, s29, 0x100
	s_addc_u32 s27, s30, 0
	v_readfirstlane_b32 s31, v142
	s_barrier
	ds_read_b128 v[190:193], v144 offset:16384
	ds_read_b128 v[194:197], v144 offset:17408
	ds_read_b128 v[198:201], v147 offset:16384
	ds_read_b128 v[202:205], v147 offset:17408
	ds_read_b128 v[206:209], v146 offset:16384
	ds_read_b128 v[212:215], v146 offset:17408
	ds_read_b128 v[224:227], v145 offset:16384
	ds_read_b128 v[228:231], v145 offset:17408
	s_mov_b32 m0, s31
	v_lshl_add_u64 v[216:217], s[26:27], 0, v[132:133]
	global_load_lds_dwordx4 v[216:217], off
	v_lshl_add_u64 v[216:217], s[26:27], 0, v[130:131]
	v_readfirstlane_b32 s26, v143
	s_mov_b32 m0, s26
	s_nop 0
	global_load_lds_dwordx4 v[216:217], off
	s_barrier
	s_waitcnt lgkmcnt(0)
	s_waitcnt lgkmcnt(0)
	v_mfma_f32_16x16x32_bf16 v[62:65], v[190:193], v[174:177], v[62:65]
	v_mfma_f32_16x16x32_bf16 v[58:61], v[190:193], v[182:185], v[58:61]
	v_mfma_f32_16x16x32_bf16 v[54:57], v[198:201], v[174:177], v[54:57]
	v_mfma_f32_16x16x32_bf16 v[50:53], v[198:201], v[182:185], v[50:53]
	v_mfma_f32_16x16x32_bf16 v[46:49], v[206:209], v[174:177], v[46:49]
	v_mfma_f32_16x16x32_bf16 v[42:45], v[206:209], v[182:185], v[42:45]
	v_mfma_f32_16x16x32_bf16 v[38:41], v[224:227], v[174:177], v[38:41]
	v_mfma_f32_16x16x32_bf16 v[34:37], v[224:227], v[182:185], v[34:37]
	v_mfma_f32_16x16x32_bf16 v[62:65], v[194:197], v[178:181], v[62:65]
	v_mfma_f32_16x16x32_bf16 v[58:61], v[194:197], v[186:189], v[58:61]
	v_mfma_f32_16x16x32_bf16 v[54:57], v[202:205], v[178:181], v[54:57]
	v_mfma_f32_16x16x32_bf16 v[50:53], v[202:205], v[186:189], v[50:53]
	v_mfma_f32_16x16x32_bf16 v[46:49], v[212:215], v[178:181], v[46:49]
	v_mfma_f32_16x16x32_bf16 v[42:45], v[212:215], v[186:189], v[42:45]
	v_mfma_f32_16x16x32_bf16 v[38:41], v[228:231], v[178:181], v[38:41]
	v_mfma_f32_16x16x32_bf16 v[34:37], v[228:231], v[186:189], v[34:37]
	s_barrier
	s_add_u32 s31, s8, s12
	s_addc_u32 s34, s9, s13
	s_add_u32 s26, s31, 0x100
	s_addc_u32 s27, s34, 0
	v_readfirstlane_b32 s35, v150
	s_mov_b32 m0, s35
	v_lshl_add_u64 v[174:175], s[26:27], 0, v[134:135]
	global_load_lds_dwordx4 v[174:175], off
	v_lshl_add_u64 v[174:175], s[26:27], 0, v[136:137]
	v_readfirstlane_b32 s26, v151
	s_mov_b32 m0, s26
	s_nop 0
	global_load_lds_dwordx4 v[174:175], off
	s_waitcnt vmcnt(6)
	s_barrier
	v_mfma_f32_16x16x32_bf16 v[30:33], v[190:193], v[232:235], v[30:33]
	v_mfma_f32_16x16x32_bf16 v[26:29], v[190:193], v[240:243], v[26:29]
	v_mfma_f32_16x16x32_bf16 v[22:25], v[198:201], v[232:235], v[22:25]
	v_mfma_f32_16x16x32_bf16 v[18:21], v[198:201], v[240:243], v[18:21]
	v_mfma_f32_16x16x32_bf16 v[14:17], v[206:209], v[232:235], v[14:17]
	v_mfma_f32_16x16x32_bf16 v[10:13], v[206:209], v[240:243], v[10:13]
	v_mfma_f32_16x16x32_bf16 v[6:9], v[224:227], v[232:235], v[6:9]
	v_mfma_f32_16x16x32_bf16 v[2:5], v[224:227], v[240:243], v[2:5]
	v_mfma_f32_16x16x32_bf16 v[30:33], v[194:197], v[236:239], v[30:33]
	v_mfma_f32_16x16x32_bf16 v[26:29], v[194:197], v[244:247], v[26:29]
	v_mfma_f32_16x16x32_bf16 v[22:25], v[202:205], v[236:239], v[22:25]
	v_mfma_f32_16x16x32_bf16 v[18:21], v[202:205], v[244:247], v[18:21]
	v_mfma_f32_16x16x32_bf16 v[14:17], v[212:215], v[236:239], v[14:17]
	v_mfma_f32_16x16x32_bf16 v[10:13], v[212:215], v[244:247], v[10:13]
	v_mfma_f32_16x16x32_bf16 v[6:9], v[228:231], v[236:239], v[6:9]
	v_mfma_f32_16x16x32_bf16 v[2:5], v[228:231], v[244:247], v[2:5]
	v_or_b32_e32 v174, 0x18000, v160
	v_or_b32_e32 v176, 0x18000, v162
	s_barrier
	v_or_b32_e32 v175, 0x18000, v161
	ds_read_b128 v[182:185], v174
	ds_read_b128 v[186:189], v175
	v_or_b32_e32 v177, 0x18000, v163
	ds_read_b128 v[190:193], v176
	ds_read_b128 v[194:197], v177
	s_add_u32 s26, s20, s12
	s_addc_u32 s27, s21, s13
	v_readfirstlane_b32 s35, v152
	ds_read_b128 v[198:201], v144 offset:32768
	ds_read_b128 v[202:205], v144 offset:33792
	ds_read_b128 v[206:209], v147 offset:32768
	ds_read_b128 v[212:215], v147 offset:33792
	ds_read_b128 v[224:227], v146 offset:32768
	ds_read_b128 v[228:231], v146 offset:33792
	ds_read_b128 v[232:235], v145 offset:32768
	ds_read_b128 v[236:239], v145 offset:33792
	s_mov_b32 m0, s35
	v_lshl_add_u64 v[178:179], s[26:27], 0, v[132:133]
	global_load_lds_dwordx4 v[178:179], off
	v_lshl_add_u64 v[178:179], s[26:27], 0, v[130:131]
	v_readfirstlane_b32 s26, v153
	s_mov_b32 m0, s26
	s_nop 0
	global_load_lds_dwordx4 v[178:179], off
	s_waitcnt lgkmcnt(8)
	s_barrier
	s_waitcnt lgkmcnt(0)
	s_waitcnt lgkmcnt(0)
	v_mfma_f32_16x16x32_bf16 v[126:129], v[198:201], v[182:185], v[126:129]
	v_mfma_f32_16x16x32_bf16 v[122:125], v[198:201], v[190:193], v[122:125]
	v_mfma_f32_16x16x32_bf16 v[118:121], v[206:209], v[182:185], v[118:121]
	v_mfma_f32_16x16x32_bf16 v[114:117], v[206:209], v[190:193], v[114:117]
	v_mfma_f32_16x16x32_bf16 v[110:113], v[224:227], v[182:185], v[110:113]
	v_mfma_f32_16x16x32_bf16 v[106:109], v[224:227], v[190:193], v[106:109]
	v_mfma_f32_16x16x32_bf16 v[102:105], v[232:235], v[182:185], v[102:105]
	v_mfma_f32_16x16x32_bf16 v[98:101], v[232:235], v[190:193], v[98:101]
	v_mfma_f32_16x16x32_bf16 v[126:129], v[202:205], v[186:189], v[126:129]
	v_mfma_f32_16x16x32_bf16 v[122:125], v[202:205], v[194:197], v[122:125]
	v_mfma_f32_16x16x32_bf16 v[118:121], v[212:215], v[186:189], v[118:121]
	v_mfma_f32_16x16x32_bf16 v[114:117], v[212:215], v[194:197], v[114:117]
	v_mfma_f32_16x16x32_bf16 v[110:113], v[228:231], v[186:189], v[110:113]
	v_mfma_f32_16x16x32_bf16 v[106:109], v[228:231], v[194:197], v[106:109]
	v_mfma_f32_16x16x32_bf16 v[102:105], v[236:239], v[186:189], v[102:105]
	v_mfma_f32_16x16x32_bf16 v[98:101], v[236:239], v[194:197], v[98:101]
	s_barrier
	s_add_u32 s26, s25, 0x180
	v_or_b32_e32 v178, 0x1c000, v160
	v_or_b32_e32 v180, 0x1c000, v162
	s_addc_u32 s27, s28, 0
	v_readfirstlane_b32 s25, v154
	v_or_b32_e32 v179, 0x1c000, v161
	ds_read_b128 v[240:243], v178
	ds_read_b128 v[244:247], v179
	v_or_b32_e32 v181, 0x1c000, v163
	ds_read_b128 v[248:251], v180
	ds_read_b128 v[216:219], v181
	s_mov_b32 m0, s25
	v_lshl_add_u64 v[252:253], s[26:27], 0, v[134:135]
	v_readfirstlane_b32 s25, v155
	global_load_lds_dwordx4 v[252:253], off
	v_lshl_add_u64 v[252:253], s[26:27], 0, v[136:137]
	s_mov_b32 m0, s25
	s_nop 0
	global_load_lds_dwordx4 v[252:253], off
	s_barrier
	s_waitcnt lgkmcnt(0)
	s_waitcnt lgkmcnt(0)
	v_mfma_f32_16x16x32_bf16 v[94:97], v[198:201], v[240:243], v[94:97]
	v_mfma_f32_16x16x32_bf16 v[90:93], v[198:201], v[248:251], v[90:93]
	v_mfma_f32_16x16x32_bf16 v[86:89], v[206:209], v[240:243], v[86:89]
	v_mfma_f32_16x16x32_bf16 v[82:85], v[206:209], v[248:251], v[82:85]
	v_mfma_f32_16x16x32_bf16 v[78:81], v[224:227], v[240:243], v[78:81]
	v_mfma_f32_16x16x32_bf16 v[74:77], v[224:227], v[248:251], v[74:77]
	v_mfma_f32_16x16x32_bf16 v[70:73], v[232:235], v[240:243], v[70:73]
	v_mfma_f32_16x16x32_bf16 v[66:69], v[232:235], v[248:251], v[66:69]
	v_mfma_f32_16x16x32_bf16 v[94:97], v[202:205], v[244:247], v[94:97]
	v_mfma_f32_16x16x32_bf16 v[90:93], v[202:205], v[216:219], v[90:93]
	v_mfma_f32_16x16x32_bf16 v[86:89], v[212:215], v[244:247], v[86:89]
	v_mfma_f32_16x16x32_bf16 v[82:85], v[212:215], v[216:219], v[82:85]
	v_mfma_f32_16x16x32_bf16 v[78:81], v[228:231], v[244:247], v[78:81]
	v_mfma_f32_16x16x32_bf16 v[74:77], v[228:231], v[216:219], v[74:77]
	v_mfma_f32_16x16x32_bf16 v[70:73], v[236:239], v[244:247], v[70:73]
	v_mfma_f32_16x16x32_bf16 v[66:69], v[236:239], v[216:219], v[66:69]
	s_add_u32 s26, s29, 0x180
	s_addc_u32 s27, s30, 0
	v_readfirstlane_b32 s25, v156
	s_barrier
	ds_read_b128 v[198:201], v144 offset:49152
	ds_read_b128 v[202:205], v144 offset:50176
	ds_read_b128 v[206:209], v147 offset:49152
	ds_read_b128 v[212:215], v147 offset:50176
	ds_read_b128 v[224:227], v146 offset:49152
	ds_read_b128 v[228:231], v146 offset:50176
	ds_read_b128 v[232:235], v145 offset:49152
	ds_read_b128 v[236:239], v145 offset:50176
	s_mov_b32 m0, s25
	v_lshl_add_u64 v[252:253], s[26:27], 0, v[132:133]
	v_readfirstlane_b32 s25, v157
	global_load_lds_dwordx4 v[252:253], off
	v_lshl_add_u64 v[252:253], s[26:27], 0, v[130:131]
	s_mov_b32 m0, s25
	s_nop 0
	global_load_lds_dwordx4 v[252:253], off
	s_barrier
	s_waitcnt lgkmcnt(0)
	s_waitcnt lgkmcnt(0)
	v_mfma_f32_16x16x32_bf16 v[62:65], v[198:201], v[182:185], v[62:65]
	v_mfma_f32_16x16x32_bf16 v[58:61], v[198:201], v[190:193], v[58:61]
	v_mfma_f32_16x16x32_bf16 v[54:57], v[206:209], v[182:185], v[54:57]
	v_mfma_f32_16x16x32_bf16 v[50:53], v[206:209], v[190:193], v[50:53]
	v_mfma_f32_16x16x32_bf16 v[46:49], v[224:227], v[182:185], v[46:49]
	v_mfma_f32_16x16x32_bf16 v[42:45], v[224:227], v[190:193], v[42:45]
	v_mfma_f32_16x16x32_bf16 v[38:41], v[232:235], v[182:185], v[38:41]
	v_mfma_f32_16x16x32_bf16 v[34:37], v[232:235], v[190:193], v[34:37]
	v_mfma_f32_16x16x32_bf16 v[62:65], v[202:205], v[186:189], v[62:65]
	v_mfma_f32_16x16x32_bf16 v[58:61], v[202:205], v[194:197], v[58:61]
	v_mfma_f32_16x16x32_bf16 v[54:57], v[212:215], v[186:189], v[54:57]
	v_mfma_f32_16x16x32_bf16 v[50:53], v[212:215], v[194:197], v[50:53]
	v_mfma_f32_16x16x32_bf16 v[46:49], v[228:231], v[186:189], v[46:49]
	v_mfma_f32_16x16x32_bf16 v[42:45], v[228:231], v[194:197], v[42:45]
	v_mfma_f32_16x16x32_bf16 v[38:41], v[236:239], v[186:189], v[38:41]
	v_mfma_f32_16x16x32_bf16 v[34:37], v[236:239], v[194:197], v[34:37]
	s_barrier
	s_add_u32 s26, s31, 0x180
	s_addc_u32 s27, s34, 0
	v_readfirstlane_b32 s25, v158
	s_mov_b32 m0, s25
	v_lshl_add_u64 v[182:183], s[26:27], 0, v[134:135]
	v_readfirstlane_b32 s25, v159
	global_load_lds_dwordx4 v[182:183], off
	v_lshl_add_u64 v[182:183], s[26:27], 0, v[136:137]
	s_mov_b32 m0, s25
	s_nop 0
	global_load_lds_dwordx4 v[182:183], off
	s_waitcnt vmcnt(6)
	s_barrier
	v_mfma_f32_16x16x32_bf16 v[30:33], v[198:201], v[240:243], v[30:33]
	v_mfma_f32_16x16x32_bf16 v[26:29], v[198:201], v[248:251], v[26:29]
	v_mfma_f32_16x16x32_bf16 v[22:25], v[206:209], v[240:243], v[22:25]
	v_mfma_f32_16x16x32_bf16 v[18:21], v[206:209], v[248:251], v[18:21]
	v_mfma_f32_16x16x32_bf16 v[14:17], v[224:227], v[240:243], v[14:17]
	v_mfma_f32_16x16x32_bf16 v[10:13], v[224:227], v[248:251], v[10:13]
	v_mfma_f32_16x16x32_bf16 v[6:9], v[232:235], v[240:243], v[6:9]
	v_mfma_f32_16x16x32_bf16 v[2:5], v[232:235], v[248:251], v[2:5]
	v_mfma_f32_16x16x32_bf16 v[30:33], v[202:205], v[244:247], v[30:33]
	v_mfma_f32_16x16x32_bf16 v[26:29], v[202:205], v[216:219], v[26:29]
	v_mfma_f32_16x16x32_bf16 v[22:25], v[212:215], v[244:247], v[22:25]
	v_mfma_f32_16x16x32_bf16 v[18:21], v[212:215], v[216:219], v[18:21]
	v_mfma_f32_16x16x32_bf16 v[14:17], v[228:231], v[244:247], v[14:17]
	v_mfma_f32_16x16x32_bf16 v[10:13], v[228:231], v[216:219], v[10:13]
	v_mfma_f32_16x16x32_bf16 v[6:9], v[236:239], v[244:247], v[6:9]
	v_mfma_f32_16x16x32_bf16 v[2:5], v[236:239], v[216:219], v[2:5]
	s_add_i32 s24, s24, 2
	s_add_u32 s12, s12, 0x100
	s_addc_u32 s13, s13, 0
	s_cmp_lt_u32 s24, 28
	s_barrier
	s_cbranch_scc1 .LBB0_1353
	s_add_u32 s4, s10, 0xf80
	s_addc_u32 s5, s11, 0
	ds_read_b128 v[134:137], v164
	ds_read_b128 v[148:151], v165
	ds_read_b128 v[152:155], v166
	ds_read_b128 v[156:159], v167
	ds_read_b128 v[160:163], v144
	ds_read_b128 v[164:167], v144 offset:1024
	ds_read_b128 v[182:185], v147
	ds_read_b128 v[186:189], v147 offset:1024
	ds_read_b128 v[190:193], v146
	ds_read_b128 v[194:197], v146 offset:1024
	ds_read_b128 v[198:201], v145
	ds_read_b128 v[202:205], v145 offset:1024
	v_readfirstlane_b32 s6, v168
	v_lshl_add_u64 v[132:133], s[4:5], 0, v[132:133]
	s_mov_b32 m0, s6
	v_lshl_add_u64 v[130:131], s[4:5], 0, v[130:131]
	v_readfirstlane_b32 s4, v169
	global_load_lds_dwordx4 v[132:133], off
	s_mov_b32 m0, s4
	s_nop 0
	global_load_lds_dwordx4 v[130:131], off
	s_barrier
	s_waitcnt lgkmcnt(0)
	s_waitcnt lgkmcnt(0)
	v_mfma_f32_16x16x32_bf16 v[126:129], v[160:163], v[134:137], v[126:129]
	v_mfma_f32_16x16x32_bf16 v[122:125], v[160:163], v[152:155], v[122:125]
	v_mfma_f32_16x16x32_bf16 v[118:121], v[182:185], v[134:137], v[118:121]
	v_mfma_f32_16x16x32_bf16 v[114:117], v[182:185], v[152:155], v[114:117]
	v_mfma_f32_16x16x32_bf16 v[110:113], v[190:193], v[134:137], v[110:113]
	v_mfma_f32_16x16x32_bf16 v[106:109], v[190:193], v[152:155], v[106:109]
	v_mfma_f32_16x16x32_bf16 v[98:101], v[198:201], v[152:155], v[98:101]
	v_mfma_f32_16x16x32_bf16 v[126:129], v[164:167], v[148:151], v[126:129]
	v_mfma_f32_16x16x32_bf16 v[122:125], v[164:167], v[156:159], v[122:125]
	v_mfma_f32_16x16x32_bf16 v[118:121], v[186:189], v[148:151], v[118:121]
	v_mfma_f32_16x16x32_bf16 v[114:117], v[186:189], v[156:159], v[114:117]
	v_mfma_f32_16x16x32_bf16 v[110:113], v[194:197], v[148:151], v[110:113]
	v_mfma_f32_16x16x32_bf16 v[106:109], v[194:197], v[156:159], v[106:109]
	v_mfma_f32_16x16x32_bf16 v[102:105], v[198:201], v[134:137], v[102:105]
	v_mfma_f32_16x16x32_bf16 v[98:101], v[202:205], v[156:159], v[98:101]
	v_mfma_f32_16x16x32_bf16 v[130:133], v[202:205], v[148:151], v[102:105]
	s_barrier
	s_nop 2
	ds_read_b128 v[102:105], v170
	ds_read_b128 v[168:171], v171
	ds_read_b128 v[206:209], v172
	ds_read_b128 v[212:215], v173
	s_barrier
	s_waitcnt lgkmcnt(0)
	s_waitcnt lgkmcnt(1)
	v_mfma_f32_16x16x32_bf16 v[90:93], v[160:163], v[206:209], v[90:93]
	v_mfma_f32_16x16x32_bf16 v[94:97], v[160:163], v[102:105], v[94:97]
	s_waitcnt lgkmcnt(0)
	v_mfma_f32_16x16x32_bf16 v[90:93], v[164:167], v[212:215], v[90:93]
	v_mfma_f32_16x16x32_bf16 v[86:89], v[182:185], v[102:105], v[86:89]
	v_mfma_f32_16x16x32_bf16 v[82:85], v[182:185], v[206:209], v[82:85]
	v_mfma_f32_16x16x32_bf16 v[78:81], v[190:193], v[102:105], v[78:81]
	v_mfma_f32_16x16x32_bf16 v[74:77], v[190:193], v[206:209], v[74:77]
	v_mfma_f32_16x16x32_bf16 v[70:73], v[198:201], v[102:105], v[70:73]
	v_mfma_f32_16x16x32_bf16 v[66:69], v[198:201], v[206:209], v[66:69]
	v_mfma_f32_16x16x32_bf16 v[216:219], v[164:167], v[168:171], v[94:97]
	v_mfma_f32_16x16x32_bf16 v[160:163], v[186:189], v[168:171], v[86:89]
	v_mfma_f32_16x16x32_bf16 v[164:167], v[186:189], v[212:215], v[82:85]
	v_mfma_f32_16x16x32_bf16 v[182:185], v[194:197], v[168:171], v[78:81]
	v_mfma_f32_16x16x32_bf16 v[186:189], v[194:197], v[212:215], v[74:77]
	v_mfma_f32_16x16x32_bf16 v[190:193], v[202:205], v[168:171], v[70:73]
	v_mfma_f32_16x16x32_bf16 v[194:197], v[202:205], v[212:215], v[66:69]
	s_barrier
	s_nop 0
	ds_read_b128 v[66:69], v144 offset:16384
	ds_read_b128 v[70:73], v144 offset:17408
	ds_read_b128 v[74:77], v147 offset:16384
	ds_read_b128 v[78:81], v147 offset:17408
	ds_read_b128 v[82:85], v146 offset:16384
	ds_read_b128 v[86:89], v146 offset:17408
	ds_read_b128 v[94:97], v145 offset:16384
	ds_read_b128 v[198:201], v145 offset:17408
	s_waitcnt vmcnt(4)
	s_barrier
	s_waitcnt lgkmcnt(0)
	s_waitcnt lgkmcnt(7)
	v_mfma_f32_16x16x32_bf16 v[62:65], v[66:69], v[134:137], v[62:65]
	v_mfma_f32_16x16x32_bf16 v[58:61], v[66:69], v[152:155], v[58:61]
	s_waitcnt lgkmcnt(5)
	v_mfma_f32_16x16x32_bf16 v[54:57], v[74:77], v[134:137], v[54:57]
	v_mfma_f32_16x16x32_bf16 v[50:53], v[74:77], v[152:155], v[50:53]
	s_waitcnt lgkmcnt(3)
	v_mfma_f32_16x16x32_bf16 v[46:49], v[82:85], v[134:137], v[46:49]
	v_mfma_f32_16x16x32_bf16 v[42:45], v[82:85], v[152:155], v[42:45]
	s_waitcnt lgkmcnt(1)
	v_mfma_f32_16x16x32_bf16 v[38:41], v[94:97], v[134:137], v[38:41]
	v_mfma_f32_16x16x32_bf16 v[34:37], v[94:97], v[152:155], v[34:37]
	v_mfma_f32_16x16x32_bf16 v[62:65], v[70:73], v[148:151], v[62:65]
	v_mfma_f32_16x16x32_bf16 v[58:61], v[70:73], v[156:159], v[58:61]
	v_mfma_f32_16x16x32_bf16 v[54:57], v[78:81], v[148:151], v[54:57]
	v_mfma_f32_16x16x32_bf16 v[50:53], v[78:81], v[156:159], v[50:53]
	v_mfma_f32_16x16x32_bf16 v[46:49], v[86:89], v[148:151], v[46:49]
	v_mfma_f32_16x16x32_bf16 v[42:45], v[86:89], v[156:159], v[42:45]
	s_waitcnt lgkmcnt(0)
	v_mfma_f32_16x16x32_bf16 v[38:41], v[198:201], v[148:151], v[38:41]
	v_mfma_f32_16x16x32_bf16 v[34:37], v[198:201], v[156:159], v[34:37]
	v_mfma_f32_16x16x32_bf16 v[30:33], v[66:69], v[102:105], v[30:33]
	v_mfma_f32_16x16x32_bf16 v[26:29], v[66:69], v[206:209], v[26:29]
	v_mfma_f32_16x16x32_bf16 v[22:25], v[74:77], v[102:105], v[22:25]
	v_mfma_f32_16x16x32_bf16 v[18:21], v[74:77], v[206:209], v[18:21]
	v_mfma_f32_16x16x32_bf16 v[14:17], v[82:85], v[102:105], v[14:17]
	v_mfma_f32_16x16x32_bf16 v[10:13], v[82:85], v[206:209], v[10:13]
	v_mfma_f32_16x16x32_bf16 v[6:9], v[94:97], v[102:105], v[6:9]
	v_mfma_f32_16x16x32_bf16 v[2:5], v[94:97], v[206:209], v[2:5]
	v_mfma_f32_16x16x32_bf16 v[134:137], v[70:73], v[168:171], v[30:33]
	v_mfma_f32_16x16x32_bf16 v[148:151], v[70:73], v[212:215], v[26:29]
	v_mfma_f32_16x16x32_bf16 v[152:155], v[78:81], v[168:171], v[22:25]
	v_mfma_f32_16x16x32_bf16 v[156:159], v[78:81], v[212:215], v[18:21]
	v_mfma_f32_16x16x32_bf16 v[202:205], v[86:89], v[168:171], v[14:17]
	v_mfma_f32_16x16x32_bf16 v[224:227], v[86:89], v[212:215], v[10:13]
	v_mfma_f32_16x16x32_bf16 v[168:171], v[198:201], v[168:171], v[6:9]
	v_mfma_f32_16x16x32_bf16 v[198:201], v[198:201], v[212:215], v[2:5]
	s_barrier
	s_nop 0
	ds_read_b128 v[2:5], v174
	ds_read_b128 v[6:9], v175
	ds_read_b128 v[172:175], v176
	ds_read_b128 v[206:209], v177
	ds_read_b128 v[10:13], v144 offset:32768
	ds_read_b128 v[14:17], v144 offset:33792
	ds_read_b128 v[18:21], v147 offset:32768
	ds_read_b128 v[22:25], v147 offset:33792
	ds_read_b128 v[26:29], v146 offset:32768
	ds_read_b128 v[30:33], v146 offset:33792
	ds_read_b128 v[212:215], v145 offset:32768
	ds_read_b128 v[228:231], v145 offset:33792
	s_waitcnt vmcnt(2)
	s_barrier
	s_waitcnt lgkmcnt(0)
	s_waitcnt lgkmcnt(7)
	v_mfma_f32_16x16x32_bf16 v[66:69], v[10:13], v[2:5], v[126:129]
	s_waitcnt lgkmcnt(6)
	v_mfma_f32_16x16x32_bf16 v[94:97], v[14:17], v[6:9], v[66:69]
	v_mfma_f32_16x16x32_bf16 v[66:69], v[10:13], v[172:175], v[122:125]
	v_mfma_f32_16x16x32_bf16 v[102:105], v[14:17], v[206:209], v[66:69]
	s_waitcnt lgkmcnt(5)
	v_mfma_f32_16x16x32_bf16 v[66:69], v[18:21], v[2:5], v[118:121]
	s_waitcnt lgkmcnt(4)
	v_mfma_f32_16x16x32_bf16 v[82:85], v[22:25], v[6:9], v[66:69]
	v_mfma_f32_16x16x32_bf16 v[66:69], v[18:21], v[172:175], v[114:117]
	v_mfma_f32_16x16x32_bf16 v[86:89], v[22:25], v[206:209], v[66:69]
	s_waitcnt lgkmcnt(3)
	v_mfma_f32_16x16x32_bf16 v[66:69], v[26:29], v[2:5], v[110:113]
	s_waitcnt lgkmcnt(2)
	v_mfma_f32_16x16x32_bf16 v[74:77], v[30:33], v[6:9], v[66:69]
	v_mfma_f32_16x16x32_bf16 v[66:69], v[26:29], v[172:175], v[106:109]
	v_mfma_f32_16x16x32_bf16 v[78:81], v[30:33], v[206:209], v[66:69]
	s_waitcnt lgkmcnt(1)
	v_mfma_f32_16x16x32_bf16 v[66:69], v[212:215], v[2:5], v[130:133]
	v_mfma_f32_16x16x32_bf16 v[70:73], v[212:215], v[172:175], v[98:101]
	s_waitcnt lgkmcnt(0)
	v_mfma_f32_16x16x32_bf16 v[66:69], v[228:231], v[6:9], v[66:69]
	v_mfma_f32_16x16x32_bf16 v[70:73], v[228:231], v[206:209], v[70:73]
	s_barrier
	ds_read_b128 v[130:133], v178
	ds_read_b128 v[176:179], v179
	ds_read_b128 v[232:235], v180
	ds_read_b128 v[236:239], v181
	s_waitcnt vmcnt(0)
	s_barrier
	s_waitcnt lgkmcnt(0)
	s_waitcnt lgkmcnt(3)
	v_mfma_f32_16x16x32_bf16 v[98:101], v[10:13], v[130:133], v[216:219]
	s_waitcnt lgkmcnt(1)
	v_mfma_f32_16x16x32_bf16 v[10:13], v[10:13], v[232:235], v[90:93]
	s_waitcnt lgkmcnt(0)
	v_mfma_f32_16x16x32_bf16 v[126:129], v[14:17], v[236:239], v[10:13]
	v_mfma_f32_16x16x32_bf16 v[10:13], v[18:21], v[130:133], v[160:163]
	v_mfma_f32_16x16x32_bf16 v[114:117], v[22:25], v[176:179], v[10:13]
	v_mfma_f32_16x16x32_bf16 v[10:13], v[18:21], v[232:235], v[164:167]
	v_mfma_f32_16x16x32_bf16 v[118:121], v[22:25], v[236:239], v[10:13]
	v_mfma_f32_16x16x32_bf16 v[10:13], v[26:29], v[130:133], v[182:185]
	v_mfma_f32_16x16x32_bf16 v[106:109], v[30:33], v[176:179], v[10:13]
	v_mfma_f32_16x16x32_bf16 v[10:13], v[26:29], v[232:235], v[186:189]
	v_mfma_f32_16x16x32_bf16 v[110:113], v[30:33], v[236:239], v[10:13]
	v_mfma_f32_16x16x32_bf16 v[10:13], v[212:215], v[130:133], v[190:193]
	v_mfma_f32_16x16x32_bf16 v[90:93], v[228:231], v[176:179], v[10:13]
	v_mfma_f32_16x16x32_bf16 v[10:13], v[212:215], v[232:235], v[194:197]
	v_mfma_f32_16x16x32_bf16 v[122:125], v[14:17], v[176:179], v[98:101]
	v_mfma_f32_16x16x32_bf16 v[98:101], v[228:231], v[236:239], v[10:13]
	s_barrier
	ds_read_b128 v[160:163], v144 offset:49152
	ds_read_b128 v[164:167], v144 offset:50176
	ds_read_b128 v[180:183], v147 offset:49152
	ds_read_b128 v[184:187], v147 offset:50176
	ds_read_b128 v[188:191], v146 offset:49152
	ds_read_b128 v[192:195], v146 offset:50176
	ds_read_b128 v[212:215], v145 offset:49152
	ds_read_b128 v[142:145], v145 offset:50176
	s_barrier
	s_waitcnt lgkmcnt(0)
	s_waitcnt lgkmcnt(7)
	v_mfma_f32_16x16x32_bf16 v[10:13], v[160:163], v[2:5], v[62:65]
	s_waitcnt lgkmcnt(6)
	v_mfma_f32_16x16x32_bf16 v[26:29], v[164:167], v[6:9], v[10:13]
	v_mfma_f32_16x16x32_bf16 v[10:13], v[160:163], v[172:175], v[58:61]
	v_mfma_f32_16x16x32_bf16 v[30:33], v[164:167], v[206:209], v[10:13]
	s_waitcnt lgkmcnt(5)
	v_mfma_f32_16x16x32_bf16 v[10:13], v[180:183], v[2:5], v[54:57]
	s_waitcnt lgkmcnt(4)
	v_mfma_f32_16x16x32_bf16 v[18:21], v[184:187], v[6:9], v[10:13]
	v_mfma_f32_16x16x32_bf16 v[10:13], v[180:183], v[172:175], v[50:53]
	v_mfma_f32_16x16x32_bf16 v[22:25], v[184:187], v[206:209], v[10:13]
	s_waitcnt lgkmcnt(3)
	v_mfma_f32_16x16x32_bf16 v[10:13], v[188:191], v[2:5], v[46:49]
	s_waitcnt lgkmcnt(1)
	v_mfma_f32_16x16x32_bf16 v[2:5], v[212:215], v[2:5], v[38:41]
	v_mfma_f32_16x16x32_bf16 v[10:13], v[192:195], v[6:9], v[10:13]
	v_mfma_f32_16x16x32_bf16 v[14:17], v[188:191], v[172:175], v[42:45]
	s_waitcnt lgkmcnt(0)
	v_mfma_f32_16x16x32_bf16 v[2:5], v[142:145], v[6:9], v[2:5]
	v_mfma_f32_16x16x32_bf16 v[6:9], v[212:215], v[172:175], v[34:37]
	v_mfma_f32_16x16x32_bf16 v[14:17], v[192:195], v[206:209], v[14:17]
	v_mfma_f32_16x16x32_bf16 v[6:9], v[142:145], v[206:209], v[6:9]
	v_mfma_f32_16x16x32_bf16 v[34:37], v[160:163], v[130:133], v[134:137]
	v_mfma_f32_16x16x32_bf16 v[58:61], v[164:167], v[176:179], v[34:37]
	v_mfma_f32_16x16x32_bf16 v[34:37], v[160:163], v[232:235], v[148:151]
	v_mfma_f32_16x16x32_bf16 v[62:65], v[164:167], v[236:239], v[34:37]
	v_mfma_f32_16x16x32_bf16 v[34:37], v[180:183], v[130:133], v[152:155]
	v_mfma_f32_16x16x32_bf16 v[50:53], v[184:187], v[176:179], v[34:37]
	v_mfma_f32_16x16x32_bf16 v[34:37], v[180:183], v[232:235], v[156:159]
	v_mfma_f32_16x16x32_bf16 v[54:57], v[184:187], v[236:239], v[34:37]
	v_mfma_f32_16x16x32_bf16 v[34:37], v[188:191], v[130:133], v[202:205]
	v_mfma_f32_16x16x32_bf16 v[42:45], v[192:195], v[176:179], v[34:37]
	v_mfma_f32_16x16x32_bf16 v[34:37], v[188:191], v[232:235], v[224:227]
	v_mfma_f32_16x16x32_bf16 v[46:49], v[192:195], v[236:239], v[34:37]
	v_mfma_f32_16x16x32_bf16 v[34:37], v[212:215], v[130:133], v[168:171]
	v_mfma_f32_16x16x32_bf16 v[38:41], v[212:215], v[232:235], v[198:201]
	v_mfma_f32_16x16x32_bf16 v[34:37], v[142:145], v[176:179], v[34:37]
	v_mfma_f32_16x16x32_bf16 v[38:41], v[142:145], v[236:239], v[38:41]
	s_movk_i32 s4, 0x100
	v_cmp_gt_u32_e32 vcc, s4, v1
	s_barrier
	s_and_saveexec_b64 s[4:5], vcc
	s_cbranch_execz .LBB0_1356
	s_barrier

.LBB0_1491:
	v_or_b32_e32 v161, 0x10000, v157
	v_or_b32_e32 v163, 0x10000, v159
	v_or_b32_e32 v162, 0x10000, v158
	ds_read_b128 v[172:175], v161
	ds_read_b128 v[176:179], v162
	v_or_b32_e32 v164, 0x10000, v160
	ds_read_b128 v[180:183], v163
	ds_read_b128 v[184:187], v164
	s_add_u32 s43, s25, s22
	s_addc_u32 s45, s41, s23
	s_add_u32 s44, s43, 0x80
	v_add_u32_e32 v165, 0xc000, v139
	s_addc_u32 s45, s45, 0
	v_readfirstlane_b32 s43, v165
	ds_read_b128 v[188:191], v141
	ds_read_b128 v[192:195], v141 offset:1024
	ds_read_b128 v[196:199], v144
	ds_read_b128 v[200:203], v144 offset:1024
	ds_read_b128 v[204:207], v143
	ds_read_b128 v[212:215], v143 offset:1024
	ds_read_b128 v[216:219], v142
	ds_read_b128 v[224:227], v142 offset:1024
	s_mov_b32 m0, s43
	v_lshl_add_u64 v[166:167], s[44:45], 0, v[132:133]
	global_load_lds_dwordx4 v[166:167], off
	v_add_u32_e32 v166, 0xe000, v139
	v_lshl_add_u64 v[168:169], s[44:45], 0, v[130:131]
	v_readfirstlane_b32 s43, v166
	s_mov_b32 m0, s43
	s_nop 0
	global_load_lds_dwordx4 v[168:169], off
	s_waitcnt lgkmcnt(8)
	s_barrier
	s_waitcnt lgkmcnt(0)
	s_waitcnt lgkmcnt(0)
	v_mfma_f32_16x16x32_bf16 v[126:129], v[188:191], v[172:175], v[126:129]
	v_mfma_f32_16x16x32_bf16 v[122:125], v[188:191], v[180:183], v[122:125]
	v_mfma_f32_16x16x32_bf16 v[118:121], v[196:199], v[172:175], v[118:121]
	v_mfma_f32_16x16x32_bf16 v[114:117], v[196:199], v[180:183], v[114:117]
	v_mfma_f32_16x16x32_bf16 v[110:113], v[204:207], v[172:175], v[110:113]
	v_mfma_f32_16x16x32_bf16 v[106:109], v[204:207], v[180:183], v[106:109]
	v_mfma_f32_16x16x32_bf16 v[102:105], v[216:219], v[172:175], v[102:105]
	v_mfma_f32_16x16x32_bf16 v[98:101], v[216:219], v[180:183], v[98:101]
	v_mfma_f32_16x16x32_bf16 v[126:129], v[192:195], v[176:179], v[126:129]
	v_mfma_f32_16x16x32_bf16 v[122:125], v[192:195], v[184:187], v[122:125]
	v_mfma_f32_16x16x32_bf16 v[118:121], v[200:203], v[176:179], v[118:121]
	v_mfma_f32_16x16x32_bf16 v[114:117], v[200:203], v[184:187], v[114:117]
	v_mfma_f32_16x16x32_bf16 v[110:113], v[212:215], v[176:179], v[110:113]
	v_mfma_f32_16x16x32_bf16 v[106:109], v[212:215], v[184:187], v[106:109]
	v_mfma_f32_16x16x32_bf16 v[102:105], v[224:227], v[176:179], v[102:105]
	v_mfma_f32_16x16x32_bf16 v[98:101], v[224:227], v[184:187], v[98:101]
	s_barrier
	s_add_u32 s43, s14, s22
	s_addc_u32 s46, s15, s23
	s_add_u32 s44, s43, 0x100
	v_or_b32_e32 v167, 0x14000, v157
	v_or_b32_e32 v169, 0x14000, v159
	s_addc_u32 s45, s46, 0
	v_readfirstlane_b32 s47, v145
	v_or_b32_e32 v168, 0x14000, v158
	ds_read_b128 v[228:231], v167
	ds_read_b128 v[232:235], v168
	v_or_b32_e32 v170, 0x14000, v160
	ds_read_b128 v[236:239], v169
	ds_read_b128 v[240:243], v170
	s_mov_b32 m0, s47
	v_lshl_add_u64 v[208:209], s[44:45], 0, v[132:133]
	global_load_lds_dwordx4 v[208:209], off
	v_lshl_add_u64 v[208:209], s[44:45], 0, v[130:131]
	v_readfirstlane_b32 s44, v146
	s_mov_b32 m0, s44
	s_nop 0
	global_load_lds_dwordx4 v[208:209], off
	s_barrier
	s_waitcnt lgkmcnt(0)
	s_waitcnt lgkmcnt(0)
	v_mfma_f32_16x16x32_bf16 v[94:97], v[188:191], v[228:231], v[94:97]
	v_mfma_f32_16x16x32_bf16 v[90:93], v[188:191], v[236:239], v[90:93]
	v_mfma_f32_16x16x32_bf16 v[86:89], v[196:199], v[228:231], v[86:89]
	v_mfma_f32_16x16x32_bf16 v[82:85], v[196:199], v[236:239], v[82:85]
	v_mfma_f32_16x16x32_bf16 v[78:81], v[204:207], v[228:231], v[78:81]
	v_mfma_f32_16x16x32_bf16 v[74:77], v[204:207], v[236:239], v[74:77]
	v_mfma_f32_16x16x32_bf16 v[70:73], v[216:219], v[228:231], v[70:73]
	v_mfma_f32_16x16x32_bf16 v[66:69], v[216:219], v[236:239], v[66:69]
	v_mfma_f32_16x16x32_bf16 v[94:97], v[192:195], v[232:235], v[94:97]
	v_mfma_f32_16x16x32_bf16 v[90:93], v[192:195], v[240:243], v[90:93]
	v_mfma_f32_16x16x32_bf16 v[86:89], v[200:203], v[232:235], v[86:89]
	v_mfma_f32_16x16x32_bf16 v[82:85], v[200:203], v[240:243], v[82:85]
	v_mfma_f32_16x16x32_bf16 v[78:81], v[212:215], v[232:235], v[78:81]
	v_mfma_f32_16x16x32_bf16 v[74:77], v[212:215], v[240:243], v[74:77]
	v_mfma_f32_16x16x32_bf16 v[70:73], v[224:227], v[232:235], v[70:73]
	v_mfma_f32_16x16x32_bf16 v[66:69], v[224:227], v[240:243], v[66:69]
	s_add_u32 s47, s16, s22
	s_addc_u32 s50, s17, s23
	s_add_u32 s44, s47, 0x100
	s_addc_u32 s45, s50, 0
	v_readfirstlane_b32 s51, v139
	s_barrier
	ds_read_b128 v[188:191], v141 offset:16384
	ds_read_b128 v[192:195], v141 offset:17408
	ds_read_b128 v[196:199], v144 offset:16384
	ds_read_b128 v[200:203], v144 offset:17408
	ds_read_b128 v[204:207], v143 offset:16384
	ds_read_b128 v[212:215], v143 offset:17408
	ds_read_b128 v[216:219], v142 offset:16384
	ds_read_b128 v[224:227], v142 offset:17408
	s_mov_b32 m0, s51
	v_lshl_add_u64 v[208:209], s[44:45], 0, v[132:133]
	global_load_lds_dwordx4 v[208:209], off
	v_lshl_add_u64 v[208:209], s[44:45], 0, v[130:131]
	v_readfirstlane_b32 s44, v140
	s_mov_b32 m0, s44
	s_nop 0
	global_load_lds_dwordx4 v[208:209], off
	s_barrier
	s_waitcnt lgkmcnt(0)
	s_waitcnt lgkmcnt(0)
	v_mfma_f32_16x16x32_bf16 v[62:65], v[188:191], v[172:175], v[62:65]
	v_mfma_f32_16x16x32_bf16 v[58:61], v[188:191], v[180:183], v[58:61]
	v_mfma_f32_16x16x32_bf16 v[54:57], v[196:199], v[172:175], v[54:57]
	v_mfma_f32_16x16x32_bf16 v[50:53], v[196:199], v[180:183], v[50:53]
	v_mfma_f32_16x16x32_bf16 v[46:49], v[204:207], v[172:175], v[46:49]
	v_mfma_f32_16x16x32_bf16 v[42:45], v[204:207], v[180:183], v[42:45]
	v_mfma_f32_16x16x32_bf16 v[38:41], v[216:219], v[172:175], v[38:41]
	v_mfma_f32_16x16x32_bf16 v[34:37], v[216:219], v[180:183], v[34:37]
	v_mfma_f32_16x16x32_bf16 v[62:65], v[192:195], v[176:179], v[62:65]
	v_mfma_f32_16x16x32_bf16 v[58:61], v[192:195], v[184:187], v[58:61]
	v_mfma_f32_16x16x32_bf16 v[54:57], v[200:203], v[176:179], v[54:57]
	v_mfma_f32_16x16x32_bf16 v[50:53], v[200:203], v[184:187], v[50:53]
	v_mfma_f32_16x16x32_bf16 v[46:49], v[212:215], v[176:179], v[46:49]
	v_mfma_f32_16x16x32_bf16 v[42:45], v[212:215], v[184:187], v[42:45]
	v_mfma_f32_16x16x32_bf16 v[38:41], v[224:227], v[176:179], v[38:41]
	v_mfma_f32_16x16x32_bf16 v[34:37], v[224:227], v[184:187], v[34:37]
	s_barrier
	s_add_u32 s51, s18, s22
	s_addc_u32 s52, s19, s23
	s_add_u32 s44, s51, 0x100
	s_addc_u32 s45, s52, 0
	v_readfirstlane_b32 s53, v147
	s_mov_b32 m0, s53
	v_lshl_add_u64 v[172:173], s[44:45], 0, v[132:133]
	global_load_lds_dwordx4 v[172:173], off
	v_lshl_add_u64 v[172:173], s[44:45], 0, v[130:131]
	v_readfirstlane_b32 s44, v148
	s_mov_b32 m0, s44
	s_nop 0
	global_load_lds_dwordx4 v[172:173], off
	s_waitcnt vmcnt(6)
	s_barrier
	v_mfma_f32_16x16x32_bf16 v[30:33], v[188:191], v[228:231], v[30:33]
	v_mfma_f32_16x16x32_bf16 v[26:29], v[188:191], v[236:239], v[26:29]
	v_mfma_f32_16x16x32_bf16 v[22:25], v[196:199], v[228:231], v[22:25]
	v_mfma_f32_16x16x32_bf16 v[18:21], v[196:199], v[236:239], v[18:21]
	v_mfma_f32_16x16x32_bf16 v[14:17], v[204:207], v[228:231], v[14:17]
	v_mfma_f32_16x16x32_bf16 v[10:13], v[204:207], v[236:239], v[10:13]
	v_mfma_f32_16x16x32_bf16 v[6:9], v[216:219], v[228:231], v[6:9]
	v_mfma_f32_16x16x32_bf16 v[2:5], v[216:219], v[236:239], v[2:5]
	v_mfma_f32_16x16x32_bf16 v[30:33], v[192:195], v[232:235], v[30:33]
	v_mfma_f32_16x16x32_bf16 v[26:29], v[192:195], v[240:243], v[26:29]
	v_mfma_f32_16x16x32_bf16 v[22:25], v[200:203], v[232:235], v[22:25]
	v_mfma_f32_16x16x32_bf16 v[18:21], v[200:203], v[240:243], v[18:21]
	v_mfma_f32_16x16x32_bf16 v[14:17], v[212:215], v[232:235], v[14:17]
	v_mfma_f32_16x16x32_bf16 v[10:13], v[212:215], v[240:243], v[10:13]
	v_mfma_f32_16x16x32_bf16 v[6:9], v[224:227], v[232:235], v[6:9]
	v_mfma_f32_16x16x32_bf16 v[2:5], v[224:227], v[240:243], v[2:5]
	v_or_b32_e32 v171, 0x18000, v157
	v_or_b32_e32 v173, 0x18000, v159
	s_barrier
	v_or_b32_e32 v172, 0x18000, v158
	ds_read_b128 v[180:183], v171
	ds_read_b128 v[184:187], v172
	v_or_b32_e32 v174, 0x18000, v160
	ds_read_b128 v[188:191], v173
	ds_read_b128 v[192:195], v174
	s_add_u32 s44, s11, s22
	s_addc_u32 s45, s24, s23
	v_readfirstlane_b32 s53, v149
	ds_read_b128 v[196:199], v141 offset:32768
	ds_read_b128 v[200:203], v141 offset:33792
	ds_read_b128 v[204:207], v144 offset:32768
	ds_read_b128 v[212:215], v144 offset:33792
	ds_read_b128 v[216:219], v143 offset:32768
	ds_read_b128 v[224:227], v143 offset:33792
	ds_read_b128 v[228:231], v142 offset:32768
	ds_read_b128 v[232:235], v142 offset:33792
	s_mov_b32 m0, s53
	v_lshl_add_u64 v[176:177], s[44:45], 0, v[132:133]
	global_load_lds_dwordx4 v[176:177], off
	v_lshl_add_u64 v[176:177], s[44:45], 0, v[130:131]
	v_readfirstlane_b32 s44, v150
	s_mov_b32 m0, s44
	s_nop 0
	global_load_lds_dwordx4 v[176:177], off
	s_waitcnt lgkmcnt(8)
	s_barrier
	s_waitcnt lgkmcnt(0)
	s_waitcnt lgkmcnt(0)
	v_mfma_f32_16x16x32_bf16 v[126:129], v[196:199], v[180:183], v[126:129]
	v_mfma_f32_16x16x32_bf16 v[122:125], v[196:199], v[188:191], v[122:125]
	v_mfma_f32_16x16x32_bf16 v[118:121], v[204:207], v[180:183], v[118:121]
	v_mfma_f32_16x16x32_bf16 v[114:117], v[204:207], v[188:191], v[114:117]
	v_mfma_f32_16x16x32_bf16 v[110:113], v[216:219], v[180:183], v[110:113]
	v_mfma_f32_16x16x32_bf16 v[106:109], v[216:219], v[188:191], v[106:109]
	v_mfma_f32_16x16x32_bf16 v[102:105], v[228:231], v[180:183], v[102:105]
	v_mfma_f32_16x16x32_bf16 v[98:101], v[228:231], v[188:191], v[98:101]
	v_mfma_f32_16x16x32_bf16 v[126:129], v[200:203], v[184:187], v[126:129]
	v_mfma_f32_16x16x32_bf16 v[122:125], v[200:203], v[192:195], v[122:125]
	v_mfma_f32_16x16x32_bf16 v[118:121], v[212:215], v[184:187], v[118:121]
	v_mfma_f32_16x16x32_bf16 v[114:117], v[212:215], v[192:195], v[114:117]
	v_mfma_f32_16x16x32_bf16 v[110:113], v[224:227], v[184:187], v[110:113]
	v_mfma_f32_16x16x32_bf16 v[106:109], v[224:227], v[192:195], v[106:109]
	v_mfma_f32_16x16x32_bf16 v[102:105], v[232:235], v[184:187], v[102:105]
	v_mfma_f32_16x16x32_bf16 v[98:101], v[232:235], v[192:195], v[98:101]
	s_barrier
	s_add_u32 s44, s43, 0x180
	v_or_b32_e32 v175, 0x1c000, v157
	v_or_b32_e32 v177, 0x1c000, v159
	s_addc_u32 s45, s46, 0
	v_readfirstlane_b32 s43, v151
	v_or_b32_e32 v176, 0x1c000, v158
	ds_read_b128 v[236:239], v175
	ds_read_b128 v[240:243], v176
	v_or_b32_e32 v178, 0x1c000, v160
	ds_read_b128 v[244:247], v177
	ds_read_b128 v[248:251], v178
	s_mov_b32 m0, s43
	v_lshl_add_u64 v[208:209], s[44:45], 0, v[132:133]
	v_readfirstlane_b32 s43, v152
	global_load_lds_dwordx4 v[208:209], off
	v_lshl_add_u64 v[208:209], s[44:45], 0, v[130:131]
	s_mov_b32 m0, s43
	s_nop 0
	global_load_lds_dwordx4 v[208:209], off
	s_barrier
	s_waitcnt lgkmcnt(0)
	s_waitcnt lgkmcnt(0)
	v_mfma_f32_16x16x32_bf16 v[94:97], v[196:199], v[236:239], v[94:97]
	v_mfma_f32_16x16x32_bf16 v[90:93], v[196:199], v[244:247], v[90:93]
	v_mfma_f32_16x16x32_bf16 v[86:89], v[204:207], v[236:239], v[86:89]
	v_mfma_f32_16x16x32_bf16 v[82:85], v[204:207], v[244:247], v[82:85]
	v_mfma_f32_16x16x32_bf16 v[78:81], v[216:219], v[236:239], v[78:81]
	v_mfma_f32_16x16x32_bf16 v[74:77], v[216:219], v[244:247], v[74:77]
	v_mfma_f32_16x16x32_bf16 v[70:73], v[228:231], v[236:239], v[70:73]
	v_mfma_f32_16x16x32_bf16 v[66:69], v[228:231], v[244:247], v[66:69]
	v_mfma_f32_16x16x32_bf16 v[94:97], v[200:203], v[240:243], v[94:97]
	v_mfma_f32_16x16x32_bf16 v[90:93], v[200:203], v[248:251], v[90:93]
	v_mfma_f32_16x16x32_bf16 v[86:89], v[212:215], v[240:243], v[86:89]
	v_mfma_f32_16x16x32_bf16 v[82:85], v[212:215], v[248:251], v[82:85]
	v_mfma_f32_16x16x32_bf16 v[78:81], v[224:227], v[240:243], v[78:81]
	v_mfma_f32_16x16x32_bf16 v[74:77], v[224:227], v[248:251], v[74:77]
	v_mfma_f32_16x16x32_bf16 v[70:73], v[232:235], v[240:243], v[70:73]
	v_mfma_f32_16x16x32_bf16 v[66:69], v[232:235], v[248:251], v[66:69]
	s_add_u32 s44, s47, 0x180
	s_addc_u32 s45, s50, 0
	v_readfirstlane_b32 s43, v153
	s_barrier
	ds_read_b128 v[196:199], v141 offset:49152
	ds_read_b128 v[200:203], v141 offset:50176
	ds_read_b128 v[204:207], v144 offset:49152
	ds_read_b128 v[212:215], v144 offset:50176
	ds_read_b128 v[216:219], v143 offset:49152
	ds_read_b128 v[224:227], v143 offset:50176
	ds_read_b128 v[228:231], v142 offset:49152
	ds_read_b128 v[232:235], v142 offset:50176
	s_mov_b32 m0, s43
	v_lshl_add_u64 v[208:209], s[44:45], 0, v[132:133]
	v_readfirstlane_b32 s43, v154
	global_load_lds_dwordx4 v[208:209], off
	v_lshl_add_u64 v[208:209], s[44:45], 0, v[130:131]
	s_mov_b32 m0, s43
	s_nop 0
	global_load_lds_dwordx4 v[208:209], off
	s_barrier
	s_waitcnt lgkmcnt(0)
	s_waitcnt lgkmcnt(0)
	v_mfma_f32_16x16x32_bf16 v[62:65], v[196:199], v[180:183], v[62:65]
	v_mfma_f32_16x16x32_bf16 v[58:61], v[196:199], v[188:191], v[58:61]
	v_mfma_f32_16x16x32_bf16 v[54:57], v[204:207], v[180:183], v[54:57]
	v_mfma_f32_16x16x32_bf16 v[50:53], v[204:207], v[188:191], v[50:53]
	v_mfma_f32_16x16x32_bf16 v[46:49], v[216:219], v[180:183], v[46:49]
	v_mfma_f32_16x16x32_bf16 v[42:45], v[216:219], v[188:191], v[42:45]
	v_mfma_f32_16x16x32_bf16 v[38:41], v[228:231], v[180:183], v[38:41]
	v_mfma_f32_16x16x32_bf16 v[34:37], v[228:231], v[188:191], v[34:37]
	v_mfma_f32_16x16x32_bf16 v[62:65], v[200:203], v[184:187], v[62:65]
	v_mfma_f32_16x16x32_bf16 v[58:61], v[200:203], v[192:195], v[58:61]
	v_mfma_f32_16x16x32_bf16 v[54:57], v[212:215], v[184:187], v[54:57]
	v_mfma_f32_16x16x32_bf16 v[50:53], v[212:215], v[192:195], v[50:53]
	v_mfma_f32_16x16x32_bf16 v[46:49], v[224:227], v[184:187], v[46:49]
	v_mfma_f32_16x16x32_bf16 v[42:45], v[224:227], v[192:195], v[42:45]
	v_mfma_f32_16x16x32_bf16 v[38:41], v[232:235], v[184:187], v[38:41]
	v_mfma_f32_16x16x32_bf16 v[34:37], v[232:235], v[192:195], v[34:37]
	s_barrier
	s_add_u32 s44, s51, 0x180
	s_addc_u32 s45, s52, 0
	v_readfirstlane_b32 s43, v155
	s_mov_b32 m0, s43
	v_lshl_add_u64 v[180:181], s[44:45], 0, v[132:133]
	v_readfirstlane_b32 s43, v156
	global_load_lds_dwordx4 v[180:181], off
	v_lshl_add_u64 v[180:181], s[44:45], 0, v[130:131]
	s_mov_b32 m0, s43
	s_nop 0
	global_load_lds_dwordx4 v[180:181], off
	s_waitcnt vmcnt(6)
	s_barrier
	v_mfma_f32_16x16x32_bf16 v[30:33], v[196:199], v[236:239], v[30:33]
	v_mfma_f32_16x16x32_bf16 v[26:29], v[196:199], v[244:247], v[26:29]
	v_mfma_f32_16x16x32_bf16 v[22:25], v[204:207], v[236:239], v[22:25]
	v_mfma_f32_16x16x32_bf16 v[18:21], v[204:207], v[244:247], v[18:21]
	v_mfma_f32_16x16x32_bf16 v[14:17], v[216:219], v[236:239], v[14:17]
	v_mfma_f32_16x16x32_bf16 v[10:13], v[216:219], v[244:247], v[10:13]
	v_mfma_f32_16x16x32_bf16 v[6:9], v[228:231], v[236:239], v[6:9]
	v_mfma_f32_16x16x32_bf16 v[2:5], v[228:231], v[244:247], v[2:5]
	v_mfma_f32_16x16x32_bf16 v[30:33], v[200:203], v[240:243], v[30:33]
	v_mfma_f32_16x16x32_bf16 v[26:29], v[200:203], v[248:251], v[26:29]
	v_mfma_f32_16x16x32_bf16 v[22:25], v[212:215], v[240:243], v[22:25]
	v_mfma_f32_16x16x32_bf16 v[18:21], v[212:215], v[248:251], v[18:21]
	v_mfma_f32_16x16x32_bf16 v[14:17], v[224:227], v[240:243], v[14:17]
	v_mfma_f32_16x16x32_bf16 v[10:13], v[224:227], v[248:251], v[10:13]
	v_mfma_f32_16x16x32_bf16 v[6:9], v[232:235], v[240:243], v[6:9]
	v_mfma_f32_16x16x32_bf16 v[2:5], v[232:235], v[248:251], v[2:5]
	s_add_i32 s42, s42, 2
	s_add_u32 s22, s22, 0x100
	s_addc_u32 s23, s23, 0
	s_cmp_lt_u32 s42, 12
	s_barrier
	s_cbranch_scc1 .LBB0_1491
	s_add_u32 s14, s20, 0x780
	s_addc_u32 s15, s21, 0
	v_readfirstlane_b32 s11, v165
	ds_read_b128 v[146:149], v161
	ds_read_b128 v[150:153], v162
	ds_read_b128 v[154:157], v163
	ds_read_b128 v[158:161], v164
	ds_read_b128 v[180:183], v141
	ds_read_b128 v[184:187], v141 offset:1024
	ds_read_b128 v[188:191], v144
	ds_read_b128 v[192:195], v144 offset:1024
	ds_read_b128 v[196:199], v143
	ds_read_b128 v[200:203], v143 offset:1024
	ds_read_b128 v[204:207], v142
	ds_read_b128 v[212:215], v142 offset:1024
	s_mov_b32 m0, s11
	v_lshl_add_u64 v[132:133], s[14:15], 0, v[132:133]
	v_readfirstlane_b32 s11, v166
	global_load_lds_dwordx4 v[132:133], off
	v_lshl_add_u64 v[130:131], s[14:15], 0, v[130:131]
	s_mov_b32 m0, s11
	s_nop 0
	global_load_lds_dwordx4 v[130:131], off
	s_barrier
	s_waitcnt lgkmcnt(0)
	s_waitcnt lgkmcnt(0)
	v_mfma_f32_16x16x32_bf16 v[126:129], v[180:183], v[146:149], v[126:129]
	v_mfma_f32_16x16x32_bf16 v[122:125], v[180:183], v[154:157], v[122:125]
	v_mfma_f32_16x16x32_bf16 v[110:113], v[196:199], v[146:149], v[110:113]
	v_mfma_f32_16x16x32_bf16 v[106:109], v[196:199], v[154:157], v[106:109]
	v_mfma_f32_16x16x32_bf16 v[126:129], v[184:187], v[150:153], v[126:129]
	v_mfma_f32_16x16x32_bf16 v[122:125], v[184:187], v[158:161], v[122:125]
	v_mfma_f32_16x16x32_bf16 v[118:121], v[188:191], v[146:149], v[118:121]
	v_mfma_f32_16x16x32_bf16 v[114:117], v[188:191], v[154:157], v[114:117]
	v_mfma_f32_16x16x32_bf16 v[110:113], v[200:203], v[150:153], v[110:113]
	v_mfma_f32_16x16x32_bf16 v[106:109], v[200:203], v[158:161], v[106:109]
	v_mfma_f32_16x16x32_bf16 v[102:105], v[204:207], v[146:149], v[102:105]
	v_mfma_f32_16x16x32_bf16 v[98:101], v[204:207], v[154:157], v[98:101]
	v_mfma_f32_16x16x32_bf16 v[130:133], v[192:195], v[150:153], v[118:121]
	v_mfma_f32_16x16x32_bf16 v[162:165], v[192:195], v[158:161], v[114:117]
	v_mfma_f32_16x16x32_bf16 v[216:219], v[212:215], v[150:153], v[102:105]
	v_mfma_f32_16x16x32_bf16 v[224:227], v[212:215], v[158:161], v[98:101]
	s_barrier
	s_nop 0
	ds_read_b128 v[98:101], v167
	ds_read_b128 v[102:105], v168
	ds_read_b128 v[114:117], v169
	ds_read_b128 v[118:121], v170
	s_barrier
	s_waitcnt lgkmcnt(0)
	s_waitcnt lgkmcnt(3)
	v_mfma_f32_16x16x32_bf16 v[94:97], v[180:183], v[98:101], v[94:97]
	s_waitcnt lgkmcnt(1)
	v_mfma_f32_16x16x32_bf16 v[90:93], v[180:183], v[114:117], v[90:93]
	v_mfma_f32_16x16x32_bf16 v[78:81], v[196:199], v[98:101], v[78:81]
	v_mfma_f32_16x16x32_bf16 v[74:77], v[196:199], v[114:117], v[74:77]
	v_mfma_f32_16x16x32_bf16 v[94:97], v[184:187], v[102:105], v[94:97]
	s_waitcnt lgkmcnt(0)
	v_mfma_f32_16x16x32_bf16 v[90:93], v[184:187], v[118:121], v[90:93]
	v_mfma_f32_16x16x32_bf16 v[86:89], v[188:191], v[98:101], v[86:89]
	v_mfma_f32_16x16x32_bf16 v[82:85], v[188:191], v[114:117], v[82:85]
	v_mfma_f32_16x16x32_bf16 v[78:81], v[200:203], v[102:105], v[78:81]
	v_mfma_f32_16x16x32_bf16 v[74:77], v[200:203], v[118:121], v[74:77]
	v_mfma_f32_16x16x32_bf16 v[70:73], v[204:207], v[98:101], v[70:73]
	v_mfma_f32_16x16x32_bf16 v[66:69], v[204:207], v[114:117], v[66:69]
	v_mfma_f32_16x16x32_bf16 v[166:169], v[192:195], v[102:105], v[86:89]
	v_mfma_f32_16x16x32_bf16 v[180:183], v[192:195], v[118:121], v[82:85]
	v_mfma_f32_16x16x32_bf16 v[184:187], v[212:215], v[102:105], v[70:73]
	v_mfma_f32_16x16x32_bf16 v[188:191], v[212:215], v[118:121], v[66:69]
	s_barrier
	s_nop 1
	ds_read_b128 v[66:69], v141 offset:16384
	ds_read_b128 v[70:73], v141 offset:17408
	ds_read_b128 v[82:85], v144 offset:16384
	ds_read_b128 v[86:89], v144 offset:17408
	ds_read_b128 v[192:195], v143 offset:16384
	ds_read_b128 v[196:199], v143 offset:17408
	ds_read_b128 v[200:203], v142 offset:16384
	ds_read_b128 v[204:207], v142 offset:17408
	s_waitcnt vmcnt(4)
	s_barrier
	s_waitcnt lgkmcnt(0)
	s_waitcnt lgkmcnt(7)
	v_mfma_f32_16x16x32_bf16 v[62:65], v[66:69], v[146:149], v[62:65]
	v_mfma_f32_16x16x32_bf16 v[58:61], v[66:69], v[154:157], v[58:61]
	s_waitcnt lgkmcnt(3)
	v_mfma_f32_16x16x32_bf16 v[46:49], v[192:195], v[146:149], v[46:49]
	v_mfma_f32_16x16x32_bf16 v[42:45], v[192:195], v[154:157], v[42:45]
	v_mfma_f32_16x16x32_bf16 v[62:65], v[70:73], v[150:153], v[62:65]
	v_mfma_f32_16x16x32_bf16 v[58:61], v[70:73], v[158:161], v[58:61]
	v_mfma_f32_16x16x32_bf16 v[54:57], v[82:85], v[146:149], v[54:57]
	v_mfma_f32_16x16x32_bf16 v[50:53], v[82:85], v[154:157], v[50:53]
	s_waitcnt lgkmcnt(2)
	v_mfma_f32_16x16x32_bf16 v[46:49], v[196:199], v[150:153], v[46:49]
	v_mfma_f32_16x16x32_bf16 v[42:45], v[196:199], v[158:161], v[42:45]
	s_waitcnt lgkmcnt(1)
	v_mfma_f32_16x16x32_bf16 v[38:41], v[200:203], v[146:149], v[38:41]
	v_mfma_f32_16x16x32_bf16 v[34:37], v[200:203], v[154:157], v[34:37]
	v_mfma_f32_16x16x32_bf16 v[212:215], v[86:89], v[150:153], v[54:57]
	v_mfma_f32_16x16x32_bf16 v[228:231], v[86:89], v[158:161], v[50:53]
	s_waitcnt lgkmcnt(0)
	v_mfma_f32_16x16x32_bf16 v[146:149], v[204:207], v[150:153], v[38:41]
	v_mfma_f32_16x16x32_bf16 v[150:153], v[204:207], v[158:161], v[34:37]
	v_mfma_f32_16x16x32_bf16 v[30:33], v[66:69], v[98:101], v[30:33]
	v_mfma_f32_16x16x32_bf16 v[26:29], v[66:69], v[114:117], v[26:29]
	v_mfma_f32_16x16x32_bf16 v[14:17], v[192:195], v[98:101], v[14:17]
	v_mfma_f32_16x16x32_bf16 v[10:13], v[192:195], v[114:117], v[10:13]
	v_mfma_f32_16x16x32_bf16 v[30:33], v[70:73], v[102:105], v[30:33]
	v_mfma_f32_16x16x32_bf16 v[26:29], v[70:73], v[118:121], v[26:29]
	v_mfma_f32_16x16x32_bf16 v[22:25], v[82:85], v[98:101], v[22:25]
	v_mfma_f32_16x16x32_bf16 v[18:21], v[82:85], v[114:117], v[18:21]
	v_mfma_f32_16x16x32_bf16 v[14:17], v[196:199], v[102:105], v[14:17]
	v_mfma_f32_16x16x32_bf16 v[10:13], v[196:199], v[118:121], v[10:13]
	v_mfma_f32_16x16x32_bf16 v[6:9], v[200:203], v[98:101], v[6:9]
	v_mfma_f32_16x16x32_bf16 v[2:5], v[200:203], v[114:117], v[2:5]
	v_mfma_f32_16x16x32_bf16 v[154:157], v[86:89], v[102:105], v[22:25]
	v_mfma_f32_16x16x32_bf16 v[158:161], v[86:89], v[118:121], v[18:21]
	v_mfma_f32_16x16x32_bf16 v[192:195], v[204:207], v[102:105], v[6:9]
	v_mfma_f32_16x16x32_bf16 v[196:199], v[204:207], v[118:121], v[2:5]
	s_barrier
	s_nop 1
	ds_read_b128 v[2:5], v171
	ds_read_b128 v[6:9], v172
	ds_read_b128 v[170:173], v173
	ds_read_b128 v[200:203], v174
	ds_read_b128 v[18:21], v141 offset:32768
	ds_read_b128 v[22:25], v141 offset:33792
	ds_read_b128 v[34:37], v144 offset:32768
	ds_read_b128 v[38:41], v144 offset:33792
	ds_read_b128 v[50:53], v143 offset:32768
	ds_read_b128 v[54:57], v143 offset:33792
	ds_read_b128 v[204:207], v142 offset:32768
	ds_read_b128 v[232:235], v142 offset:33792
	s_waitcnt vmcnt(2)
	s_barrier
	s_waitcnt lgkmcnt(0)
	s_waitcnt lgkmcnt(7)
	v_mfma_f32_16x16x32_bf16 v[66:69], v[18:21], v[2:5], v[126:129]
	s_waitcnt lgkmcnt(6)
	v_mfma_f32_16x16x32_bf16 v[114:117], v[22:25], v[6:9], v[66:69]
	v_mfma_f32_16x16x32_bf16 v[66:69], v[18:21], v[170:173], v[122:125]
	v_mfma_f32_16x16x32_bf16 v[118:121], v[22:25], v[200:203], v[66:69]
	s_waitcnt lgkmcnt(5)
	v_mfma_f32_16x16x32_bf16 v[66:69], v[34:37], v[2:5], v[130:133]
	s_waitcnt lgkmcnt(4)
	v_mfma_f32_16x16x32_bf16 v[98:101], v[38:41], v[6:9], v[66:69]
	v_mfma_f32_16x16x32_bf16 v[66:69], v[34:37], v[170:173], v[162:165]
	v_mfma_f32_16x16x32_bf16 v[102:105], v[38:41], v[200:203], v[66:69]
	s_waitcnt lgkmcnt(3)
	v_mfma_f32_16x16x32_bf16 v[66:69], v[50:53], v[2:5], v[110:113]
	s_waitcnt lgkmcnt(2)
	v_mfma_f32_16x16x32_bf16 v[82:85], v[54:57], v[6:9], v[66:69]
	v_mfma_f32_16x16x32_bf16 v[66:69], v[50:53], v[170:173], v[106:109]
	v_mfma_f32_16x16x32_bf16 v[86:89], v[54:57], v[200:203], v[66:69]
	s_waitcnt lgkmcnt(1)
	v_mfma_f32_16x16x32_bf16 v[66:69], v[204:207], v[2:5], v[216:219]
	v_mfma_f32_16x16x32_bf16 v[70:73], v[204:207], v[170:173], v[224:227]
	s_waitcnt lgkmcnt(0)
	v_mfma_f32_16x16x32_bf16 v[66:69], v[232:235], v[6:9], v[66:69]
	v_mfma_f32_16x16x32_bf16 v[70:73], v[232:235], v[200:203], v[70:73]
	s_barrier
	ds_read_b128 v[130:133], v175
	ds_read_b128 v[162:165], v176
	ds_read_b128 v[174:177], v177
	ds_read_b128 v[216:219], v178
	s_waitcnt vmcnt(0)
	s_barrier
	s_waitcnt lgkmcnt(0)
	s_waitcnt lgkmcnt(3)
	v_mfma_f32_16x16x32_bf16 v[94:97], v[18:21], v[130:133], v[94:97]
	s_waitcnt lgkmcnt(1)
	v_mfma_f32_16x16x32_bf16 v[18:21], v[18:21], v[174:177], v[90:93]
	s_waitcnt lgkmcnt(0)
	v_mfma_f32_16x16x32_bf16 v[126:129], v[22:25], v[216:219], v[18:21]
	v_mfma_f32_16x16x32_bf16 v[18:21], v[34:37], v[130:133], v[166:169]
	v_mfma_f32_16x16x32_bf16 v[106:109], v[38:41], v[162:165], v[18:21]
	v_mfma_f32_16x16x32_bf16 v[18:21], v[34:37], v[174:177], v[180:183]
	v_mfma_f32_16x16x32_bf16 v[110:113], v[38:41], v[216:219], v[18:21]
	v_mfma_f32_16x16x32_bf16 v[18:21], v[50:53], v[130:133], v[78:81]
	v_mfma_f32_16x16x32_bf16 v[90:93], v[54:57], v[162:165], v[18:21]
	v_mfma_f32_16x16x32_bf16 v[18:21], v[50:53], v[174:177], v[74:77]
	v_mfma_f32_16x16x32_bf16 v[122:125], v[22:25], v[162:165], v[94:97]
	v_mfma_f32_16x16x32_bf16 v[94:97], v[54:57], v[216:219], v[18:21]
	v_mfma_f32_16x16x32_bf16 v[18:21], v[204:207], v[130:133], v[184:187]
	v_mfma_f32_16x16x32_bf16 v[74:77], v[232:235], v[162:165], v[18:21]
	v_mfma_f32_16x16x32_bf16 v[18:21], v[204:207], v[174:177], v[188:191]
	v_mfma_f32_16x16x32_bf16 v[78:81], v[232:235], v[216:219], v[18:21]
	s_barrier
	ds_read_b128 v[166:169], v141 offset:49152
	ds_read_b128 v[178:181], v141 offset:50176
	ds_read_b128 v[182:185], v144 offset:49152
	ds_read_b128 v[186:189], v144 offset:50176
	ds_read_b128 v[204:207], v143 offset:49152
	ds_read_b128 v[224:227], v143 offset:50176
	ds_read_b128 v[232:235], v142 offset:49152
	ds_read_b128 v[140:143], v142 offset:50176
	s_barrier
	s_waitcnt lgkmcnt(0)
	s_waitcnt lgkmcnt(7)
	v_mfma_f32_16x16x32_bf16 v[18:21], v[166:169], v[2:5], v[62:65]
	s_waitcnt lgkmcnt(6)
	v_mfma_f32_16x16x32_bf16 v[50:53], v[178:181], v[6:9], v[18:21]
	v_mfma_f32_16x16x32_bf16 v[18:21], v[166:169], v[170:173], v[58:61]
	v_mfma_f32_16x16x32_bf16 v[54:57], v[178:181], v[200:203], v[18:21]
	s_waitcnt lgkmcnt(5)
	v_mfma_f32_16x16x32_bf16 v[18:21], v[182:185], v[2:5], v[212:215]
	s_waitcnt lgkmcnt(4)
	v_mfma_f32_16x16x32_bf16 v[34:37], v[186:189], v[6:9], v[18:21]
	v_mfma_f32_16x16x32_bf16 v[18:21], v[182:185], v[170:173], v[228:231]
	v_mfma_f32_16x16x32_bf16 v[38:41], v[186:189], v[200:203], v[18:21]
	s_waitcnt lgkmcnt(3)
	v_mfma_f32_16x16x32_bf16 v[18:21], v[204:207], v[2:5], v[46:49]
	s_waitcnt lgkmcnt(1)
	v_mfma_f32_16x16x32_bf16 v[2:5], v[232:235], v[2:5], v[146:149]
	v_mfma_f32_16x16x32_bf16 v[18:21], v[224:227], v[6:9], v[18:21]
	v_mfma_f32_16x16x32_bf16 v[22:25], v[204:207], v[170:173], v[42:45]
	s_waitcnt lgkmcnt(0)
	v_mfma_f32_16x16x32_bf16 v[2:5], v[140:143], v[6:9], v[2:5]
	v_mfma_f32_16x16x32_bf16 v[6:9], v[232:235], v[170:173], v[150:153]
	v_mfma_f32_16x16x32_bf16 v[22:25], v[224:227], v[200:203], v[22:25]
	v_mfma_f32_16x16x32_bf16 v[6:9], v[140:143], v[200:203], v[6:9]
	v_mfma_f32_16x16x32_bf16 v[26:29], v[166:169], v[174:177], v[26:29]
	v_mfma_f32_16x16x32_bf16 v[62:65], v[178:181], v[216:219], v[26:29]
	v_mfma_f32_16x16x32_bf16 v[26:29], v[182:185], v[130:133], v[154:157]
	v_mfma_f32_16x16x32_bf16 v[30:33], v[166:169], v[130:133], v[30:33]
	v_mfma_f32_16x16x32_bf16 v[42:45], v[186:189], v[162:165], v[26:29]
	v_mfma_f32_16x16x32_bf16 v[26:29], v[182:185], v[174:177], v[158:161]
	v_mfma_f32_16x16x32_bf16 v[14:17], v[204:207], v[130:133], v[14:17]
	v_mfma_f32_16x16x32_bf16 v[10:13], v[204:207], v[174:177], v[10:13]
	v_mfma_f32_16x16x32_bf16 v[58:61], v[178:181], v[162:165], v[30:33]
	v_mfma_f32_16x16x32_bf16 v[46:49], v[186:189], v[216:219], v[26:29]
	v_mfma_f32_16x16x32_bf16 v[26:29], v[224:227], v[162:165], v[14:17]
	v_mfma_f32_16x16x32_bf16 v[30:33], v[224:227], v[216:219], v[10:13]
	v_mfma_f32_16x16x32_bf16 v[10:13], v[232:235], v[130:133], v[192:195]
	v_mfma_f32_16x16x32_bf16 v[14:17], v[232:235], v[174:177], v[196:199]
	v_mfma_f32_16x16x32_bf16 v[10:13], v[140:143], v[162:165], v[10:13]
	v_mfma_f32_16x16x32_bf16 v[14:17], v[140:143], v[216:219], v[14:17]
	s_movk_i32 s11, 0x100
	v_cmp_gt_u32_e32 vcc, s11, v134
	s_barrier
	s_and_saveexec_b64 s[14:15], vcc
	s_cbranch_execz .LBB0_1494
	s_barrier

.LBB0_1733:
	v_or_b32_e32 v160, 0x10000, v156
	v_or_b32_e32 v162, 0x10000, v158
	v_or_b32_e32 v161, 0x10000, v157
	ds_read_b128 v[170:173], v160
	ds_read_b128 v[174:177], v161
	v_or_b32_e32 v163, 0x10000, v159
	ds_read_b128 v[178:181], v162
	ds_read_b128 v[182:185], v163
	s_add_u32 s25, s17, s14
	s_addc_u32 s27, s23, s15
	s_add_u32 s26, s25, 0x80
	v_add_u32_e32 v164, 0xc000, v138
	s_addc_u32 s27, s27, 0
	v_readfirstlane_b32 s25, v164
	v_add_u32_e32 v165, 0xe000, v138
	ds_read_b128 v[186:189], v140
	ds_read_b128 v[190:193], v140 offset:1024
	ds_read_b128 v[194:197], v143
	ds_read_b128 v[198:201], v143 offset:1024
	ds_read_b128 v[202:205], v142
	ds_read_b128 v[206:209], v142 offset:1024
	ds_read_b128 v[212:215], v141
	ds_read_b128 v[216:219], v141 offset:1024
	s_mov_b32 m0, s25
	v_lshl_add_u64 v[166:167], s[26:27], 0, v[132:133]
	v_readfirstlane_b32 s25, v165
	global_load_lds_dwordx4 v[166:167], off
	v_lshl_add_u64 v[166:167], s[26:27], 0, v[130:131]
	s_mov_b32 m0, s25
	s_nop 0
	global_load_lds_dwordx4 v[166:167], off
	s_waitcnt lgkmcnt(8)
	s_barrier
	s_waitcnt lgkmcnt(0)
	s_waitcnt lgkmcnt(0)
	v_mfma_f32_16x16x32_bf16 v[126:129], v[186:189], v[170:173], v[126:129]
	v_mfma_f32_16x16x32_bf16 v[122:125], v[186:189], v[178:181], v[122:125]
	v_mfma_f32_16x16x32_bf16 v[118:121], v[194:197], v[170:173], v[118:121]
	v_mfma_f32_16x16x32_bf16 v[114:117], v[194:197], v[178:181], v[114:117]
	v_mfma_f32_16x16x32_bf16 v[110:113], v[202:205], v[170:173], v[110:113]
	v_mfma_f32_16x16x32_bf16 v[106:109], v[202:205], v[178:181], v[106:109]
	v_mfma_f32_16x16x32_bf16 v[102:105], v[212:215], v[170:173], v[102:105]
	v_mfma_f32_16x16x32_bf16 v[98:101], v[212:215], v[178:181], v[98:101]
	v_mfma_f32_16x16x32_bf16 v[126:129], v[190:193], v[174:177], v[126:129]
	v_mfma_f32_16x16x32_bf16 v[122:125], v[190:193], v[182:185], v[122:125]
	v_mfma_f32_16x16x32_bf16 v[118:121], v[198:201], v[174:177], v[118:121]
	v_mfma_f32_16x16x32_bf16 v[114:117], v[198:201], v[182:185], v[114:117]
	v_mfma_f32_16x16x32_bf16 v[110:113], v[206:209], v[174:177], v[110:113]
	v_mfma_f32_16x16x32_bf16 v[106:109], v[206:209], v[182:185], v[106:109]
	v_mfma_f32_16x16x32_bf16 v[102:105], v[216:219], v[174:177], v[102:105]
	v_mfma_f32_16x16x32_bf16 v[98:101], v[216:219], v[182:185], v[98:101]
	s_barrier
	s_add_u32 s25, s6, s14
	s_addc_u32 s28, s7, s15
	s_add_u32 s26, s25, 0x100
	v_or_b32_e32 v166, 0x14000, v156
	v_or_b32_e32 v168, 0x14000, v158
	s_addc_u32 s27, s28, 0
	v_readfirstlane_b32 s29, v144
	v_or_b32_e32 v167, 0x14000, v157
	ds_read_b128 v[224:227], v166
	ds_read_b128 v[228:231], v167
	v_or_b32_e32 v169, 0x14000, v159
	ds_read_b128 v[232:235], v168
	ds_read_b128 v[236:239], v169
	s_mov_b32 m0, s29
	v_lshl_add_u64 v[240:241], s[26:27], 0, v[132:133]
	global_load_lds_dwordx4 v[240:241], off
	v_lshl_add_u64 v[240:241], s[26:27], 0, v[130:131]
	v_readfirstlane_b32 s26, v145
	s_mov_b32 m0, s26
	s_nop 0
	global_load_lds_dwordx4 v[240:241], off
	s_barrier
	s_waitcnt lgkmcnt(0)
	s_waitcnt lgkmcnt(0)
	v_mfma_f32_16x16x32_bf16 v[94:97], v[186:189], v[224:227], v[94:97]
	v_mfma_f32_16x16x32_bf16 v[90:93], v[186:189], v[232:235], v[90:93]
	v_mfma_f32_16x16x32_bf16 v[86:89], v[194:197], v[224:227], v[86:89]
	v_mfma_f32_16x16x32_bf16 v[82:85], v[194:197], v[232:235], v[82:85]
	v_mfma_f32_16x16x32_bf16 v[78:81], v[202:205], v[224:227], v[78:81]
	v_mfma_f32_16x16x32_bf16 v[74:77], v[202:205], v[232:235], v[74:77]
	v_mfma_f32_16x16x32_bf16 v[70:73], v[212:215], v[224:227], v[70:73]
	v_mfma_f32_16x16x32_bf16 v[66:69], v[212:215], v[232:235], v[66:69]
	v_mfma_f32_16x16x32_bf16 v[94:97], v[190:193], v[228:231], v[94:97]
	v_mfma_f32_16x16x32_bf16 v[90:93], v[190:193], v[236:239], v[90:93]
	v_mfma_f32_16x16x32_bf16 v[86:89], v[198:201], v[228:231], v[86:89]
	v_mfma_f32_16x16x32_bf16 v[82:85], v[198:201], v[236:239], v[82:85]
	v_mfma_f32_16x16x32_bf16 v[78:81], v[206:209], v[228:231], v[78:81]
	v_mfma_f32_16x16x32_bf16 v[74:77], v[206:209], v[236:239], v[74:77]
	v_mfma_f32_16x16x32_bf16 v[70:73], v[216:219], v[228:231], v[70:73]
	v_mfma_f32_16x16x32_bf16 v[66:69], v[216:219], v[236:239], v[66:69]
	s_add_u32 s29, s8, s14
	s_addc_u32 s30, s9, s15
	s_add_u32 s26, s29, 0x100
	s_addc_u32 s27, s30, 0
	v_readfirstlane_b32 s31, v138
	s_barrier
	ds_read_b128 v[186:189], v140 offset:16384
	ds_read_b128 v[190:193], v140 offset:17408
	ds_read_b128 v[194:197], v143 offset:16384
	ds_read_b128 v[198:201], v143 offset:17408
	ds_read_b128 v[202:205], v142 offset:16384
	ds_read_b128 v[206:209], v142 offset:17408
	ds_read_b128 v[212:215], v141 offset:16384
	ds_read_b128 v[216:219], v141 offset:17408
	s_mov_b32 m0, s31
	v_lshl_add_u64 v[240:241], s[26:27], 0, v[132:133]
	global_load_lds_dwordx4 v[240:241], off
	v_lshl_add_u64 v[240:241], s[26:27], 0, v[130:131]
	v_readfirstlane_b32 s26, v139
	s_mov_b32 m0, s26
	s_nop 0
	global_load_lds_dwordx4 v[240:241], off
	s_barrier
	s_waitcnt lgkmcnt(0)
	s_waitcnt lgkmcnt(0)
	v_mfma_f32_16x16x32_bf16 v[62:65], v[186:189], v[170:173], v[62:65]
	v_mfma_f32_16x16x32_bf16 v[58:61], v[186:189], v[178:181], v[58:61]
	v_mfma_f32_16x16x32_bf16 v[54:57], v[194:197], v[170:173], v[54:57]
	v_mfma_f32_16x16x32_bf16 v[50:53], v[194:197], v[178:181], v[50:53]
	v_mfma_f32_16x16x32_bf16 v[46:49], v[202:205], v[170:173], v[46:49]
	v_mfma_f32_16x16x32_bf16 v[42:45], v[202:205], v[178:181], v[42:45]
	v_mfma_f32_16x16x32_bf16 v[38:41], v[212:215], v[170:173], v[38:41]
	v_mfma_f32_16x16x32_bf16 v[34:37], v[212:215], v[178:181], v[34:37]
	v_mfma_f32_16x16x32_bf16 v[62:65], v[190:193], v[174:177], v[62:65]
	v_mfma_f32_16x16x32_bf16 v[58:61], v[190:193], v[182:185], v[58:61]
	v_mfma_f32_16x16x32_bf16 v[54:57], v[198:201], v[174:177], v[54:57]
	v_mfma_f32_16x16x32_bf16 v[50:53], v[198:201], v[182:185], v[50:53]
	v_mfma_f32_16x16x32_bf16 v[46:49], v[206:209], v[174:177], v[46:49]
	v_mfma_f32_16x16x32_bf16 v[42:45], v[206:209], v[182:185], v[42:45]
	v_mfma_f32_16x16x32_bf16 v[38:41], v[216:219], v[174:177], v[38:41]
	v_mfma_f32_16x16x32_bf16 v[34:37], v[216:219], v[182:185], v[34:37]
	s_barrier
	s_add_u32 s31, s10, s14
	s_addc_u32 s34, s11, s15
	s_add_u32 s26, s31, 0x100
	s_addc_u32 s27, s34, 0
	v_readfirstlane_b32 s35, v146
	s_mov_b32 m0, s35
	v_lshl_add_u64 v[170:171], s[26:27], 0, v[132:133]
	global_load_lds_dwordx4 v[170:171], off
	v_lshl_add_u64 v[170:171], s[26:27], 0, v[130:131]
	v_readfirstlane_b32 s26, v147
	s_mov_b32 m0, s26
	s_nop 0
	global_load_lds_dwordx4 v[170:171], off
	s_waitcnt vmcnt(6)
	s_barrier
	v_mfma_f32_16x16x32_bf16 v[30:33], v[186:189], v[224:227], v[30:33]
	v_mfma_f32_16x16x32_bf16 v[26:29], v[186:189], v[232:235], v[26:29]
	v_mfma_f32_16x16x32_bf16 v[22:25], v[194:197], v[224:227], v[22:25]
	v_mfma_f32_16x16x32_bf16 v[18:21], v[194:197], v[232:235], v[18:21]
	v_mfma_f32_16x16x32_bf16 v[14:17], v[202:205], v[224:227], v[14:17]
	v_mfma_f32_16x16x32_bf16 v[10:13], v[202:205], v[232:235], v[10:13]
	v_mfma_f32_16x16x32_bf16 v[6:9], v[212:215], v[224:227], v[6:9]
	v_mfma_f32_16x16x32_bf16 v[2:5], v[212:215], v[232:235], v[2:5]
	v_mfma_f32_16x16x32_bf16 v[30:33], v[190:193], v[228:231], v[30:33]
	v_mfma_f32_16x16x32_bf16 v[26:29], v[190:193], v[236:239], v[26:29]
	v_mfma_f32_16x16x32_bf16 v[22:25], v[198:201], v[228:231], v[22:25]
	v_mfma_f32_16x16x32_bf16 v[18:21], v[198:201], v[236:239], v[18:21]
	v_mfma_f32_16x16x32_bf16 v[14:17], v[206:209], v[228:231], v[14:17]
	v_mfma_f32_16x16x32_bf16 v[10:13], v[206:209], v[236:239], v[10:13]
	v_mfma_f32_16x16x32_bf16 v[6:9], v[216:219], v[228:231], v[6:9]
	v_mfma_f32_16x16x32_bf16 v[2:5], v[216:219], v[236:239], v[2:5]
	v_or_b32_e32 v170, 0x18000, v156
	v_or_b32_e32 v172, 0x18000, v158
	s_barrier
	v_or_b32_e32 v171, 0x18000, v157
	ds_read_b128 v[178:181], v170
	ds_read_b128 v[182:185], v171
	v_or_b32_e32 v173, 0x18000, v159
	ds_read_b128 v[186:189], v172
	ds_read_b128 v[190:193], v173
	s_add_u32 s26, s1, s14
	s_addc_u32 s27, s16, s15
	v_readfirstlane_b32 s35, v148
	ds_read_b128 v[194:197], v140 offset:32768
	ds_read_b128 v[198:201], v140 offset:33792
	ds_read_b128 v[202:205], v143 offset:32768
	ds_read_b128 v[206:209], v143 offset:33792
	ds_read_b128 v[212:215], v142 offset:32768
	ds_read_b128 v[216:219], v142 offset:33792
	ds_read_b128 v[224:227], v141 offset:32768
	ds_read_b128 v[228:231], v141 offset:33792
	s_mov_b32 m0, s35
	v_lshl_add_u64 v[174:175], s[26:27], 0, v[132:133]
	global_load_lds_dwordx4 v[174:175], off
	v_lshl_add_u64 v[174:175], s[26:27], 0, v[130:131]
	v_readfirstlane_b32 s26, v149
	s_mov_b32 m0, s26
	s_nop 0
	global_load_lds_dwordx4 v[174:175], off
	s_waitcnt lgkmcnt(8)
	s_barrier
	s_waitcnt lgkmcnt(0)
	s_waitcnt lgkmcnt(0)
	v_mfma_f32_16x16x32_bf16 v[126:129], v[194:197], v[178:181], v[126:129]
	v_mfma_f32_16x16x32_bf16 v[122:125], v[194:197], v[186:189], v[122:125]
	v_mfma_f32_16x16x32_bf16 v[118:121], v[202:205], v[178:181], v[118:121]
	v_mfma_f32_16x16x32_bf16 v[114:117], v[202:205], v[186:189], v[114:117]
	v_mfma_f32_16x16x32_bf16 v[110:113], v[212:215], v[178:181], v[110:113]
	v_mfma_f32_16x16x32_bf16 v[106:109], v[212:215], v[186:189], v[106:109]
	v_mfma_f32_16x16x32_bf16 v[102:105], v[224:227], v[178:181], v[102:105]
	v_mfma_f32_16x16x32_bf16 v[98:101], v[224:227], v[186:189], v[98:101]
	v_mfma_f32_16x16x32_bf16 v[126:129], v[198:201], v[182:185], v[126:129]
	v_mfma_f32_16x16x32_bf16 v[122:125], v[198:201], v[190:193], v[122:125]
	v_mfma_f32_16x16x32_bf16 v[118:121], v[206:209], v[182:185], v[118:121]
	v_mfma_f32_16x16x32_bf16 v[114:117], v[206:209], v[190:193], v[114:117]
	v_mfma_f32_16x16x32_bf16 v[110:113], v[216:219], v[182:185], v[110:113]
	v_mfma_f32_16x16x32_bf16 v[106:109], v[216:219], v[190:193], v[106:109]
	v_mfma_f32_16x16x32_bf16 v[102:105], v[228:231], v[182:185], v[102:105]
	v_mfma_f32_16x16x32_bf16 v[98:101], v[228:231], v[190:193], v[98:101]
	s_barrier
	s_add_u32 s26, s25, 0x180
	v_or_b32_e32 v174, 0x1c000, v156
	v_or_b32_e32 v176, 0x1c000, v158
	s_addc_u32 s27, s28, 0
	v_readfirstlane_b32 s25, v150
	v_or_b32_e32 v175, 0x1c000, v157
	ds_read_b128 v[232:235], v174
	ds_read_b128 v[236:239], v175
	v_or_b32_e32 v177, 0x1c000, v159
	ds_read_b128 v[240:243], v176
	ds_read_b128 v[244:247], v177
	s_mov_b32 m0, s25
	v_lshl_add_u64 v[248:249], s[26:27], 0, v[132:133]
	v_readfirstlane_b32 s25, v151
	global_load_lds_dwordx4 v[248:249], off
	v_lshl_add_u64 v[248:249], s[26:27], 0, v[130:131]
	s_mov_b32 m0, s25
	s_nop 0
	global_load_lds_dwordx4 v[248:249], off
	s_barrier
	s_waitcnt lgkmcnt(0)
	s_waitcnt lgkmcnt(0)
	v_mfma_f32_16x16x32_bf16 v[94:97], v[194:197], v[232:235], v[94:97]
	v_mfma_f32_16x16x32_bf16 v[90:93], v[194:197], v[240:243], v[90:93]
	v_mfma_f32_16x16x32_bf16 v[86:89], v[202:205], v[232:235], v[86:89]
	v_mfma_f32_16x16x32_bf16 v[82:85], v[202:205], v[240:243], v[82:85]
	v_mfma_f32_16x16x32_bf16 v[78:81], v[212:215], v[232:235], v[78:81]
	v_mfma_f32_16x16x32_bf16 v[74:77], v[212:215], v[240:243], v[74:77]
	v_mfma_f32_16x16x32_bf16 v[70:73], v[224:227], v[232:235], v[70:73]
	v_mfma_f32_16x16x32_bf16 v[66:69], v[224:227], v[240:243], v[66:69]
	v_mfma_f32_16x16x32_bf16 v[94:97], v[198:201], v[236:239], v[94:97]
	v_mfma_f32_16x16x32_bf16 v[90:93], v[198:201], v[244:247], v[90:93]
	v_mfma_f32_16x16x32_bf16 v[86:89], v[206:209], v[236:239], v[86:89]
	v_mfma_f32_16x16x32_bf16 v[82:85], v[206:209], v[244:247], v[82:85]
	v_mfma_f32_16x16x32_bf16 v[78:81], v[216:219], v[236:239], v[78:81]
	v_mfma_f32_16x16x32_bf16 v[74:77], v[216:219], v[244:247], v[74:77]
	v_mfma_f32_16x16x32_bf16 v[70:73], v[228:231], v[236:239], v[70:73]
	v_mfma_f32_16x16x32_bf16 v[66:69], v[228:231], v[244:247], v[66:69]
	s_add_u32 s26, s29, 0x180
	s_addc_u32 s27, s30, 0
	v_readfirstlane_b32 s25, v152
	s_barrier
	ds_read_b128 v[194:197], v140 offset:49152
	ds_read_b128 v[198:201], v140 offset:50176
	ds_read_b128 v[202:205], v143 offset:49152
	ds_read_b128 v[206:209], v143 offset:50176
	ds_read_b128 v[212:215], v142 offset:49152
	ds_read_b128 v[216:219], v142 offset:50176
	ds_read_b128 v[224:227], v141 offset:49152
	ds_read_b128 v[228:231], v141 offset:50176
	s_mov_b32 m0, s25
	v_lshl_add_u64 v[248:249], s[26:27], 0, v[132:133]
	v_readfirstlane_b32 s25, v153
	global_load_lds_dwordx4 v[248:249], off
	v_lshl_add_u64 v[248:249], s[26:27], 0, v[130:131]
	s_mov_b32 m0, s25
	s_nop 0
	global_load_lds_dwordx4 v[248:249], off
	s_barrier
	s_waitcnt lgkmcnt(0)
	s_waitcnt lgkmcnt(0)
	v_mfma_f32_16x16x32_bf16 v[62:65], v[194:197], v[178:181], v[62:65]
	v_mfma_f32_16x16x32_bf16 v[58:61], v[194:197], v[186:189], v[58:61]
	v_mfma_f32_16x16x32_bf16 v[54:57], v[202:205], v[178:181], v[54:57]
	v_mfma_f32_16x16x32_bf16 v[50:53], v[202:205], v[186:189], v[50:53]
	v_mfma_f32_16x16x32_bf16 v[46:49], v[212:215], v[178:181], v[46:49]
	v_mfma_f32_16x16x32_bf16 v[42:45], v[212:215], v[186:189], v[42:45]
	v_mfma_f32_16x16x32_bf16 v[38:41], v[224:227], v[178:181], v[38:41]
	v_mfma_f32_16x16x32_bf16 v[34:37], v[224:227], v[186:189], v[34:37]
	v_mfma_f32_16x16x32_bf16 v[62:65], v[198:201], v[182:185], v[62:65]
	v_mfma_f32_16x16x32_bf16 v[58:61], v[198:201], v[190:193], v[58:61]
	v_mfma_f32_16x16x32_bf16 v[54:57], v[206:209], v[182:185], v[54:57]
	v_mfma_f32_16x16x32_bf16 v[50:53], v[206:209], v[190:193], v[50:53]
	v_mfma_f32_16x16x32_bf16 v[46:49], v[216:219], v[182:185], v[46:49]
	v_mfma_f32_16x16x32_bf16 v[42:45], v[216:219], v[190:193], v[42:45]
	v_mfma_f32_16x16x32_bf16 v[38:41], v[228:231], v[182:185], v[38:41]
	v_mfma_f32_16x16x32_bf16 v[34:37], v[228:231], v[190:193], v[34:37]
	s_barrier
	s_add_u32 s26, s31, 0x180
	s_addc_u32 s27, s34, 0
	v_readfirstlane_b32 s25, v154
	s_mov_b32 m0, s25
	v_lshl_add_u64 v[178:179], s[26:27], 0, v[132:133]
	v_readfirstlane_b32 s25, v155
	global_load_lds_dwordx4 v[178:179], off
	v_lshl_add_u64 v[178:179], s[26:27], 0, v[130:131]
	s_mov_b32 m0, s25
	s_nop 0
	global_load_lds_dwordx4 v[178:179], off
	s_waitcnt vmcnt(6)
	s_barrier
	v_mfma_f32_16x16x32_bf16 v[30:33], v[194:197], v[232:235], v[30:33]
	v_mfma_f32_16x16x32_bf16 v[26:29], v[194:197], v[240:243], v[26:29]
	v_mfma_f32_16x16x32_bf16 v[22:25], v[202:205], v[232:235], v[22:25]
	v_mfma_f32_16x16x32_bf16 v[18:21], v[202:205], v[240:243], v[18:21]
	v_mfma_f32_16x16x32_bf16 v[14:17], v[212:215], v[232:235], v[14:17]
	v_mfma_f32_16x16x32_bf16 v[10:13], v[212:215], v[240:243], v[10:13]
	v_mfma_f32_16x16x32_bf16 v[6:9], v[224:227], v[232:235], v[6:9]
	v_mfma_f32_16x16x32_bf16 v[2:5], v[224:227], v[240:243], v[2:5]
	v_mfma_f32_16x16x32_bf16 v[30:33], v[198:201], v[236:239], v[30:33]
	v_mfma_f32_16x16x32_bf16 v[26:29], v[198:201], v[244:247], v[26:29]
	v_mfma_f32_16x16x32_bf16 v[22:25], v[206:209], v[236:239], v[22:25]
	v_mfma_f32_16x16x32_bf16 v[18:21], v[206:209], v[244:247], v[18:21]
	v_mfma_f32_16x16x32_bf16 v[14:17], v[216:219], v[236:239], v[14:17]
	v_mfma_f32_16x16x32_bf16 v[10:13], v[216:219], v[244:247], v[10:13]
	v_mfma_f32_16x16x32_bf16 v[6:9], v[228:231], v[236:239], v[6:9]
	v_mfma_f32_16x16x32_bf16 v[2:5], v[228:231], v[244:247], v[2:5]
	s_add_i32 s24, s24, 2
	s_add_u32 s14, s14, 0x100
	s_addc_u32 s15, s15, 0
	s_cmp_lt_u32 s24, 28
	s_barrier
	s_cbranch_scc1 .LBB0_1733
	s_add_u32 s6, s12, 0xf80
	s_addc_u32 s7, s13, 0
	v_readfirstlane_b32 s1, v164
	ds_read_b128 v[144:147], v160
	ds_read_b128 v[148:151], v161
	ds_read_b128 v[152:155], v162
	ds_read_b128 v[156:159], v163
	ds_read_b128 v[160:163], v140
	ds_read_b128 v[178:181], v140 offset:1024
	ds_read_b128 v[182:185], v143
	ds_read_b128 v[186:189], v143 offset:1024
	ds_read_b128 v[190:193], v142
	ds_read_b128 v[194:197], v142 offset:1024
	ds_read_b128 v[198:201], v141
	ds_read_b128 v[202:205], v141 offset:1024
	s_mov_b32 m0, s1
	v_lshl_add_u64 v[132:133], s[6:7], 0, v[132:133]
	v_readfirstlane_b32 s1, v165
	global_load_lds_dwordx4 v[132:133], off
	v_lshl_add_u64 v[130:131], s[6:7], 0, v[130:131]
	s_mov_b32 m0, s1
	s_nop 0
	global_load_lds_dwordx4 v[130:131], off
	s_barrier
	s_waitcnt lgkmcnt(0)
	s_waitcnt lgkmcnt(0)
	v_mfma_f32_16x16x32_bf16 v[126:129], v[160:163], v[144:147], v[126:129]
	v_mfma_f32_16x16x32_bf16 v[122:125], v[160:163], v[152:155], v[122:125]
	v_mfma_f32_16x16x32_bf16 v[118:121], v[182:185], v[144:147], v[118:121]
	v_mfma_f32_16x16x32_bf16 v[114:117], v[182:185], v[152:155], v[114:117]
	v_mfma_f32_16x16x32_bf16 v[110:113], v[190:193], v[144:147], v[110:113]
	v_mfma_f32_16x16x32_bf16 v[106:109], v[190:193], v[152:155], v[106:109]
	v_mfma_f32_16x16x32_bf16 v[98:101], v[198:201], v[152:155], v[98:101]
	v_mfma_f32_16x16x32_bf16 v[126:129], v[178:181], v[148:151], v[126:129]
	v_mfma_f32_16x16x32_bf16 v[122:125], v[178:181], v[156:159], v[122:125]
	v_mfma_f32_16x16x32_bf16 v[118:121], v[186:189], v[148:151], v[118:121]
	v_mfma_f32_16x16x32_bf16 v[114:117], v[186:189], v[156:159], v[114:117]
	v_mfma_f32_16x16x32_bf16 v[110:113], v[194:197], v[148:151], v[110:113]
	v_mfma_f32_16x16x32_bf16 v[106:109], v[194:197], v[156:159], v[106:109]
	v_mfma_f32_16x16x32_bf16 v[102:105], v[198:201], v[144:147], v[102:105]
	v_mfma_f32_16x16x32_bf16 v[98:101], v[202:205], v[156:159], v[98:101]
	v_mfma_f32_16x16x32_bf16 v[130:133], v[202:205], v[148:151], v[102:105]
	s_barrier
	s_nop 2
	ds_read_b128 v[102:105], v166
	ds_read_b128 v[164:167], v167
	ds_read_b128 v[206:209], v168
	ds_read_b128 v[212:215], v169
	s_barrier
	s_waitcnt lgkmcnt(0)
	s_waitcnt lgkmcnt(1)
	v_mfma_f32_16x16x32_bf16 v[90:93], v[160:163], v[206:209], v[90:93]
	v_mfma_f32_16x16x32_bf16 v[94:97], v[160:163], v[102:105], v[94:97]
	s_waitcnt lgkmcnt(0)
	v_mfma_f32_16x16x32_bf16 v[90:93], v[178:181], v[212:215], v[90:93]
	v_mfma_f32_16x16x32_bf16 v[86:89], v[182:185], v[102:105], v[86:89]
	v_mfma_f32_16x16x32_bf16 v[82:85], v[182:185], v[206:209], v[82:85]
	v_mfma_f32_16x16x32_bf16 v[78:81], v[190:193], v[102:105], v[78:81]
	v_mfma_f32_16x16x32_bf16 v[74:77], v[190:193], v[206:209], v[74:77]
	v_mfma_f32_16x16x32_bf16 v[70:73], v[198:201], v[102:105], v[70:73]
	v_mfma_f32_16x16x32_bf16 v[66:69], v[198:201], v[206:209], v[66:69]
	v_mfma_f32_16x16x32_bf16 v[216:219], v[178:181], v[164:167], v[94:97]
	v_mfma_f32_16x16x32_bf16 v[160:163], v[186:189], v[164:167], v[86:89]
	v_mfma_f32_16x16x32_bf16 v[178:181], v[186:189], v[212:215], v[82:85]
	v_mfma_f32_16x16x32_bf16 v[182:185], v[194:197], v[164:167], v[78:81]
	v_mfma_f32_16x16x32_bf16 v[186:189], v[194:197], v[212:215], v[74:77]
	v_mfma_f32_16x16x32_bf16 v[190:193], v[202:205], v[164:167], v[70:73]
	v_mfma_f32_16x16x32_bf16 v[194:197], v[202:205], v[212:215], v[66:69]
	s_barrier
	s_nop 0
	ds_read_b128 v[66:69], v140 offset:16384
	ds_read_b128 v[70:73], v140 offset:17408
	ds_read_b128 v[74:77], v143 offset:16384
	ds_read_b128 v[78:81], v143 offset:17408
	ds_read_b128 v[82:85], v142 offset:16384
	ds_read_b128 v[86:89], v142 offset:17408
	ds_read_b128 v[94:97], v141 offset:16384
	ds_read_b128 v[198:201], v141 offset:17408
	s_waitcnt vmcnt(4)
	s_barrier
	s_waitcnt lgkmcnt(0)
	s_waitcnt lgkmcnt(7)
	v_mfma_f32_16x16x32_bf16 v[62:65], v[66:69], v[144:147], v[62:65]
	v_mfma_f32_16x16x32_bf16 v[58:61], v[66:69], v[152:155], v[58:61]
	s_waitcnt lgkmcnt(5)
	v_mfma_f32_16x16x32_bf16 v[54:57], v[74:77], v[144:147], v[54:57]
	v_mfma_f32_16x16x32_bf16 v[50:53], v[74:77], v[152:155], v[50:53]
	s_waitcnt lgkmcnt(3)
	v_mfma_f32_16x16x32_bf16 v[46:49], v[82:85], v[144:147], v[46:49]
	v_mfma_f32_16x16x32_bf16 v[42:45], v[82:85], v[152:155], v[42:45]
	s_waitcnt lgkmcnt(1)
	v_mfma_f32_16x16x32_bf16 v[38:41], v[94:97], v[144:147], v[38:41]
	v_mfma_f32_16x16x32_bf16 v[34:37], v[94:97], v[152:155], v[34:37]
	v_mfma_f32_16x16x32_bf16 v[62:65], v[70:73], v[148:151], v[62:65]
	v_mfma_f32_16x16x32_bf16 v[58:61], v[70:73], v[156:159], v[58:61]
	v_mfma_f32_16x16x32_bf16 v[54:57], v[78:81], v[148:151], v[54:57]
	v_mfma_f32_16x16x32_bf16 v[50:53], v[78:81], v[156:159], v[50:53]
	v_mfma_f32_16x16x32_bf16 v[46:49], v[86:89], v[148:151], v[46:49]
	v_mfma_f32_16x16x32_bf16 v[42:45], v[86:89], v[156:159], v[42:45]
	s_waitcnt lgkmcnt(0)
	v_mfma_f32_16x16x32_bf16 v[38:41], v[198:201], v[148:151], v[38:41]
	v_mfma_f32_16x16x32_bf16 v[34:37], v[198:201], v[156:159], v[34:37]
	v_mfma_f32_16x16x32_bf16 v[30:33], v[66:69], v[102:105], v[30:33]
	v_mfma_f32_16x16x32_bf16 v[26:29], v[66:69], v[206:209], v[26:29]
	v_mfma_f32_16x16x32_bf16 v[22:25], v[74:77], v[102:105], v[22:25]
	v_mfma_f32_16x16x32_bf16 v[18:21], v[74:77], v[206:209], v[18:21]
	v_mfma_f32_16x16x32_bf16 v[14:17], v[82:85], v[102:105], v[14:17]
	v_mfma_f32_16x16x32_bf16 v[10:13], v[82:85], v[206:209], v[10:13]
	v_mfma_f32_16x16x32_bf16 v[6:9], v[94:97], v[102:105], v[6:9]
	v_mfma_f32_16x16x32_bf16 v[2:5], v[94:97], v[206:209], v[2:5]
	v_mfma_f32_16x16x32_bf16 v[144:147], v[70:73], v[164:167], v[30:33]
	v_mfma_f32_16x16x32_bf16 v[148:151], v[70:73], v[212:215], v[26:29]
	v_mfma_f32_16x16x32_bf16 v[152:155], v[78:81], v[164:167], v[22:25]
	v_mfma_f32_16x16x32_bf16 v[156:159], v[78:81], v[212:215], v[18:21]
	v_mfma_f32_16x16x32_bf16 v[202:205], v[86:89], v[164:167], v[14:17]
	v_mfma_f32_16x16x32_bf16 v[224:227], v[86:89], v[212:215], v[10:13]
	v_mfma_f32_16x16x32_bf16 v[164:167], v[198:201], v[164:167], v[6:9]
	v_mfma_f32_16x16x32_bf16 v[198:201], v[198:201], v[212:215], v[2:5]
	s_barrier
	s_nop 0
	ds_read_b128 v[2:5], v170
	ds_read_b128 v[6:9], v171
	ds_read_b128 v[168:171], v172
	ds_read_b128 v[206:209], v173
	ds_read_b128 v[10:13], v140 offset:32768
	ds_read_b128 v[14:17], v140 offset:33792
	ds_read_b128 v[18:21], v143 offset:32768
	ds_read_b128 v[22:25], v143 offset:33792
	ds_read_b128 v[26:29], v142 offset:32768
	ds_read_b128 v[30:33], v142 offset:33792
	ds_read_b128 v[212:215], v141 offset:32768
	ds_read_b128 v[228:231], v141 offset:33792
	s_waitcnt vmcnt(2)
	s_barrier
	s_waitcnt lgkmcnt(0)
	s_waitcnt lgkmcnt(7)
	v_mfma_f32_16x16x32_bf16 v[66:69], v[10:13], v[2:5], v[126:129]
	s_waitcnt lgkmcnt(6)
	v_mfma_f32_16x16x32_bf16 v[94:97], v[14:17], v[6:9], v[66:69]
	v_mfma_f32_16x16x32_bf16 v[66:69], v[10:13], v[168:171], v[122:125]
	v_mfma_f32_16x16x32_bf16 v[102:105], v[14:17], v[206:209], v[66:69]
	s_waitcnt lgkmcnt(5)
	v_mfma_f32_16x16x32_bf16 v[66:69], v[18:21], v[2:5], v[118:121]
	s_waitcnt lgkmcnt(4)
	v_mfma_f32_16x16x32_bf16 v[82:85], v[22:25], v[6:9], v[66:69]
	v_mfma_f32_16x16x32_bf16 v[66:69], v[18:21], v[168:171], v[114:117]
	v_mfma_f32_16x16x32_bf16 v[86:89], v[22:25], v[206:209], v[66:69]
	s_waitcnt lgkmcnt(3)
	v_mfma_f32_16x16x32_bf16 v[66:69], v[26:29], v[2:5], v[110:113]
	s_waitcnt lgkmcnt(2)
	v_mfma_f32_16x16x32_bf16 v[74:77], v[30:33], v[6:9], v[66:69]
	v_mfma_f32_16x16x32_bf16 v[66:69], v[26:29], v[168:171], v[106:109]
	v_mfma_f32_16x16x32_bf16 v[78:81], v[30:33], v[206:209], v[66:69]
	s_waitcnt lgkmcnt(1)
	v_mfma_f32_16x16x32_bf16 v[66:69], v[212:215], v[2:5], v[130:133]
	v_mfma_f32_16x16x32_bf16 v[70:73], v[212:215], v[168:171], v[98:101]
	s_waitcnt lgkmcnt(0)
	v_mfma_f32_16x16x32_bf16 v[66:69], v[228:231], v[6:9], v[66:69]
	v_mfma_f32_16x16x32_bf16 v[70:73], v[228:231], v[206:209], v[70:73]
	s_barrier
	ds_read_b128 v[130:133], v174
	ds_read_b128 v[172:175], v175
	ds_read_b128 v[232:235], v176
	ds_read_b128 v[236:239], v177
	s_waitcnt vmcnt(0)
	s_barrier
	s_waitcnt lgkmcnt(0)
	s_waitcnt lgkmcnt(3)
	v_mfma_f32_16x16x32_bf16 v[98:101], v[10:13], v[130:133], v[216:219]
	s_waitcnt lgkmcnt(1)
	v_mfma_f32_16x16x32_bf16 v[10:13], v[10:13], v[232:235], v[90:93]
	s_waitcnt lgkmcnt(0)
	v_mfma_f32_16x16x32_bf16 v[126:129], v[14:17], v[236:239], v[10:13]
	v_mfma_f32_16x16x32_bf16 v[10:13], v[18:21], v[130:133], v[160:163]
	v_mfma_f32_16x16x32_bf16 v[114:117], v[22:25], v[172:175], v[10:13]
	v_mfma_f32_16x16x32_bf16 v[10:13], v[18:21], v[232:235], v[178:181]
	v_mfma_f32_16x16x32_bf16 v[118:121], v[22:25], v[236:239], v[10:13]
	v_mfma_f32_16x16x32_bf16 v[10:13], v[26:29], v[130:133], v[182:185]
	v_mfma_f32_16x16x32_bf16 v[106:109], v[30:33], v[172:175], v[10:13]
	v_mfma_f32_16x16x32_bf16 v[10:13], v[26:29], v[232:235], v[186:189]
	v_mfma_f32_16x16x32_bf16 v[110:113], v[30:33], v[236:239], v[10:13]
	v_mfma_f32_16x16x32_bf16 v[10:13], v[212:215], v[130:133], v[190:193]
	v_mfma_f32_16x16x32_bf16 v[90:93], v[228:231], v[172:175], v[10:13]
	v_mfma_f32_16x16x32_bf16 v[10:13], v[212:215], v[232:235], v[194:197]
	v_mfma_f32_16x16x32_bf16 v[122:125], v[14:17], v[172:175], v[98:101]
	v_mfma_f32_16x16x32_bf16 v[98:101], v[228:231], v[236:239], v[10:13]
	s_barrier
	ds_read_b128 v[160:163], v140 offset:49152
	ds_read_b128 v[176:179], v140 offset:50176
	ds_read_b128 v[180:183], v143 offset:49152
	ds_read_b128 v[184:187], v143 offset:50176
	ds_read_b128 v[188:191], v142 offset:49152
	ds_read_b128 v[192:195], v142 offset:50176
	ds_read_b128 v[212:215], v141 offset:49152
	ds_read_b128 v[138:141], v141 offset:50176
	s_barrier
	s_waitcnt lgkmcnt(0)
	s_waitcnt lgkmcnt(7)
	v_mfma_f32_16x16x32_bf16 v[10:13], v[160:163], v[2:5], v[62:65]
	s_waitcnt lgkmcnt(6)
	v_mfma_f32_16x16x32_bf16 v[26:29], v[176:179], v[6:9], v[10:13]
	v_mfma_f32_16x16x32_bf16 v[10:13], v[160:163], v[168:171], v[58:61]
	v_mfma_f32_16x16x32_bf16 v[30:33], v[176:179], v[206:209], v[10:13]
	s_waitcnt lgkmcnt(5)
	v_mfma_f32_16x16x32_bf16 v[10:13], v[180:183], v[2:5], v[54:57]
	s_waitcnt lgkmcnt(4)
	v_mfma_f32_16x16x32_bf16 v[18:21], v[184:187], v[6:9], v[10:13]
	v_mfma_f32_16x16x32_bf16 v[10:13], v[180:183], v[168:171], v[50:53]
	v_mfma_f32_16x16x32_bf16 v[22:25], v[184:187], v[206:209], v[10:13]
	s_waitcnt lgkmcnt(3)
	v_mfma_f32_16x16x32_bf16 v[10:13], v[188:191], v[2:5], v[46:49]
	s_waitcnt lgkmcnt(1)
	v_mfma_f32_16x16x32_bf16 v[2:5], v[212:215], v[2:5], v[38:41]
	v_mfma_f32_16x16x32_bf16 v[10:13], v[192:195], v[6:9], v[10:13]
	v_mfma_f32_16x16x32_bf16 v[14:17], v[188:191], v[168:171], v[42:45]
	s_waitcnt lgkmcnt(0)
	v_mfma_f32_16x16x32_bf16 v[2:5], v[138:141], v[6:9], v[2:5]
	v_mfma_f32_16x16x32_bf16 v[6:9], v[212:215], v[168:171], v[34:37]
	v_mfma_f32_16x16x32_bf16 v[14:17], v[192:195], v[206:209], v[14:17]
	v_mfma_f32_16x16x32_bf16 v[6:9], v[138:141], v[206:209], v[6:9]
	v_mfma_f32_16x16x32_bf16 v[34:37], v[160:163], v[130:133], v[144:147]
	v_mfma_f32_16x16x32_bf16 v[58:61], v[176:179], v[172:175], v[34:37]
	v_mfma_f32_16x16x32_bf16 v[34:37], v[160:163], v[232:235], v[148:151]
	v_mfma_f32_16x16x32_bf16 v[62:65], v[176:179], v[236:239], v[34:37]
	v_mfma_f32_16x16x32_bf16 v[34:37], v[180:183], v[130:133], v[152:155]
	v_mfma_f32_16x16x32_bf16 v[50:53], v[184:187], v[172:175], v[34:37]
	v_mfma_f32_16x16x32_bf16 v[34:37], v[180:183], v[232:235], v[156:159]
	v_mfma_f32_16x16x32_bf16 v[54:57], v[184:187], v[236:239], v[34:37]
	v_mfma_f32_16x16x32_bf16 v[34:37], v[188:191], v[130:133], v[202:205]
	v_mfma_f32_16x16x32_bf16 v[42:45], v[192:195], v[172:175], v[34:37]
	v_mfma_f32_16x16x32_bf16 v[34:37], v[188:191], v[232:235], v[224:227]
	v_mfma_f32_16x16x32_bf16 v[46:49], v[192:195], v[236:239], v[34:37]
	v_mfma_f32_16x16x32_bf16 v[34:37], v[212:215], v[130:133], v[164:167]
	v_mfma_f32_16x16x32_bf16 v[38:41], v[212:215], v[232:235], v[198:201]
	v_mfma_f32_16x16x32_bf16 v[34:37], v[138:141], v[172:175], v[34:37]
	v_mfma_f32_16x16x32_bf16 v[38:41], v[138:141], v[236:239], v[38:41]
	s_movk_i32 s1, 0x100
	v_cmp_gt_u32_e32 vcc, s1, v1
	s_barrier
	s_and_saveexec_b64 s[6:7], vcc
	s_cbranch_execz .LBB0_1736
	s_barrier

.LBB0_1871:
	v_or_b32_e32 v160, 0x10000, v156
	v_or_b32_e32 v162, 0x10000, v158
	v_or_b32_e32 v161, 0x10000, v157
	ds_read_b128 v[170:173], v160
	ds_read_b128 v[174:177], v161
	v_or_b32_e32 v163, 0x10000, v159
	ds_read_b128 v[178:181], v162
	ds_read_b128 v[182:185], v163
	s_add_u32 s36, s19, s16
	s_addc_u32 s37, s34, s17
	s_add_u32 s36, s36, 0x80
	v_add_u32_e32 v164, 0xc000, v137
	s_addc_u32 s37, s37, 0
	v_readfirstlane_b32 s38, v164
	ds_read_b128 v[186:189], v139
	ds_read_b128 v[190:193], v139 offset:1024
	ds_read_b128 v[194:197], v142
	ds_read_b128 v[198:201], v142 offset:1024
	ds_read_b128 v[202:205], v141
	ds_read_b128 v[206:209], v141 offset:1024
	ds_read_b128 v[212:215], v140
	ds_read_b128 v[216:219], v140 offset:1024
	s_mov_b32 m0, s38
	v_lshl_add_u64 v[166:167], s[36:37], 0, v[132:133]
	v_add_u32_e32 v165, 0xe000, v137
	global_load_lds_dwordx4 v[166:167], off
	v_lshl_add_u64 v[166:167], s[36:37], 0, v[130:131]
	v_readfirstlane_b32 s36, v165
	s_mov_b32 m0, s36
	s_nop 0
	global_load_lds_dwordx4 v[166:167], off
	s_waitcnt lgkmcnt(8)
	s_barrier
	s_waitcnt lgkmcnt(0)
	s_waitcnt lgkmcnt(0)
	v_mfma_f32_16x16x32_bf16 v[126:129], v[186:189], v[170:173], v[126:129]
	v_mfma_f32_16x16x32_bf16 v[122:125], v[186:189], v[178:181], v[122:125]
	v_mfma_f32_16x16x32_bf16 v[118:121], v[194:197], v[170:173], v[118:121]
	v_mfma_f32_16x16x32_bf16 v[114:117], v[194:197], v[178:181], v[114:117]
	v_mfma_f32_16x16x32_bf16 v[110:113], v[202:205], v[170:173], v[110:113]
	v_mfma_f32_16x16x32_bf16 v[106:109], v[202:205], v[178:181], v[106:109]
	v_mfma_f32_16x16x32_bf16 v[102:105], v[212:215], v[170:173], v[102:105]
	v_mfma_f32_16x16x32_bf16 v[98:101], v[212:215], v[178:181], v[98:101]
	v_mfma_f32_16x16x32_bf16 v[126:129], v[190:193], v[174:177], v[126:129]
	v_mfma_f32_16x16x32_bf16 v[122:125], v[190:193], v[182:185], v[122:125]
	v_mfma_f32_16x16x32_bf16 v[118:121], v[198:201], v[174:177], v[118:121]
	v_mfma_f32_16x16x32_bf16 v[114:117], v[198:201], v[182:185], v[114:117]
	v_mfma_f32_16x16x32_bf16 v[110:113], v[206:209], v[174:177], v[110:113]
	v_mfma_f32_16x16x32_bf16 v[106:109], v[206:209], v[182:185], v[106:109]
	v_mfma_f32_16x16x32_bf16 v[102:105], v[216:219], v[174:177], v[102:105]
	v_mfma_f32_16x16x32_bf16 v[98:101], v[216:219], v[182:185], v[98:101]
	s_barrier
	s_add_u32 s38, s0, s16
	s_addc_u32 s39, s1, s17
	s_add_u32 s36, s38, 0x100
	v_or_b32_e32 v166, 0x14000, v156
	v_or_b32_e32 v168, 0x14000, v158
	s_addc_u32 s37, s39, 0
	v_readfirstlane_b32 s40, v143
	v_or_b32_e32 v167, 0x14000, v157
	ds_read_b128 v[224:227], v166
	ds_read_b128 v[228:231], v167
	v_or_b32_e32 v169, 0x14000, v159
	ds_read_b128 v[232:235], v168
	ds_read_b128 v[236:239], v169
	s_mov_b32 m0, s40
	v_lshl_add_u64 v[240:241], s[36:37], 0, v[132:133]
	global_load_lds_dwordx4 v[240:241], off
	v_lshl_add_u64 v[240:241], s[36:37], 0, v[130:131]
	v_readfirstlane_b32 s36, v144
	s_mov_b32 m0, s36
	s_nop 0
	global_load_lds_dwordx4 v[240:241], off
	s_barrier
	s_waitcnt lgkmcnt(0)
	s_waitcnt lgkmcnt(0)
	v_mfma_f32_16x16x32_bf16 v[94:97], v[186:189], v[224:227], v[94:97]
	v_mfma_f32_16x16x32_bf16 v[90:93], v[186:189], v[232:235], v[90:93]
	v_mfma_f32_16x16x32_bf16 v[86:89], v[194:197], v[224:227], v[86:89]
	v_mfma_f32_16x16x32_bf16 v[82:85], v[194:197], v[232:235], v[82:85]
	v_mfma_f32_16x16x32_bf16 v[78:81], v[202:205], v[224:227], v[78:81]
	v_mfma_f32_16x16x32_bf16 v[74:77], v[202:205], v[232:235], v[74:77]
	v_mfma_f32_16x16x32_bf16 v[70:73], v[212:215], v[224:227], v[70:73]
	v_mfma_f32_16x16x32_bf16 v[66:69], v[212:215], v[232:235], v[66:69]
	v_mfma_f32_16x16x32_bf16 v[94:97], v[190:193], v[228:231], v[94:97]
	v_mfma_f32_16x16x32_bf16 v[90:93], v[190:193], v[236:239], v[90:93]
	v_mfma_f32_16x16x32_bf16 v[86:89], v[198:201], v[228:231], v[86:89]
	v_mfma_f32_16x16x32_bf16 v[82:85], v[198:201], v[236:239], v[82:85]
	v_mfma_f32_16x16x32_bf16 v[78:81], v[206:209], v[228:231], v[78:81]
	v_mfma_f32_16x16x32_bf16 v[74:77], v[206:209], v[236:239], v[74:77]
	v_mfma_f32_16x16x32_bf16 v[70:73], v[216:219], v[228:231], v[70:73]
	v_mfma_f32_16x16x32_bf16 v[66:69], v[216:219], v[236:239], v[66:69]
	s_add_u32 s40, s10, s16
	s_addc_u32 s41, s11, s17
	s_add_u32 s36, s40, 0x100
	s_addc_u32 s37, s41, 0
	v_readfirstlane_b32 s42, v137
	s_barrier
	ds_read_b128 v[186:189], v139 offset:16384
	ds_read_b128 v[190:193], v139 offset:17408
	ds_read_b128 v[194:197], v142 offset:16384
	ds_read_b128 v[198:201], v142 offset:17408
	ds_read_b128 v[202:205], v141 offset:16384
	ds_read_b128 v[206:209], v141 offset:17408
	ds_read_b128 v[212:215], v140 offset:16384
	ds_read_b128 v[216:219], v140 offset:17408
	s_mov_b32 m0, s42
	v_lshl_add_u64 v[240:241], s[36:37], 0, v[132:133]
	global_load_lds_dwordx4 v[240:241], off
	v_lshl_add_u64 v[240:241], s[36:37], 0, v[130:131]
	v_readfirstlane_b32 s36, v138
	s_mov_b32 m0, s36
	s_nop 0
	global_load_lds_dwordx4 v[240:241], off
	s_barrier
	s_waitcnt lgkmcnt(0)
	s_waitcnt lgkmcnt(0)
	v_mfma_f32_16x16x32_bf16 v[62:65], v[186:189], v[170:173], v[62:65]
	v_mfma_f32_16x16x32_bf16 v[58:61], v[186:189], v[178:181], v[58:61]
	v_mfma_f32_16x16x32_bf16 v[54:57], v[194:197], v[170:173], v[54:57]
	v_mfma_f32_16x16x32_bf16 v[50:53], v[194:197], v[178:181], v[50:53]
	v_mfma_f32_16x16x32_bf16 v[46:49], v[202:205], v[170:173], v[46:49]
	v_mfma_f32_16x16x32_bf16 v[42:45], v[202:205], v[178:181], v[42:45]
	v_mfma_f32_16x16x32_bf16 v[38:41], v[212:215], v[170:173], v[38:41]
	v_mfma_f32_16x16x32_bf16 v[34:37], v[212:215], v[178:181], v[34:37]
	v_mfma_f32_16x16x32_bf16 v[62:65], v[190:193], v[174:177], v[62:65]
	v_mfma_f32_16x16x32_bf16 v[58:61], v[190:193], v[182:185], v[58:61]
	v_mfma_f32_16x16x32_bf16 v[54:57], v[198:201], v[174:177], v[54:57]
	v_mfma_f32_16x16x32_bf16 v[50:53], v[198:201], v[182:185], v[50:53]
	v_mfma_f32_16x16x32_bf16 v[46:49], v[206:209], v[174:177], v[46:49]
	v_mfma_f32_16x16x32_bf16 v[42:45], v[206:209], v[182:185], v[42:45]
	v_mfma_f32_16x16x32_bf16 v[38:41], v[216:219], v[174:177], v[38:41]
	v_mfma_f32_16x16x32_bf16 v[34:37], v[216:219], v[182:185], v[34:37]
	s_barrier
	s_add_u32 s42, s12, s16
	s_addc_u32 s43, s13, s17
	s_add_u32 s36, s42, 0x100
	s_addc_u32 s37, s43, 0
	v_readfirstlane_b32 s44, v146
	s_mov_b32 m0, s44
	v_lshl_add_u64 v[170:171], s[36:37], 0, v[132:133]
	global_load_lds_dwordx4 v[170:171], off
	v_lshl_add_u64 v[170:171], s[36:37], 0, v[130:131]
	v_readfirstlane_b32 s36, v147
	s_mov_b32 m0, s36
	s_nop 0
	global_load_lds_dwordx4 v[170:171], off
	s_waitcnt vmcnt(6)
	s_barrier
	v_mfma_f32_16x16x32_bf16 v[30:33], v[186:189], v[224:227], v[30:33]
	v_mfma_f32_16x16x32_bf16 v[26:29], v[186:189], v[232:235], v[26:29]
	v_mfma_f32_16x16x32_bf16 v[22:25], v[194:197], v[224:227], v[22:25]
	v_mfma_f32_16x16x32_bf16 v[18:21], v[194:197], v[232:235], v[18:21]
	v_mfma_f32_16x16x32_bf16 v[14:17], v[202:205], v[224:227], v[14:17]
	v_mfma_f32_16x16x32_bf16 v[10:13], v[202:205], v[232:235], v[10:13]
	v_mfma_f32_16x16x32_bf16 v[6:9], v[212:215], v[224:227], v[6:9]
	v_mfma_f32_16x16x32_bf16 v[2:5], v[212:215], v[232:235], v[2:5]
	v_mfma_f32_16x16x32_bf16 v[30:33], v[190:193], v[228:231], v[30:33]
	v_mfma_f32_16x16x32_bf16 v[26:29], v[190:193], v[236:239], v[26:29]
	v_mfma_f32_16x16x32_bf16 v[22:25], v[198:201], v[228:231], v[22:25]
	v_mfma_f32_16x16x32_bf16 v[18:21], v[198:201], v[236:239], v[18:21]
	v_mfma_f32_16x16x32_bf16 v[14:17], v[206:209], v[228:231], v[14:17]
	v_mfma_f32_16x16x32_bf16 v[10:13], v[206:209], v[236:239], v[10:13]
	v_mfma_f32_16x16x32_bf16 v[6:9], v[216:219], v[228:231], v[6:9]
	v_mfma_f32_16x16x32_bf16 v[2:5], v[216:219], v[236:239], v[2:5]
	v_or_b32_e32 v170, 0x18000, v156
	v_or_b32_e32 v172, 0x18000, v158
	s_barrier
	v_or_b32_e32 v171, 0x18000, v157
	ds_read_b128 v[178:181], v170
	ds_read_b128 v[182:185], v171
	v_or_b32_e32 v173, 0x18000, v159
	ds_read_b128 v[186:189], v172
	ds_read_b128 v[190:193], v173
	s_add_u32 s36, s7, s16
	s_addc_u32 s37, s18, s17
	v_readfirstlane_b32 s44, v148
	ds_read_b128 v[194:197], v139 offset:32768
	ds_read_b128 v[198:201], v139 offset:33792
	ds_read_b128 v[202:205], v142 offset:32768
	ds_read_b128 v[206:209], v142 offset:33792
	ds_read_b128 v[212:215], v141 offset:32768
	ds_read_b128 v[216:219], v141 offset:33792
	ds_read_b128 v[224:227], v140 offset:32768
	ds_read_b128 v[228:231], v140 offset:33792
	s_mov_b32 m0, s44
	v_lshl_add_u64 v[174:175], s[36:37], 0, v[132:133]
	global_load_lds_dwordx4 v[174:175], off
	v_lshl_add_u64 v[174:175], s[36:37], 0, v[130:131]
	v_readfirstlane_b32 s36, v149
	s_mov_b32 m0, s36
	s_nop 0
	global_load_lds_dwordx4 v[174:175], off
	s_waitcnt lgkmcnt(8)
	s_barrier
	s_waitcnt lgkmcnt(0)
	s_waitcnt lgkmcnt(0)
	v_mfma_f32_16x16x32_bf16 v[126:129], v[194:197], v[178:181], v[126:129]
	v_mfma_f32_16x16x32_bf16 v[122:125], v[194:197], v[186:189], v[122:125]
	v_mfma_f32_16x16x32_bf16 v[118:121], v[202:205], v[178:181], v[118:121]
	v_mfma_f32_16x16x32_bf16 v[114:117], v[202:205], v[186:189], v[114:117]
	v_mfma_f32_16x16x32_bf16 v[110:113], v[212:215], v[178:181], v[110:113]
	v_mfma_f32_16x16x32_bf16 v[106:109], v[212:215], v[186:189], v[106:109]
	v_mfma_f32_16x16x32_bf16 v[102:105], v[224:227], v[178:181], v[102:105]
	v_mfma_f32_16x16x32_bf16 v[98:101], v[224:227], v[186:189], v[98:101]
	v_mfma_f32_16x16x32_bf16 v[126:129], v[198:201], v[182:185], v[126:129]
	v_mfma_f32_16x16x32_bf16 v[122:125], v[198:201], v[190:193], v[122:125]
	v_mfma_f32_16x16x32_bf16 v[118:121], v[206:209], v[182:185], v[118:121]
	v_mfma_f32_16x16x32_bf16 v[114:117], v[206:209], v[190:193], v[114:117]
	v_mfma_f32_16x16x32_bf16 v[110:113], v[216:219], v[182:185], v[110:113]
	v_mfma_f32_16x16x32_bf16 v[106:109], v[216:219], v[190:193], v[106:109]
	v_mfma_f32_16x16x32_bf16 v[102:105], v[228:231], v[182:185], v[102:105]
	v_mfma_f32_16x16x32_bf16 v[98:101], v[228:231], v[190:193], v[98:101]
	s_barrier
	s_add_u32 s36, s38, 0x180
	v_or_b32_e32 v174, 0x1c000, v156
	v_or_b32_e32 v176, 0x1c000, v158
	s_addc_u32 s37, s39, 0
	v_readfirstlane_b32 s38, v150
	v_or_b32_e32 v175, 0x1c000, v157
	ds_read_b128 v[232:235], v174
	ds_read_b128 v[236:239], v175
	v_or_b32_e32 v177, 0x1c000, v159
	ds_read_b128 v[240:243], v176
	ds_read_b128 v[244:247], v177
	s_mov_b32 m0, s38
	v_lshl_add_u64 v[248:249], s[36:37], 0, v[132:133]
	global_load_lds_dwordx4 v[248:249], off
	v_lshl_add_u64 v[248:249], s[36:37], 0, v[130:131]
	v_readfirstlane_b32 s36, v151
	s_mov_b32 m0, s36
	s_nop 0
	global_load_lds_dwordx4 v[248:249], off
	s_barrier
	s_waitcnt lgkmcnt(0)
	s_waitcnt lgkmcnt(0)
	v_mfma_f32_16x16x32_bf16 v[94:97], v[194:197], v[232:235], v[94:97]
	v_mfma_f32_16x16x32_bf16 v[90:93], v[194:197], v[240:243], v[90:93]
	v_mfma_f32_16x16x32_bf16 v[86:89], v[202:205], v[232:235], v[86:89]
	v_mfma_f32_16x16x32_bf16 v[82:85], v[202:205], v[240:243], v[82:85]
	v_mfma_f32_16x16x32_bf16 v[78:81], v[212:215], v[232:235], v[78:81]
	v_mfma_f32_16x16x32_bf16 v[74:77], v[212:215], v[240:243], v[74:77]
	v_mfma_f32_16x16x32_bf16 v[70:73], v[224:227], v[232:235], v[70:73]
	v_mfma_f32_16x16x32_bf16 v[66:69], v[224:227], v[240:243], v[66:69]
	v_mfma_f32_16x16x32_bf16 v[94:97], v[198:201], v[236:239], v[94:97]
	v_mfma_f32_16x16x32_bf16 v[90:93], v[198:201], v[244:247], v[90:93]
	v_mfma_f32_16x16x32_bf16 v[86:89], v[206:209], v[236:239], v[86:89]
	v_mfma_f32_16x16x32_bf16 v[82:85], v[206:209], v[244:247], v[82:85]
	v_mfma_f32_16x16x32_bf16 v[78:81], v[216:219], v[236:239], v[78:81]
	v_mfma_f32_16x16x32_bf16 v[74:77], v[216:219], v[244:247], v[74:77]
	v_mfma_f32_16x16x32_bf16 v[70:73], v[228:231], v[236:239], v[70:73]
	v_mfma_f32_16x16x32_bf16 v[66:69], v[228:231], v[244:247], v[66:69]
	s_add_u32 s36, s40, 0x180
	s_addc_u32 s37, s41, 0
	v_readfirstlane_b32 s38, v152
	s_barrier
	ds_read_b128 v[194:197], v139 offset:49152
	ds_read_b128 v[198:201], v139 offset:50176
	ds_read_b128 v[202:205], v142 offset:49152
	ds_read_b128 v[206:209], v142 offset:50176
	ds_read_b128 v[212:215], v141 offset:49152
	ds_read_b128 v[216:219], v141 offset:50176
	ds_read_b128 v[224:227], v140 offset:49152
	ds_read_b128 v[228:231], v140 offset:50176
	s_mov_b32 m0, s38
	v_lshl_add_u64 v[248:249], s[36:37], 0, v[132:133]
	global_load_lds_dwordx4 v[248:249], off
	v_lshl_add_u64 v[248:249], s[36:37], 0, v[130:131]
	v_readfirstlane_b32 s36, v153
	s_mov_b32 m0, s36
	s_nop 0
	global_load_lds_dwordx4 v[248:249], off
	s_barrier
	s_waitcnt lgkmcnt(0)
	s_waitcnt lgkmcnt(0)
	v_mfma_f32_16x16x32_bf16 v[62:65], v[194:197], v[178:181], v[62:65]
	v_mfma_f32_16x16x32_bf16 v[58:61], v[194:197], v[186:189], v[58:61]
	v_mfma_f32_16x16x32_bf16 v[54:57], v[202:205], v[178:181], v[54:57]
	v_mfma_f32_16x16x32_bf16 v[50:53], v[202:205], v[186:189], v[50:53]
	v_mfma_f32_16x16x32_bf16 v[46:49], v[212:215], v[178:181], v[46:49]
	v_mfma_f32_16x16x32_bf16 v[42:45], v[212:215], v[186:189], v[42:45]
	v_mfma_f32_16x16x32_bf16 v[38:41], v[224:227], v[178:181], v[38:41]
	v_mfma_f32_16x16x32_bf16 v[34:37], v[224:227], v[186:189], v[34:37]
	v_mfma_f32_16x16x32_bf16 v[62:65], v[198:201], v[182:185], v[62:65]
	v_mfma_f32_16x16x32_bf16 v[58:61], v[198:201], v[190:193], v[58:61]
	v_mfma_f32_16x16x32_bf16 v[54:57], v[206:209], v[182:185], v[54:57]
	v_mfma_f32_16x16x32_bf16 v[50:53], v[206:209], v[190:193], v[50:53]
	v_mfma_f32_16x16x32_bf16 v[46:49], v[216:219], v[182:185], v[46:49]
	v_mfma_f32_16x16x32_bf16 v[42:45], v[216:219], v[190:193], v[42:45]
	v_mfma_f32_16x16x32_bf16 v[38:41], v[228:231], v[182:185], v[38:41]
	v_mfma_f32_16x16x32_bf16 v[34:37], v[228:231], v[190:193], v[34:37]
	s_barrier
	s_add_u32 s36, s42, 0x180
	s_addc_u32 s37, s43, 0
	v_readfirstlane_b32 s38, v154
	s_mov_b32 m0, s38
	v_lshl_add_u64 v[178:179], s[36:37], 0, v[132:133]
	global_load_lds_dwordx4 v[178:179], off
	v_lshl_add_u64 v[178:179], s[36:37], 0, v[130:131]
	v_readfirstlane_b32 s36, v155
	s_mov_b32 m0, s36
	s_nop 0
	global_load_lds_dwordx4 v[178:179], off
	s_waitcnt vmcnt(6)
	s_barrier
	v_mfma_f32_16x16x32_bf16 v[30:33], v[194:197], v[232:235], v[30:33]
	v_mfma_f32_16x16x32_bf16 v[26:29], v[194:197], v[240:243], v[26:29]
	v_mfma_f32_16x16x32_bf16 v[22:25], v[202:205], v[232:235], v[22:25]
	v_mfma_f32_16x16x32_bf16 v[18:21], v[202:205], v[240:243], v[18:21]
	v_mfma_f32_16x16x32_bf16 v[14:17], v[212:215], v[232:235], v[14:17]
	v_mfma_f32_16x16x32_bf16 v[10:13], v[212:215], v[240:243], v[10:13]
	v_mfma_f32_16x16x32_bf16 v[6:9], v[224:227], v[232:235], v[6:9]
	v_mfma_f32_16x16x32_bf16 v[2:5], v[224:227], v[240:243], v[2:5]
	v_mfma_f32_16x16x32_bf16 v[30:33], v[198:201], v[236:239], v[30:33]
	v_mfma_f32_16x16x32_bf16 v[26:29], v[198:201], v[244:247], v[26:29]
	v_mfma_f32_16x16x32_bf16 v[22:25], v[206:209], v[236:239], v[22:25]
	v_mfma_f32_16x16x32_bf16 v[18:21], v[206:209], v[244:247], v[18:21]
	v_mfma_f32_16x16x32_bf16 v[14:17], v[216:219], v[236:239], v[14:17]
	v_mfma_f32_16x16x32_bf16 v[10:13], v[216:219], v[244:247], v[10:13]
	v_mfma_f32_16x16x32_bf16 v[6:9], v[228:231], v[236:239], v[6:9]
	v_mfma_f32_16x16x32_bf16 v[2:5], v[228:231], v[244:247], v[2:5]
	s_add_i32 s35, s35, 2
	s_add_u32 s16, s16, 0x100
	s_addc_u32 s17, s17, 0
	s_cmp_lt_u32 s35, 12
	s_barrier
	s_cbranch_scc1 .LBB0_1871
	s_add_u32 s0, s14, 0x780
	s_addc_u32 s1, s15, 0
	ds_read_b128 v[146:149], v160
	ds_read_b128 v[150:153], v161
	ds_read_b128 v[154:157], v162
	ds_read_b128 v[158:161], v163
	ds_read_b128 v[178:181], v139
	ds_read_b128 v[182:185], v139 offset:1024
	ds_read_b128 v[186:189], v142
	ds_read_b128 v[190:193], v142 offset:1024
	ds_read_b128 v[194:197], v141
	ds_read_b128 v[198:201], v141 offset:1024
	ds_read_b128 v[202:205], v140
	ds_read_b128 v[206:209], v140 offset:1024
	v_readfirstlane_b32 s7, v164
	v_lshl_add_u64 v[132:133], s[0:1], 0, v[132:133]
	s_mov_b32 m0, s7
	v_lshl_add_u64 v[130:131], s[0:1], 0, v[130:131]
	v_readfirstlane_b32 s0, v165
	global_load_lds_dwordx4 v[132:133], off
	s_mov_b32 m0, s0
	s_nop 0
	global_load_lds_dwordx4 v[130:131], off
	s_barrier
	s_waitcnt lgkmcnt(0)
	s_waitcnt lgkmcnt(0)
	v_mfma_f32_16x16x32_bf16 v[126:129], v[178:181], v[146:149], v[126:129]
	v_mfma_f32_16x16x32_bf16 v[122:125], v[178:181], v[154:157], v[122:125]
	v_mfma_f32_16x16x32_bf16 v[110:113], v[194:197], v[146:149], v[110:113]
	v_mfma_f32_16x16x32_bf16 v[106:109], v[194:197], v[154:157], v[106:109]
	v_mfma_f32_16x16x32_bf16 v[126:129], v[182:185], v[150:153], v[126:129]
	v_mfma_f32_16x16x32_bf16 v[122:125], v[182:185], v[158:161], v[122:125]
	v_mfma_f32_16x16x32_bf16 v[118:121], v[186:189], v[146:149], v[118:121]
	v_mfma_f32_16x16x32_bf16 v[114:117], v[186:189], v[154:157], v[114:117]
	v_mfma_f32_16x16x32_bf16 v[110:113], v[198:201], v[150:153], v[110:113]
	v_mfma_f32_16x16x32_bf16 v[106:109], v[198:201], v[158:161], v[106:109]
	v_mfma_f32_16x16x32_bf16 v[102:105], v[202:205], v[146:149], v[102:105]
	v_mfma_f32_16x16x32_bf16 v[98:101], v[202:205], v[154:157], v[98:101]
	v_mfma_f32_16x16x32_bf16 v[130:133], v[190:193], v[150:153], v[118:121]
	v_mfma_f32_16x16x32_bf16 v[162:165], v[190:193], v[158:161], v[114:117]
	v_mfma_f32_16x16x32_bf16 v[212:215], v[206:209], v[150:153], v[102:105]
	v_mfma_f32_16x16x32_bf16 v[216:219], v[206:209], v[158:161], v[98:101]
	s_barrier
	s_nop 0
	ds_read_b128 v[98:101], v166
	ds_read_b128 v[102:105], v167
	ds_read_b128 v[114:117], v168
	ds_read_b128 v[118:121], v169
	s_barrier
	s_waitcnt lgkmcnt(0)
	s_waitcnt lgkmcnt(3)
	v_mfma_f32_16x16x32_bf16 v[94:97], v[178:181], v[98:101], v[94:97]
	s_waitcnt lgkmcnt(1)
	v_mfma_f32_16x16x32_bf16 v[90:93], v[178:181], v[114:117], v[90:93]
	v_mfma_f32_16x16x32_bf16 v[78:81], v[194:197], v[98:101], v[78:81]
	v_mfma_f32_16x16x32_bf16 v[74:77], v[194:197], v[114:117], v[74:77]
	v_mfma_f32_16x16x32_bf16 v[94:97], v[182:185], v[102:105], v[94:97]
	s_waitcnt lgkmcnt(0)
	v_mfma_f32_16x16x32_bf16 v[90:93], v[182:185], v[118:121], v[90:93]
	v_mfma_f32_16x16x32_bf16 v[86:89], v[186:189], v[98:101], v[86:89]
	v_mfma_f32_16x16x32_bf16 v[82:85], v[186:189], v[114:117], v[82:85]
	v_mfma_f32_16x16x32_bf16 v[78:81], v[198:201], v[102:105], v[78:81]
	v_mfma_f32_16x16x32_bf16 v[74:77], v[198:201], v[118:121], v[74:77]
	v_mfma_f32_16x16x32_bf16 v[70:73], v[202:205], v[98:101], v[70:73]
	v_mfma_f32_16x16x32_bf16 v[66:69], v[202:205], v[114:117], v[66:69]
	v_mfma_f32_16x16x32_bf16 v[166:169], v[190:193], v[102:105], v[86:89]
	v_mfma_f32_16x16x32_bf16 v[178:181], v[190:193], v[118:121], v[82:85]
	v_mfma_f32_16x16x32_bf16 v[182:185], v[206:209], v[102:105], v[70:73]
	v_mfma_f32_16x16x32_bf16 v[186:189], v[206:209], v[118:121], v[66:69]
	s_barrier
	s_nop 1
	ds_read_b128 v[66:69], v139 offset:16384
	ds_read_b128 v[70:73], v139 offset:17408
	ds_read_b128 v[82:85], v142 offset:16384
	ds_read_b128 v[86:89], v142 offset:17408
	ds_read_b128 v[190:193], v141 offset:16384
	ds_read_b128 v[194:197], v141 offset:17408
	ds_read_b128 v[198:201], v140 offset:16384
	ds_read_b128 v[202:205], v140 offset:17408
	s_waitcnt vmcnt(4)
	s_barrier
	s_waitcnt lgkmcnt(0)
	s_waitcnt lgkmcnt(7)
	v_mfma_f32_16x16x32_bf16 v[62:65], v[66:69], v[146:149], v[62:65]
	v_mfma_f32_16x16x32_bf16 v[58:61], v[66:69], v[154:157], v[58:61]
	s_waitcnt lgkmcnt(3)
	v_mfma_f32_16x16x32_bf16 v[46:49], v[190:193], v[146:149], v[46:49]
	v_mfma_f32_16x16x32_bf16 v[42:45], v[190:193], v[154:157], v[42:45]
	v_mfma_f32_16x16x32_bf16 v[62:65], v[70:73], v[150:153], v[62:65]
	v_mfma_f32_16x16x32_bf16 v[58:61], v[70:73], v[158:161], v[58:61]
	v_mfma_f32_16x16x32_bf16 v[54:57], v[82:85], v[146:149], v[54:57]
	v_mfma_f32_16x16x32_bf16 v[50:53], v[82:85], v[154:157], v[50:53]
	s_waitcnt lgkmcnt(2)
	v_mfma_f32_16x16x32_bf16 v[46:49], v[194:197], v[150:153], v[46:49]
	v_mfma_f32_16x16x32_bf16 v[42:45], v[194:197], v[158:161], v[42:45]
	s_waitcnt lgkmcnt(1)
	v_mfma_f32_16x16x32_bf16 v[38:41], v[198:201], v[146:149], v[38:41]
	v_mfma_f32_16x16x32_bf16 v[34:37], v[198:201], v[154:157], v[34:37]
	v_mfma_f32_16x16x32_bf16 v[206:209], v[86:89], v[150:153], v[54:57]
	v_mfma_f32_16x16x32_bf16 v[224:227], v[86:89], v[158:161], v[50:53]
	s_waitcnt lgkmcnt(0)
	v_mfma_f32_16x16x32_bf16 v[146:149], v[202:205], v[150:153], v[38:41]
	v_mfma_f32_16x16x32_bf16 v[150:153], v[202:205], v[158:161], v[34:37]
	v_mfma_f32_16x16x32_bf16 v[30:33], v[66:69], v[98:101], v[30:33]
	v_mfma_f32_16x16x32_bf16 v[26:29], v[66:69], v[114:117], v[26:29]
	v_mfma_f32_16x16x32_bf16 v[14:17], v[190:193], v[98:101], v[14:17]
	v_mfma_f32_16x16x32_bf16 v[10:13], v[190:193], v[114:117], v[10:13]
	v_mfma_f32_16x16x32_bf16 v[30:33], v[70:73], v[102:105], v[30:33]
	v_mfma_f32_16x16x32_bf16 v[26:29], v[70:73], v[118:121], v[26:29]
	v_mfma_f32_16x16x32_bf16 v[22:25], v[82:85], v[98:101], v[22:25]
	v_mfma_f32_16x16x32_bf16 v[18:21], v[82:85], v[114:117], v[18:21]
	v_mfma_f32_16x16x32_bf16 v[14:17], v[194:197], v[102:105], v[14:17]
	v_mfma_f32_16x16x32_bf16 v[10:13], v[194:197], v[118:121], v[10:13]
	v_mfma_f32_16x16x32_bf16 v[6:9], v[198:201], v[98:101], v[6:9]
	v_mfma_f32_16x16x32_bf16 v[2:5], v[198:201], v[114:117], v[2:5]
	v_mfma_f32_16x16x32_bf16 v[154:157], v[86:89], v[102:105], v[22:25]
	v_mfma_f32_16x16x32_bf16 v[158:161], v[86:89], v[118:121], v[18:21]
	v_mfma_f32_16x16x32_bf16 v[190:193], v[202:205], v[102:105], v[6:9]
	v_mfma_f32_16x16x32_bf16 v[194:197], v[202:205], v[118:121], v[2:5]
	s_barrier
	s_nop 1
	ds_read_b128 v[2:5], v170
	ds_read_b128 v[6:9], v171
	ds_read_b128 v[198:201], v172
	ds_read_b128 v[170:173], v173
	ds_read_b128 v[18:21], v139 offset:32768
	ds_read_b128 v[22:25], v139 offset:33792
	ds_read_b128 v[34:37], v142 offset:32768
	ds_read_b128 v[38:41], v142 offset:33792
	ds_read_b128 v[50:53], v141 offset:32768
	ds_read_b128 v[54:57], v141 offset:33792
	ds_read_b128 v[202:205], v140 offset:32768
	ds_read_b128 v[228:231], v140 offset:33792
	s_waitcnt vmcnt(2)
	s_barrier
	s_waitcnt lgkmcnt(0)
	s_waitcnt lgkmcnt(7)
	v_mfma_f32_16x16x32_bf16 v[66:69], v[18:21], v[2:5], v[126:129]
	s_waitcnt lgkmcnt(6)
	v_mfma_f32_16x16x32_bf16 v[114:117], v[22:25], v[6:9], v[66:69]
	v_mfma_f32_16x16x32_bf16 v[66:69], v[18:21], v[198:201], v[122:125]
	v_mfma_f32_16x16x32_bf16 v[118:121], v[22:25], v[170:173], v[66:69]
	s_waitcnt lgkmcnt(5)
	v_mfma_f32_16x16x32_bf16 v[66:69], v[34:37], v[2:5], v[130:133]
	s_waitcnt lgkmcnt(4)
	v_mfma_f32_16x16x32_bf16 v[98:101], v[38:41], v[6:9], v[66:69]
	v_mfma_f32_16x16x32_bf16 v[66:69], v[34:37], v[198:201], v[162:165]
	v_mfma_f32_16x16x32_bf16 v[102:105], v[38:41], v[170:173], v[66:69]
	s_waitcnt lgkmcnt(3)
	v_mfma_f32_16x16x32_bf16 v[66:69], v[50:53], v[2:5], v[110:113]
	s_waitcnt lgkmcnt(2)
	v_mfma_f32_16x16x32_bf16 v[82:85], v[54:57], v[6:9], v[66:69]
	v_mfma_f32_16x16x32_bf16 v[66:69], v[50:53], v[198:201], v[106:109]
	v_mfma_f32_16x16x32_bf16 v[86:89], v[54:57], v[170:173], v[66:69]
	s_waitcnt lgkmcnt(1)
	v_mfma_f32_16x16x32_bf16 v[66:69], v[202:205], v[2:5], v[212:215]
	v_mfma_f32_16x16x32_bf16 v[70:73], v[202:205], v[198:201], v[216:219]
	s_waitcnt lgkmcnt(0)
	v_mfma_f32_16x16x32_bf16 v[66:69], v[228:231], v[6:9], v[66:69]
	v_mfma_f32_16x16x32_bf16 v[70:73], v[228:231], v[170:173], v[70:73]
	s_barrier
	ds_read_b128 v[130:133], v174
	ds_read_b128 v[162:165], v175
	ds_read_b128 v[212:215], v176
	ds_read_b128 v[174:177], v177
	s_waitcnt vmcnt(0)
	s_barrier
	s_waitcnt lgkmcnt(0)
	s_waitcnt lgkmcnt(3)
	v_mfma_f32_16x16x32_bf16 v[94:97], v[18:21], v[130:133], v[94:97]
	s_waitcnt lgkmcnt(1)
	v_mfma_f32_16x16x32_bf16 v[18:21], v[18:21], v[212:215], v[90:93]
	s_waitcnt lgkmcnt(0)
	v_mfma_f32_16x16x32_bf16 v[122:125], v[22:25], v[174:177], v[18:21]
	v_mfma_f32_16x16x32_bf16 v[18:21], v[34:37], v[130:133], v[166:169]
	v_mfma_f32_16x16x32_bf16 v[110:113], v[38:41], v[162:165], v[18:21]
	v_mfma_f32_16x16x32_bf16 v[18:21], v[34:37], v[212:215], v[178:181]
	v_mfma_f32_16x16x32_bf16 v[106:109], v[38:41], v[174:177], v[18:21]
	v_mfma_f32_16x16x32_bf16 v[18:21], v[50:53], v[130:133], v[78:81]
	v_mfma_f32_16x16x32_bf16 v[126:129], v[22:25], v[162:165], v[94:97]
	v_mfma_f32_16x16x32_bf16 v[94:97], v[54:57], v[162:165], v[18:21]
	v_mfma_f32_16x16x32_bf16 v[18:21], v[50:53], v[212:215], v[74:77]
	v_mfma_f32_16x16x32_bf16 v[90:93], v[54:57], v[174:177], v[18:21]
	v_mfma_f32_16x16x32_bf16 v[18:21], v[202:205], v[130:133], v[182:185]
	v_mfma_f32_16x16x32_bf16 v[78:81], v[228:231], v[162:165], v[18:21]
	v_mfma_f32_16x16x32_bf16 v[18:21], v[202:205], v[212:215], v[186:189]
	v_mfma_f32_16x16x32_bf16 v[74:77], v[228:231], v[174:177], v[18:21]
	s_barrier
	ds_read_b128 v[166:169], v139 offset:49152
	ds_read_b128 v[178:181], v139 offset:50176
	ds_read_b128 v[182:185], v142 offset:49152
	ds_read_b128 v[186:189], v142 offset:50176
	ds_read_b128 v[202:205], v141 offset:49152
	ds_read_b128 v[216:219], v141 offset:50176
	ds_read_b128 v[228:231], v140 offset:49152
	ds_read_b128 v[138:141], v140 offset:50176
	s_barrier
	s_waitcnt lgkmcnt(0)
	s_waitcnt lgkmcnt(7)
	v_mfma_f32_16x16x32_bf16 v[18:21], v[166:169], v[2:5], v[62:65]
	s_waitcnt lgkmcnt(6)
	v_mfma_f32_16x16x32_bf16 v[50:53], v[178:181], v[6:9], v[18:21]
	v_mfma_f32_16x16x32_bf16 v[18:21], v[166:169], v[198:201], v[58:61]
	v_mfma_f32_16x16x32_bf16 v[54:57], v[178:181], v[170:173], v[18:21]
	s_waitcnt lgkmcnt(5)
	v_mfma_f32_16x16x32_bf16 v[18:21], v[182:185], v[2:5], v[206:209]
	s_waitcnt lgkmcnt(4)
	v_mfma_f32_16x16x32_bf16 v[34:37], v[186:189], v[6:9], v[18:21]
	v_mfma_f32_16x16x32_bf16 v[18:21], v[182:185], v[198:201], v[224:227]
	v_mfma_f32_16x16x32_bf16 v[38:41], v[186:189], v[170:173], v[18:21]
	s_waitcnt lgkmcnt(3)
	v_mfma_f32_16x16x32_bf16 v[18:21], v[202:205], v[2:5], v[46:49]
	s_waitcnt lgkmcnt(1)
	v_mfma_f32_16x16x32_bf16 v[2:5], v[228:231], v[2:5], v[146:149]
	v_mfma_f32_16x16x32_bf16 v[18:21], v[216:219], v[6:9], v[18:21]
	v_mfma_f32_16x16x32_bf16 v[22:25], v[202:205], v[198:201], v[42:45]
	s_waitcnt lgkmcnt(0)
	v_mfma_f32_16x16x32_bf16 v[2:5], v[138:141], v[6:9], v[2:5]
	v_mfma_f32_16x16x32_bf16 v[6:9], v[228:231], v[198:201], v[150:153]
	v_mfma_f32_16x16x32_bf16 v[22:25], v[216:219], v[170:173], v[22:25]
	v_mfma_f32_16x16x32_bf16 v[6:9], v[138:141], v[170:173], v[6:9]
	v_mfma_f32_16x16x32_bf16 v[26:29], v[166:169], v[212:215], v[26:29]
	v_mfma_f32_16x16x32_bf16 v[58:61], v[178:181], v[174:177], v[26:29]
	v_mfma_f32_16x16x32_bf16 v[26:29], v[182:185], v[130:133], v[154:157]
	v_mfma_f32_16x16x32_bf16 v[46:49], v[186:189], v[162:165], v[26:29]
	v_mfma_f32_16x16x32_bf16 v[26:29], v[182:185], v[212:215], v[158:161]
	v_mfma_f32_16x16x32_bf16 v[10:13], v[202:205], v[212:215], v[10:13]
	v_mfma_f32_16x16x32_bf16 v[30:33], v[166:169], v[130:133], v[30:33]
	v_mfma_f32_16x16x32_bf16 v[42:45], v[186:189], v[174:177], v[26:29]
	v_mfma_f32_16x16x32_bf16 v[14:17], v[202:205], v[130:133], v[14:17]
	v_mfma_f32_16x16x32_bf16 v[26:29], v[216:219], v[174:177], v[10:13]
	v_mfma_f32_16x16x32_bf16 v[10:13], v[228:231], v[130:133], v[190:193]
	v_mfma_f32_16x16x32_bf16 v[62:65], v[178:181], v[162:165], v[30:33]
	v_mfma_f32_16x16x32_bf16 v[30:33], v[216:219], v[162:165], v[14:17]
	v_mfma_f32_16x16x32_bf16 v[14:17], v[138:141], v[162:165], v[10:13]
	v_mfma_f32_16x16x32_bf16 v[10:13], v[228:231], v[212:215], v[194:197]
	v_mfma_f32_16x16x32_bf16 v[10:13], v[138:141], v[174:177], v[10:13]
	s_movk_i32 s0, 0x100
	v_cmp_gt_u32_e32 vcc, s0, v134
	s_barrier
	s_and_saveexec_b64 s[0:1], vcc
	s_cbranch_execz .LBB0_1874
	s_barrier
